# kpair order + removed the already-satisfied lgkmcnt waits inside MFMA segments
# baseline (speedup 1.0000x reference)
.LBB0_642:
	ds_read_b128 v[148:151], v139
	ds_read_b128 v[152:155], v139 offset:1024
	ds_read_b128 v[156:159], v139 offset:2048
	ds_read_b128 v[160:163], v139 offset:3072
	ds_read_b128 v[164:167], v140
	ds_read_b128 v[168:171], v140 offset:1024
	ds_read_b128 v[172:175], v140 offset:2048
	ds_read_b128 v[176:179], v140 offset:3072
	s_add_i32 s18, s71, 0xffe80080
	s_cmp_eq_u32 s58, s73
	s_cselect_b32 s74, s69, s18
	s_cselect_b32 s76, s70, s72
	s_or_b32 s75, s74, 0x80
	s_add_i32 s18, s71, 0xfff80000
	s_mov_b32 m0, s59
	ds_read_b128 v[180:183], v141
	ds_read_b128 v[184:187], v141 offset:1024
	ds_read_b128 v[188:191], v141 offset:2048
	ds_read_b128 v[192:195], v141 offset:3072
	ds_read_b128 v[196:199], v141 offset:4096
	ds_read_b128 v[200:203], v141 offset:5120
	ds_read_b128 v[204:207], v141 offset:6144
	ds_read_b128 v[208:211], v141 offset:7168
	buffer_load_dwordx4 v137, s[12:15], s18 offen lds
	s_mov_b32 m0, s60
	s_nop 0
	buffer_load_dwordx4 v137, s[12:15], s71 offen lds
	s_waitcnt vmcnt(8)
	s_waitcnt lgkmcnt(0)
	s_setprio 1
	v_mfma_f32_16x16x32_bf16 v[118:121], v[148:151], v[180:183], v[118:121]
	s_barrier
	v_mfma_f32_16x16x32_bf16 v[118:121], v[152:155], v[184:187], v[118:121]
	v_mfma_f32_16x16x32_bf16 v[114:117], v[156:159], v[180:183], v[114:117]
	v_mfma_f32_16x16x32_bf16 v[114:117], v[160:163], v[184:187], v[114:117]
	v_mfma_f32_16x16x32_bf16 v[110:113], v[148:151], v[188:191], v[110:113]
	v_mfma_f32_16x16x32_bf16 v[110:113], v[152:155], v[192:195], v[110:113]
	v_mfma_f32_16x16x32_bf16 v[102:105], v[156:159], v[188:191], v[102:105]
	v_mfma_f32_16x16x32_bf16 v[102:105], v[160:163], v[192:195], v[102:105]
	v_mfma_f32_16x16x32_bf16 v[94:97], v[148:151], v[196:199], v[94:97]
	v_mfma_f32_16x16x32_bf16 v[94:97], v[152:155], v[200:203], v[94:97]
	v_mfma_f32_16x16x32_bf16 v[86:89], v[156:159], v[196:199], v[86:89]
	v_mfma_f32_16x16x32_bf16 v[86:89], v[160:163], v[200:203], v[86:89]
	v_mfma_f32_16x16x32_bf16 v[78:81], v[148:151], v[204:207], v[78:81]
	v_mfma_f32_16x16x32_bf16 v[78:81], v[152:155], v[208:211], v[78:81]
	v_mfma_f32_16x16x32_bf16 v[66:69], v[156:159], v[204:207], v[66:69]
	v_mfma_f32_16x16x32_bf16 v[66:69], v[160:163], v[208:211], v[66:69]
	v_mfma_f32_16x16x32_bf16 v[126:129], v[164:167], v[180:183], v[126:129]
	v_mfma_f32_16x16x32_bf16 v[126:129], v[168:171], v[184:187], v[126:129]
	v_mfma_f32_16x16x32_bf16 v[122:125], v[172:175], v[180:183], v[122:125]
	v_mfma_f32_16x16x32_bf16 v[122:125], v[176:179], v[184:187], v[122:125]
	v_mfma_f32_16x16x32_bf16 v[106:109], v[164:167], v[188:191], v[106:109]
	v_mfma_f32_16x16x32_bf16 v[106:109], v[168:171], v[192:195], v[106:109]
	v_mfma_f32_16x16x32_bf16 v[98:101], v[172:175], v[188:191], v[98:101]
	v_mfma_f32_16x16x32_bf16 v[98:101], v[176:179], v[192:195], v[98:101]
	v_mfma_f32_16x16x32_bf16 v[90:93], v[164:167], v[196:199], v[90:93]
	v_mfma_f32_16x16x32_bf16 v[90:93], v[168:171], v[200:203], v[90:93]
	v_mfma_f32_16x16x32_bf16 v[82:85], v[172:175], v[196:199], v[82:85]
	v_mfma_f32_16x16x32_bf16 v[82:85], v[176:179], v[200:203], v[82:85]
	v_mfma_f32_16x16x32_bf16 v[74:77], v[164:167], v[204:207], v[74:77]
	v_mfma_f32_16x16x32_bf16 v[74:77], v[168:171], v[208:211], v[74:77]
	v_mfma_f32_16x16x32_bf16 v[70:73], v[172:175], v[204:207], v[70:73]
	v_mfma_f32_16x16x32_bf16 v[70:73], v[176:179], v[208:211], v[70:73]
	s_setprio 0
	s_barrier
	s_mov_b32 m0, s30
	s_mov_b32 s18, s14
	s_mov_b32 s19, s15
	ds_read_b128 v[180:183], v141 offset:16384
	ds_read_b128 v[184:187], v141 offset:17408
	ds_read_b128 v[188:191], v141 offset:18432
	ds_read_b128 v[192:195], v141 offset:19456
	ds_read_b128 v[196:199], v141 offset:20480
	ds_read_b128 v[200:203], v141 offset:21504
	ds_read_b128 v[204:207], v141 offset:22528
	ds_read_b128 v[208:211], v141 offset:23552
	buffer_load_dwordx4 v138, s[16:19], s76 offen lds
	s_add_i32 s77, s76, 0x80000
	s_mov_b32 m0, s31
	s_nop 0
	buffer_load_dwordx4 v138, s[16:19], s77 offen lds
	s_add_i32 s77, s76, 0x100000
	s_mov_b32 m0, s44
	s_nop 0
	buffer_load_dwordx4 v138, s[16:19], s77 offen lds
	s_add_i32 s77, s76, 0x180000
	s_mov_b32 m0, s45
	s_nop 0
	buffer_load_dwordx4 v138, s[16:19], s77 offen lds
	s_mov_b32 m0, s27
	s_add_i32 s77, s74, 0x80000
	buffer_load_dwordx4 v137, s[12:15], s74 offen lds
	s_mov_b32 m0, s46
	s_nop 0
	buffer_load_dwordx4 v137, s[12:15], s77 offen lds
	s_waitcnt vmcnt(8)
	s_waitcnt lgkmcnt(0)
	s_setprio 1
	v_mfma_f32_16x16x32_bf16 v[62:65], v[148:151], v[180:183], v[62:65]
	s_barrier
	v_mfma_f32_16x16x32_bf16 v[62:65], v[152:155], v[184:187], v[62:65]
	v_mfma_f32_16x16x32_bf16 v[54:57], v[156:159], v[180:183], v[54:57]
	v_mfma_f32_16x16x32_bf16 v[54:57], v[160:163], v[184:187], v[54:57]
	v_mfma_f32_16x16x32_bf16 v[46:49], v[148:151], v[188:191], v[46:49]
	v_mfma_f32_16x16x32_bf16 v[46:49], v[152:155], v[192:195], v[46:49]
	v_mfma_f32_16x16x32_bf16 v[38:41], v[156:159], v[188:191], v[38:41]
	v_mfma_f32_16x16x32_bf16 v[38:41], v[160:163], v[192:195], v[38:41]
	v_mfma_f32_16x16x32_bf16 v[30:33], v[148:151], v[196:199], v[30:33]
	v_mfma_f32_16x16x32_bf16 v[30:33], v[152:155], v[200:203], v[30:33]
	v_mfma_f32_16x16x32_bf16 v[22:25], v[156:159], v[196:199], v[22:25]
	v_mfma_f32_16x16x32_bf16 v[22:25], v[160:163], v[200:203], v[22:25]
	v_mfma_f32_16x16x32_bf16 v[14:17], v[148:151], v[204:207], v[14:17]
	v_mfma_f32_16x16x32_bf16 v[14:17], v[152:155], v[208:211], v[14:17]
	v_mfma_f32_16x16x32_bf16 v[6:9], v[156:159], v[204:207], v[6:9]
	v_mfma_f32_16x16x32_bf16 v[6:9], v[160:163], v[208:211], v[6:9]
	v_mfma_f32_16x16x32_bf16 v[58:61], v[164:167], v[180:183], v[58:61]
	v_mfma_f32_16x16x32_bf16 v[58:61], v[168:171], v[184:187], v[58:61]
	v_mfma_f32_16x16x32_bf16 v[50:53], v[172:175], v[180:183], v[50:53]
	v_mfma_f32_16x16x32_bf16 v[50:53], v[176:179], v[184:187], v[50:53]
	v_mfma_f32_16x16x32_bf16 v[42:45], v[164:167], v[188:191], v[42:45]
	v_mfma_f32_16x16x32_bf16 v[42:45], v[168:171], v[192:195], v[42:45]
	v_mfma_f32_16x16x32_bf16 v[34:37], v[172:175], v[188:191], v[34:37]
	v_mfma_f32_16x16x32_bf16 v[34:37], v[176:179], v[192:195], v[34:37]
	v_mfma_f32_16x16x32_bf16 v[26:29], v[164:167], v[196:199], v[26:29]
	v_mfma_f32_16x16x32_bf16 v[26:29], v[168:171], v[200:203], v[26:29]
	v_mfma_f32_16x16x32_bf16 v[18:21], v[172:175], v[196:199], v[18:21]
	v_mfma_f32_16x16x32_bf16 v[18:21], v[176:179], v[200:203], v[18:21]
	v_mfma_f32_16x16x32_bf16 v[10:13], v[164:167], v[204:207], v[10:13]
	v_mfma_f32_16x16x32_bf16 v[10:13], v[168:171], v[208:211], v[10:13]
	v_mfma_f32_16x16x32_bf16 v[2:5], v[172:175], v[204:207], v[2:5]
	v_mfma_f32_16x16x32_bf16 v[2:5], v[176:179], v[208:211], v[2:5]
	s_setprio 0
	s_barrier
	ds_read_b128 v[148:151], v142
	ds_read_b128 v[152:155], v142 offset:1024
	ds_read_b128 v[156:159], v142 offset:2048
	ds_read_b128 v[160:163], v142 offset:3072
	ds_read_b128 v[164:167], v143
	ds_read_b128 v[168:171], v143 offset:1024
	ds_read_b128 v[172:175], v143 offset:2048
	ds_read_b128 v[176:179], v143 offset:3072
	s_mov_b32 m0, s47
	s_add_i32 s77, s74, 0x100000
	ds_read_b128 v[180:183], v141 offset:32768
	ds_read_b128 v[184:187], v141 offset:33792
	ds_read_b128 v[188:191], v141 offset:34816
	ds_read_b128 v[192:195], v141 offset:35840
	ds_read_b128 v[196:199], v141 offset:36864
	ds_read_b128 v[200:203], v141 offset:37888
	ds_read_b128 v[204:207], v141 offset:38912
	ds_read_b128 v[208:211], v141 offset:39936
	buffer_load_dwordx4 v137, s[12:15], s77 offen lds
	s_add_i32 s77, s74, 0x180000
	s_mov_b32 m0, s48
	s_nop 0
	buffer_load_dwordx4 v137, s[12:15], s77 offen lds
	s_waitcnt vmcnt(8)
	s_waitcnt lgkmcnt(0)
	s_setprio 1
	v_mfma_f32_16x16x32_bf16 v[118:121], v[148:151], v[180:183], v[118:121]
	s_barrier
	v_mfma_f32_16x16x32_bf16 v[118:121], v[152:155], v[184:187], v[118:121]
	v_mfma_f32_16x16x32_bf16 v[114:117], v[156:159], v[180:183], v[114:117]
	v_mfma_f32_16x16x32_bf16 v[114:117], v[160:163], v[184:187], v[114:117]
	v_mfma_f32_16x16x32_bf16 v[110:113], v[148:151], v[188:191], v[110:113]
	v_mfma_f32_16x16x32_bf16 v[110:113], v[152:155], v[192:195], v[110:113]
	v_mfma_f32_16x16x32_bf16 v[102:105], v[156:159], v[188:191], v[102:105]
	v_mfma_f32_16x16x32_bf16 v[102:105], v[160:163], v[192:195], v[102:105]
	v_mfma_f32_16x16x32_bf16 v[94:97], v[148:151], v[196:199], v[94:97]
	v_mfma_f32_16x16x32_bf16 v[94:97], v[152:155], v[200:203], v[94:97]
	v_mfma_f32_16x16x32_bf16 v[86:89], v[156:159], v[196:199], v[86:89]
	v_mfma_f32_16x16x32_bf16 v[86:89], v[160:163], v[200:203], v[86:89]
	v_mfma_f32_16x16x32_bf16 v[78:81], v[148:151], v[204:207], v[78:81]
	v_mfma_f32_16x16x32_bf16 v[78:81], v[152:155], v[208:211], v[78:81]
	v_mfma_f32_16x16x32_bf16 v[66:69], v[156:159], v[204:207], v[66:69]
	v_mfma_f32_16x16x32_bf16 v[66:69], v[160:163], v[208:211], v[66:69]
	v_mfma_f32_16x16x32_bf16 v[126:129], v[164:167], v[180:183], v[126:129]
	v_mfma_f32_16x16x32_bf16 v[126:129], v[168:171], v[184:187], v[126:129]
	v_mfma_f32_16x16x32_bf16 v[122:125], v[172:175], v[180:183], v[122:125]
	v_mfma_f32_16x16x32_bf16 v[122:125], v[176:179], v[184:187], v[122:125]
	v_mfma_f32_16x16x32_bf16 v[106:109], v[164:167], v[188:191], v[106:109]
	v_mfma_f32_16x16x32_bf16 v[106:109], v[168:171], v[192:195], v[106:109]
	v_mfma_f32_16x16x32_bf16 v[98:101], v[172:175], v[188:191], v[98:101]
	v_mfma_f32_16x16x32_bf16 v[98:101], v[176:179], v[192:195], v[98:101]
	v_mfma_f32_16x16x32_bf16 v[90:93], v[164:167], v[196:199], v[90:93]
	v_mfma_f32_16x16x32_bf16 v[90:93], v[168:171], v[200:203], v[90:93]
	v_mfma_f32_16x16x32_bf16 v[82:85], v[172:175], v[196:199], v[82:85]
	v_mfma_f32_16x16x32_bf16 v[82:85], v[176:179], v[200:203], v[82:85]
	v_mfma_f32_16x16x32_bf16 v[74:77], v[164:167], v[204:207], v[74:77]
	v_mfma_f32_16x16x32_bf16 v[74:77], v[168:171], v[208:211], v[74:77]
	v_mfma_f32_16x16x32_bf16 v[70:73], v[172:175], v[204:207], v[70:73]
	v_mfma_f32_16x16x32_bf16 v[70:73], v[176:179], v[208:211], v[70:73]
	s_setprio 0
	s_barrier
	s_mov_b32 m0, s50
	s_or_b32 s77, s76, 0x80
	ds_read_b128 v[180:183], v141 offset:49152
	ds_read_b128 v[184:187], v141 offset:50176
	ds_read_b128 v[188:191], v141 offset:51200
	ds_read_b128 v[192:195], v141 offset:52224
	ds_read_b128 v[196:199], v141 offset:53248
	ds_read_b128 v[200:203], v141 offset:54272
	ds_read_b128 v[204:207], v141 offset:55296
	ds_read_b128 v[208:211], v141 offset:56320
	buffer_load_dwordx4 v138, s[16:19], s77 offen lds
	s_add_i32 s77, s76, 0x80080
	s_mov_b32 m0, s51
	s_add_i32 s74, s74, 0x80080
	buffer_load_dwordx4 v138, s[16:19], s77 offen lds
	s_add_i32 s77, s76, 0x100080
	s_mov_b32 m0, s54
	s_add_i32 s76, s76, 0x180080
	buffer_load_dwordx4 v138, s[16:19], s77 offen lds
	s_mov_b32 m0, s55
	s_nop 0
	buffer_load_dwordx4 v138, s[16:19], s76 offen lds
	s_mov_b32 m0, s52
	s_nop 0
	buffer_load_dwordx4 v137, s[12:15], s75 offen lds
	s_mov_b32 m0, s53
	s_nop 0
	buffer_load_dwordx4 v137, s[12:15], s74 offen lds
	s_waitcnt vmcnt(8)
	s_waitcnt lgkmcnt(0)
	s_setprio 1
	v_mfma_f32_16x16x32_bf16 v[62:65], v[148:151], v[180:183], v[62:65]
	s_barrier
	v_mfma_f32_16x16x32_bf16 v[62:65], v[152:155], v[184:187], v[62:65]
	v_mfma_f32_16x16x32_bf16 v[54:57], v[156:159], v[180:183], v[54:57]
	v_mfma_f32_16x16x32_bf16 v[54:57], v[160:163], v[184:187], v[54:57]
	v_mfma_f32_16x16x32_bf16 v[46:49], v[148:151], v[188:191], v[46:49]
	v_mfma_f32_16x16x32_bf16 v[46:49], v[152:155], v[192:195], v[46:49]
	v_mfma_f32_16x16x32_bf16 v[38:41], v[156:159], v[188:191], v[38:41]
	v_mfma_f32_16x16x32_bf16 v[38:41], v[160:163], v[192:195], v[38:41]
	v_mfma_f32_16x16x32_bf16 v[30:33], v[148:151], v[196:199], v[30:33]
	v_mfma_f32_16x16x32_bf16 v[30:33], v[152:155], v[200:203], v[30:33]
	v_mfma_f32_16x16x32_bf16 v[22:25], v[156:159], v[196:199], v[22:25]
	v_mfma_f32_16x16x32_bf16 v[22:25], v[160:163], v[200:203], v[22:25]
	v_mfma_f32_16x16x32_bf16 v[14:17], v[148:151], v[204:207], v[14:17]
	v_mfma_f32_16x16x32_bf16 v[14:17], v[152:155], v[208:211], v[14:17]
	v_mfma_f32_16x16x32_bf16 v[6:9], v[156:159], v[204:207], v[6:9]
	v_mfma_f32_16x16x32_bf16 v[6:9], v[160:163], v[208:211], v[6:9]
	v_mfma_f32_16x16x32_bf16 v[58:61], v[164:167], v[180:183], v[58:61]
	v_mfma_f32_16x16x32_bf16 v[58:61], v[168:171], v[184:187], v[58:61]
	v_mfma_f32_16x16x32_bf16 v[50:53], v[172:175], v[180:183], v[50:53]
	v_mfma_f32_16x16x32_bf16 v[50:53], v[176:179], v[184:187], v[50:53]
	v_mfma_f32_16x16x32_bf16 v[42:45], v[164:167], v[188:191], v[42:45]
	v_mfma_f32_16x16x32_bf16 v[42:45], v[168:171], v[192:195], v[42:45]
	v_mfma_f32_16x16x32_bf16 v[34:37], v[172:175], v[188:191], v[34:37]
	v_mfma_f32_16x16x32_bf16 v[34:37], v[176:179], v[192:195], v[34:37]
	v_mfma_f32_16x16x32_bf16 v[26:29], v[164:167], v[196:199], v[26:29]
	v_mfma_f32_16x16x32_bf16 v[26:29], v[168:171], v[200:203], v[26:29]
	v_mfma_f32_16x16x32_bf16 v[18:21], v[172:175], v[196:199], v[18:21]
	v_mfma_f32_16x16x32_bf16 v[18:21], v[176:179], v[200:203], v[18:21]
	v_mfma_f32_16x16x32_bf16 v[10:13], v[164:167], v[204:207], v[10:13]
	v_mfma_f32_16x16x32_bf16 v[10:13], v[168:171], v[208:211], v[10:13]
	v_mfma_f32_16x16x32_bf16 v[2:5], v[172:175], v[204:207], v[2:5]
	v_mfma_f32_16x16x32_bf16 v[2:5], v[176:179], v[208:211], v[2:5]
	s_setprio 0
	s_barrier
	s_add_i32 s73, s73, 2
	s_addk_i32 s71, 0x100
	s_addk_i32 s72, 0x100
	s_cmp_ge_i32 s73, s3
	s_cbranch_scc0 .LBB0_642
	s_and_b64 vcc, exec, s[42:43]
	s_cbranch_vccz .LBB0_645

.LBB0_799:
	ds_read_b128 v[134:137], v210
	ds_read_b128 v[138:141], v210 offset:1024
	ds_read_b128 v[142:145], v210 offset:2048
	ds_read_b128 v[148:151], v210 offset:3072
	ds_read_b128 v[152:155], v211
	ds_read_b128 v[156:159], v211 offset:1024
	ds_read_b128 v[160:163], v211 offset:2048
	ds_read_b128 v[164:167], v211 offset:3072
	s_add_i32 s18, s77, 0xffbf8080
	s_cmp_eq_u32 s62, s79
	s_cselect_b32 s80, s6, s18
	s_cselect_b32 s82, s7, s78
	s_or_b32 s81, s80, 0x80
	s_add_i32 s18, s77, 0xffea8000
	s_mov_b32 m0, s63
	ds_read_b128 v[168:171], v212
	ds_read_b128 v[172:175], v212 offset:1024
	ds_read_b128 v[176:179], v212 offset:2048
	ds_read_b128 v[180:183], v212 offset:3072
	ds_read_b128 v[184:187], v212 offset:4096
	ds_read_b128 v[188:191], v212 offset:5120
	ds_read_b128 v[192:195], v212 offset:6144
	ds_read_b128 v[196:199], v212 offset:7168
	buffer_load_dwordx4 v208, s[12:15], s18 offen lds
	s_mov_b32 m0, s66
	s_nop 0
	buffer_load_dwordx4 v208, s[12:15], s77 offen lds
	s_waitcnt vmcnt(8)
	s_waitcnt lgkmcnt(0)
	s_setprio 1
	v_mfma_f32_16x16x32_bf16 v[126:129], v[134:137], v[168:171], v[126:129]
	s_barrier
	v_mfma_f32_16x16x32_bf16 v[126:129], v[138:141], v[172:175], v[126:129]
	v_mfma_f32_16x16x32_bf16 v[122:125], v[142:145], v[168:171], v[122:125]
	v_mfma_f32_16x16x32_bf16 v[122:125], v[148:151], v[172:175], v[122:125]
	v_mfma_f32_16x16x32_bf16 v[118:121], v[134:137], v[176:179], v[118:121]
	v_mfma_f32_16x16x32_bf16 v[118:121], v[138:141], v[180:183], v[118:121]
	v_mfma_f32_16x16x32_bf16 v[114:117], v[142:145], v[176:179], v[114:117]
	v_mfma_f32_16x16x32_bf16 v[114:117], v[148:151], v[180:183], v[114:117]
	v_mfma_f32_16x16x32_bf16 v[106:109], v[134:137], v[184:187], v[106:109]
	v_mfma_f32_16x16x32_bf16 v[106:109], v[138:141], v[188:191], v[106:109]
	v_mfma_f32_16x16x32_bf16 v[98:101], v[142:145], v[184:187], v[98:101]
	v_mfma_f32_16x16x32_bf16 v[98:101], v[148:151], v[188:191], v[98:101]
	v_mfma_f32_16x16x32_bf16 v[90:93], v[134:137], v[192:195], v[90:93]
	v_mfma_f32_16x16x32_bf16 v[90:93], v[138:141], v[196:199], v[90:93]
	v_mfma_f32_16x16x32_bf16 v[82:85], v[142:145], v[192:195], v[82:85]
	v_mfma_f32_16x16x32_bf16 v[82:85], v[148:151], v[196:199], v[82:85]
	v_mfma_f32_16x16x32_bf16 v[110:113], v[152:155], v[168:171], v[110:113]
	v_mfma_f32_16x16x32_bf16 v[110:113], v[156:159], v[172:175], v[110:113]
	v_mfma_f32_16x16x32_bf16 v[102:105], v[160:163], v[168:171], v[102:105]
	v_mfma_f32_16x16x32_bf16 v[102:105], v[164:167], v[172:175], v[102:105]
	v_mfma_f32_16x16x32_bf16 v[94:97], v[152:155], v[176:179], v[94:97]
	v_mfma_f32_16x16x32_bf16 v[94:97], v[156:159], v[180:183], v[94:97]
	v_mfma_f32_16x16x32_bf16 v[86:89], v[160:163], v[176:179], v[86:89]
	v_mfma_f32_16x16x32_bf16 v[86:89], v[164:167], v[180:183], v[86:89]
	v_mfma_f32_16x16x32_bf16 v[78:81], v[152:155], v[184:187], v[78:81]
	v_mfma_f32_16x16x32_bf16 v[78:81], v[156:159], v[188:191], v[78:81]
	v_mfma_f32_16x16x32_bf16 v[74:77], v[160:163], v[184:187], v[74:77]
	v_mfma_f32_16x16x32_bf16 v[74:77], v[164:167], v[188:191], v[74:77]
	v_mfma_f32_16x16x32_bf16 v[70:73], v[152:155], v[192:195], v[70:73]
	v_mfma_f32_16x16x32_bf16 v[70:73], v[156:159], v[196:199], v[70:73]
	v_mfma_f32_16x16x32_bf16 v[66:69], v[160:163], v[192:195], v[66:69]
	v_mfma_f32_16x16x32_bf16 v[66:69], v[164:167], v[196:199], v[66:69]
	s_setprio 0
	s_barrier
	s_mov_b32 m0, s25
	s_mov_b32 s18, s14
	s_mov_b32 s19, s15
	ds_read_b128 v[168:171], v212 offset:16384
	ds_read_b128 v[172:175], v212 offset:17408
	ds_read_b128 v[176:179], v212 offset:18432
	ds_read_b128 v[180:183], v212 offset:19456
	ds_read_b128 v[184:187], v212 offset:20480
	ds_read_b128 v[188:191], v212 offset:21504
	ds_read_b128 v[192:195], v212 offset:22528
	ds_read_b128 v[196:199], v212 offset:23552
	buffer_load_dwordx4 v209, s[16:19], s82 offen lds
	s_add_i32 s83, s82, 0x158000
	s_mov_b32 m0, s27
	s_nop 0
	buffer_load_dwordx4 v209, s[16:19], s83 offen lds
	s_add_i32 s83, s82, 0x2b0000
	s_mov_b32 m0, s30
	s_nop 0
	buffer_load_dwordx4 v209, s[16:19], s83 offen lds
	s_add_i32 s83, s82, 0x408000
	s_mov_b32 m0, s31
	s_nop 0
	buffer_load_dwordx4 v209, s[16:19], s83 offen lds
	s_mov_b32 m0, s21
	s_add_i32 s83, s80, 0x158000
	buffer_load_dwordx4 v208, s[12:15], s80 offen lds
	s_mov_b32 m0, s48
	s_nop 0
	buffer_load_dwordx4 v208, s[12:15], s83 offen lds
	s_waitcnt vmcnt(8)
	s_waitcnt lgkmcnt(0)
	s_setprio 1
	v_mfma_f32_16x16x32_bf16 v[62:65], v[134:137], v[168:171], v[62:65]
	s_barrier
	v_mfma_f32_16x16x32_bf16 v[62:65], v[138:141], v[172:175], v[62:65]
	v_mfma_f32_16x16x32_bf16 v[58:61], v[142:145], v[168:171], v[58:61]
	v_mfma_f32_16x16x32_bf16 v[58:61], v[148:151], v[172:175], v[58:61]
	v_mfma_f32_16x16x32_bf16 v[54:57], v[134:137], v[176:179], v[54:57]
	v_mfma_f32_16x16x32_bf16 v[54:57], v[138:141], v[180:183], v[54:57]
	v_mfma_f32_16x16x32_bf16 v[50:53], v[142:145], v[176:179], v[50:53]
	v_mfma_f32_16x16x32_bf16 v[50:53], v[148:151], v[180:183], v[50:53]
	v_mfma_f32_16x16x32_bf16 v[42:45], v[134:137], v[184:187], v[42:45]
	v_mfma_f32_16x16x32_bf16 v[42:45], v[138:141], v[188:191], v[42:45]
	v_mfma_f32_16x16x32_bf16 v[34:37], v[142:145], v[184:187], v[34:37]
	v_mfma_f32_16x16x32_bf16 v[34:37], v[148:151], v[188:191], v[34:37]
	v_mfma_f32_16x16x32_bf16 v[26:29], v[134:137], v[192:195], v[26:29]
	v_mfma_f32_16x16x32_bf16 v[26:29], v[138:141], v[196:199], v[26:29]
	v_mfma_f32_16x16x32_bf16 v[18:21], v[142:145], v[192:195], v[18:21]
	v_mfma_f32_16x16x32_bf16 v[18:21], v[148:151], v[196:199], v[18:21]
	v_mfma_f32_16x16x32_bf16 v[46:49], v[152:155], v[168:171], v[46:49]
	v_mfma_f32_16x16x32_bf16 v[46:49], v[156:159], v[172:175], v[46:49]
	v_mfma_f32_16x16x32_bf16 v[38:41], v[160:163], v[168:171], v[38:41]
	v_mfma_f32_16x16x32_bf16 v[38:41], v[164:167], v[172:175], v[38:41]
	v_mfma_f32_16x16x32_bf16 v[30:33], v[152:155], v[176:179], v[30:33]
	v_mfma_f32_16x16x32_bf16 v[30:33], v[156:159], v[180:183], v[30:33]
	v_mfma_f32_16x16x32_bf16 v[22:25], v[160:163], v[176:179], v[22:25]
	v_mfma_f32_16x16x32_bf16 v[22:25], v[164:167], v[180:183], v[22:25]
	v_mfma_f32_16x16x32_bf16 v[14:17], v[152:155], v[184:187], v[14:17]
	v_mfma_f32_16x16x32_bf16 v[14:17], v[156:159], v[188:191], v[14:17]
	v_mfma_f32_16x16x32_bf16 v[10:13], v[160:163], v[184:187], v[10:13]
	v_mfma_f32_16x16x32_bf16 v[10:13], v[164:167], v[188:191], v[10:13]
	v_mfma_f32_16x16x32_bf16 v[6:9], v[152:155], v[192:195], v[6:9]
	v_mfma_f32_16x16x32_bf16 v[6:9], v[156:159], v[196:199], v[6:9]
	v_mfma_f32_16x16x32_bf16 v[2:5], v[160:163], v[192:195], v[2:5]
	v_mfma_f32_16x16x32_bf16 v[2:5], v[164:167], v[196:199], v[2:5]
	s_setprio 0
	s_barrier
	ds_read_b128 v[134:137], v213
	ds_read_b128 v[138:141], v213 offset:1024
	ds_read_b128 v[142:145], v213 offset:2048
	ds_read_b128 v[148:151], v213 offset:3072
	ds_read_b128 v[152:155], v214
	ds_read_b128 v[156:159], v214 offset:1024
	ds_read_b128 v[160:163], v214 offset:2048
	ds_read_b128 v[164:167], v214 offset:3072
	s_mov_b32 m0, s49
	s_add_i32 s83, s80, 0x2b0000
	ds_read_b128 v[168:171], v212 offset:32768
	ds_read_b128 v[172:175], v212 offset:33792
	ds_read_b128 v[176:179], v212 offset:34816
	ds_read_b128 v[180:183], v212 offset:35840
	ds_read_b128 v[184:187], v212 offset:36864
	ds_read_b128 v[188:191], v212 offset:37888
	ds_read_b128 v[192:195], v212 offset:38912
	ds_read_b128 v[196:199], v212 offset:39936
	buffer_load_dwordx4 v208, s[12:15], s83 offen lds
	s_add_i32 s83, s80, 0x408000
	s_mov_b32 m0, s50
	s_nop 0
	buffer_load_dwordx4 v208, s[12:15], s83 offen lds
	s_waitcnt vmcnt(8)
	s_waitcnt lgkmcnt(0)
	s_setprio 1
	v_mfma_f32_16x16x32_bf16 v[126:129], v[134:137], v[168:171], v[126:129]
	s_barrier
	v_mfma_f32_16x16x32_bf16 v[126:129], v[138:141], v[172:175], v[126:129]
	v_mfma_f32_16x16x32_bf16 v[122:125], v[142:145], v[168:171], v[122:125]
	v_mfma_f32_16x16x32_bf16 v[122:125], v[148:151], v[172:175], v[122:125]
	v_mfma_f32_16x16x32_bf16 v[118:121], v[134:137], v[176:179], v[118:121]
	v_mfma_f32_16x16x32_bf16 v[118:121], v[138:141], v[180:183], v[118:121]
	v_mfma_f32_16x16x32_bf16 v[114:117], v[142:145], v[176:179], v[114:117]
	v_mfma_f32_16x16x32_bf16 v[114:117], v[148:151], v[180:183], v[114:117]
	v_mfma_f32_16x16x32_bf16 v[106:109], v[134:137], v[184:187], v[106:109]
	v_mfma_f32_16x16x32_bf16 v[106:109], v[138:141], v[188:191], v[106:109]
	v_mfma_f32_16x16x32_bf16 v[98:101], v[142:145], v[184:187], v[98:101]
	v_mfma_f32_16x16x32_bf16 v[98:101], v[148:151], v[188:191], v[98:101]
	v_mfma_f32_16x16x32_bf16 v[90:93], v[134:137], v[192:195], v[90:93]
	v_mfma_f32_16x16x32_bf16 v[90:93], v[138:141], v[196:199], v[90:93]
	v_mfma_f32_16x16x32_bf16 v[82:85], v[142:145], v[192:195], v[82:85]
	v_mfma_f32_16x16x32_bf16 v[82:85], v[148:151], v[196:199], v[82:85]
	v_mfma_f32_16x16x32_bf16 v[110:113], v[152:155], v[168:171], v[110:113]
	v_mfma_f32_16x16x32_bf16 v[110:113], v[156:159], v[172:175], v[110:113]
	v_mfma_f32_16x16x32_bf16 v[102:105], v[160:163], v[168:171], v[102:105]
	v_mfma_f32_16x16x32_bf16 v[102:105], v[164:167], v[172:175], v[102:105]
	v_mfma_f32_16x16x32_bf16 v[94:97], v[152:155], v[176:179], v[94:97]
	v_mfma_f32_16x16x32_bf16 v[94:97], v[156:159], v[180:183], v[94:97]
	v_mfma_f32_16x16x32_bf16 v[86:89], v[160:163], v[176:179], v[86:89]
	v_mfma_f32_16x16x32_bf16 v[86:89], v[164:167], v[180:183], v[86:89]
	v_mfma_f32_16x16x32_bf16 v[78:81], v[152:155], v[184:187], v[78:81]
	v_mfma_f32_16x16x32_bf16 v[78:81], v[156:159], v[188:191], v[78:81]
	v_mfma_f32_16x16x32_bf16 v[74:77], v[160:163], v[184:187], v[74:77]
	v_mfma_f32_16x16x32_bf16 v[74:77], v[164:167], v[188:191], v[74:77]
	v_mfma_f32_16x16x32_bf16 v[70:73], v[152:155], v[192:195], v[70:73]
	v_mfma_f32_16x16x32_bf16 v[70:73], v[156:159], v[196:199], v[70:73]
	v_mfma_f32_16x16x32_bf16 v[66:69], v[160:163], v[192:195], v[66:69]
	v_mfma_f32_16x16x32_bf16 v[66:69], v[164:167], v[196:199], v[66:69]
	s_setprio 0
	s_barrier
	s_mov_b32 m0, s54
	s_or_b32 s83, s82, 0x80
	ds_read_b128 v[168:171], v212 offset:49152
	ds_read_b128 v[172:175], v212 offset:50176
	ds_read_b128 v[176:179], v212 offset:51200
	ds_read_b128 v[180:183], v212 offset:52224
	ds_read_b128 v[184:187], v212 offset:53248
	ds_read_b128 v[188:191], v212 offset:54272
	ds_read_b128 v[192:195], v212 offset:55296
	ds_read_b128 v[196:199], v212 offset:56320
	buffer_load_dwordx4 v209, s[16:19], s83 offen lds
	s_add_i32 s83, s82, 0x158080
	s_mov_b32 m0, s55
	s_add_i32 s80, s80, 0x158080
	buffer_load_dwordx4 v209, s[16:19], s83 offen lds
	s_add_i32 s83, s82, 0x2b0080
	s_mov_b32 m0, s58
	s_add_i32 s82, s82, 0x408080
	buffer_load_dwordx4 v209, s[16:19], s83 offen lds
	s_mov_b32 m0, s59
	s_nop 0
	buffer_load_dwordx4 v209, s[16:19], s82 offen lds
	s_mov_b32 m0, s56
	s_nop 0
	buffer_load_dwordx4 v208, s[12:15], s81 offen lds
	s_mov_b32 m0, s57
	s_nop 0
	buffer_load_dwordx4 v208, s[12:15], s80 offen lds
	s_waitcnt vmcnt(8)
	s_waitcnt lgkmcnt(0)
	s_setprio 1
	v_mfma_f32_16x16x32_bf16 v[62:65], v[134:137], v[168:171], v[62:65]
	s_barrier
	v_mfma_f32_16x16x32_bf16 v[62:65], v[138:141], v[172:175], v[62:65]
	v_mfma_f32_16x16x32_bf16 v[58:61], v[142:145], v[168:171], v[58:61]
	v_mfma_f32_16x16x32_bf16 v[58:61], v[148:151], v[172:175], v[58:61]
	v_mfma_f32_16x16x32_bf16 v[54:57], v[134:137], v[176:179], v[54:57]
	v_mfma_f32_16x16x32_bf16 v[54:57], v[138:141], v[180:183], v[54:57]
	v_mfma_f32_16x16x32_bf16 v[50:53], v[142:145], v[176:179], v[50:53]
	v_mfma_f32_16x16x32_bf16 v[50:53], v[148:151], v[180:183], v[50:53]
	v_mfma_f32_16x16x32_bf16 v[42:45], v[134:137], v[184:187], v[42:45]
	v_mfma_f32_16x16x32_bf16 v[42:45], v[138:141], v[188:191], v[42:45]
	v_mfma_f32_16x16x32_bf16 v[34:37], v[142:145], v[184:187], v[34:37]
	v_mfma_f32_16x16x32_bf16 v[34:37], v[148:151], v[188:191], v[34:37]
	v_mfma_f32_16x16x32_bf16 v[26:29], v[134:137], v[192:195], v[26:29]
	v_mfma_f32_16x16x32_bf16 v[26:29], v[138:141], v[196:199], v[26:29]
	v_mfma_f32_16x16x32_bf16 v[18:21], v[142:145], v[192:195], v[18:21]
	v_mfma_f32_16x16x32_bf16 v[18:21], v[148:151], v[196:199], v[18:21]
	v_mfma_f32_16x16x32_bf16 v[46:49], v[152:155], v[168:171], v[46:49]
	v_mfma_f32_16x16x32_bf16 v[46:49], v[156:159], v[172:175], v[46:49]
	v_mfma_f32_16x16x32_bf16 v[38:41], v[160:163], v[168:171], v[38:41]
	v_mfma_f32_16x16x32_bf16 v[38:41], v[164:167], v[172:175], v[38:41]
	v_mfma_f32_16x16x32_bf16 v[30:33], v[152:155], v[176:179], v[30:33]
	v_mfma_f32_16x16x32_bf16 v[30:33], v[156:159], v[180:183], v[30:33]
	v_mfma_f32_16x16x32_bf16 v[22:25], v[160:163], v[176:179], v[22:25]
	v_mfma_f32_16x16x32_bf16 v[22:25], v[164:167], v[180:183], v[22:25]
	v_mfma_f32_16x16x32_bf16 v[14:17], v[152:155], v[184:187], v[14:17]
	v_mfma_f32_16x16x32_bf16 v[14:17], v[156:159], v[188:191], v[14:17]
	v_mfma_f32_16x16x32_bf16 v[10:13], v[160:163], v[184:187], v[10:13]
	v_mfma_f32_16x16x32_bf16 v[10:13], v[164:167], v[188:191], v[10:13]
	v_mfma_f32_16x16x32_bf16 v[6:9], v[152:155], v[192:195], v[6:9]
	v_mfma_f32_16x16x32_bf16 v[6:9], v[156:159], v[196:199], v[6:9]
	v_mfma_f32_16x16x32_bf16 v[2:5], v[160:163], v[192:195], v[2:5]
	v_mfma_f32_16x16x32_bf16 v[2:5], v[164:167], v[196:199], v[2:5]
	s_setprio 0
	s_barrier
	s_add_i32 s79, s79, 2
	s_addk_i32 s77, 0x100
	s_addk_i32 s78, 0x100
	s_cmp_ge_i32 s79, s3
	s_cbranch_scc0 .LBB0_799
	v_pk_mul_f32 v[184:185], v[128:129], 0.5 op_sel_hi:[1,0]
	v_pk_mul_f32 v[186:187], v[126:127], 0.5 op_sel_hi:[1,0]
	v_pk_mul_f32 v[188:189], v[124:125], 0.5 op_sel_hi:[1,0]
	v_pk_mul_f32 v[190:191], v[122:123], 0.5 op_sel_hi:[1,0]
	v_pk_mul_f32 v[198:199], v[112:113], 0.5 op_sel_hi:[1,0]
	v_pk_mul_f32 v[196:197], v[110:111], 0.5 op_sel_hi:[1,0]
	v_pk_mul_f32 v[194:195], v[104:105], 0.5 op_sel_hi:[1,0]
	v_pk_mul_f32 v[192:193], v[102:103], 0.5 op_sel_hi:[1,0]
	v_pk_mul_f32 v[182:183], v[120:121], 0.5 op_sel_hi:[1,0]
	v_pk_mul_f32 v[180:181], v[118:119], 0.5 op_sel_hi:[1,0]
	v_pk_mul_f32 v[178:179], v[116:117], 0.5 op_sel_hi:[1,0]
	v_pk_mul_f32 v[176:177], v[114:115], 0.5 op_sel_hi:[1,0]
	v_pk_mul_f32 v[172:173], v[96:97], 0.5 op_sel_hi:[1,0]
	v_pk_mul_f32 v[170:171], v[94:95], 0.5 op_sel_hi:[1,0]
	v_pk_mul_f32 v[168:169], v[88:89], 0.5 op_sel_hi:[1,0]
	v_pk_mul_f32 v[166:167], v[86:87], 0.5 op_sel_hi:[1,0]
	v_pk_mul_f32 v[164:165], v[108:109], 0.5 op_sel_hi:[1,0]
	v_pk_mul_f32 v[162:163], v[106:107], 0.5 op_sel_hi:[1,0]
	v_pk_mul_f32 v[160:161], v[100:101], 0.5 op_sel_hi:[1,0]
	v_pk_mul_f32 v[158:159], v[98:99], 0.5 op_sel_hi:[1,0]
	v_pk_mul_f32 v[156:157], v[80:81], 0.5 op_sel_hi:[1,0]
	v_pk_mul_f32 v[154:155], v[78:79], 0.5 op_sel_hi:[1,0]
	v_pk_mul_f32 v[152:153], v[76:77], 0.5 op_sel_hi:[1,0]
	v_pk_mul_f32 v[150:151], v[74:75], 0.5 op_sel_hi:[1,0]
	v_pk_mul_f32 v[144:145], v[92:93], 0.5 op_sel_hi:[1,0]
	v_pk_mul_f32 v[142:143], v[90:91], 0.5 op_sel_hi:[1,0]
	v_pk_mul_f32 v[140:141], v[84:85], 0.5 op_sel_hi:[1,0]
	v_pk_mul_f32 v[138:139], v[82:83], 0.5 op_sel_hi:[1,0]
	v_pk_mul_f32 v[136:137], v[72:73], 0.5 op_sel_hi:[1,0]
	v_pk_mul_f32 v[134:135], v[70:71], 0.5 op_sel_hi:[1,0]
	v_pk_mul_f32 v[128:129], v[68:69], 0.5 op_sel_hi:[1,0]
	v_pk_mul_f32 v[126:127], v[66:67], 0.5 op_sel_hi:[1,0]
	v_pk_mul_f32 v[122:123], v[64:65], 0.5 op_sel_hi:[1,0]
	v_pk_mul_f32 v[120:121], v[62:63], 0.5 op_sel_hi:[1,0]
	v_pk_mul_f32 v[118:119], v[60:61], 0.5 op_sel_hi:[1,0]
	v_pk_mul_f32 v[116:117], v[58:59], 0.5 op_sel_hi:[1,0]
	v_pk_mul_f32 v[112:113], v[48:49], 0.5 op_sel_hi:[1,0]
	v_pk_mul_f32 v[110:111], v[46:47], 0.5 op_sel_hi:[1,0]
	v_pk_mul_f32 v[108:109], v[40:41], 0.5 op_sel_hi:[1,0]
	v_pk_mul_f32 v[106:107], v[38:39], 0.5 op_sel_hi:[1,0]
	v_pk_mul_f32 v[104:105], v[56:57], 0.5 op_sel_hi:[1,0]
	v_pk_mul_f32 v[102:103], v[54:55], 0.5 op_sel_hi:[1,0]
	v_pk_mul_f32 v[100:101], v[52:53], 0.5 op_sel_hi:[1,0]
	v_pk_mul_f32 v[98:99], v[50:51], 0.5 op_sel_hi:[1,0]
	v_pk_mul_f32 v[96:97], v[32:33], 0.5 op_sel_hi:[1,0]
	v_pk_mul_f32 v[94:95], v[30:31], 0.5 op_sel_hi:[1,0]
	v_pk_mul_f32 v[92:93], v[24:25], 0.5 op_sel_hi:[1,0]
	v_pk_mul_f32 v[90:91], v[22:23], 0.5 op_sel_hi:[1,0]
	v_pk_mul_f32 v[88:89], v[44:45], 0.5 op_sel_hi:[1,0]
	v_pk_mul_f32 v[86:87], v[42:43], 0.5 op_sel_hi:[1,0]
	v_pk_mul_f32 v[84:85], v[36:37], 0.5 op_sel_hi:[1,0]
	v_pk_mul_f32 v[82:83], v[34:35], 0.5 op_sel_hi:[1,0]
	v_pk_mul_f32 v[80:81], v[16:17], 0.5 op_sel_hi:[1,0]
	v_pk_mul_f32 v[78:79], v[14:15], 0.5 op_sel_hi:[1,0]
	v_pk_mul_f32 v[76:77], v[12:13], 0.5 op_sel_hi:[1,0]
	v_pk_mul_f32 v[74:75], v[10:11], 0.5 op_sel_hi:[1,0]
	v_pk_mul_f32 v[72:73], v[28:29], 0.5 op_sel_hi:[1,0]
	v_pk_mul_f32 v[70:71], v[26:27], 0.5 op_sel_hi:[1,0]
	v_pk_mul_f32 v[68:69], v[20:21], 0.5 op_sel_hi:[1,0]
	v_pk_mul_f32 v[66:67], v[18:19], 0.5 op_sel_hi:[1,0]
	v_pk_mul_f32 v[64:65], v[8:9], 0.5 op_sel_hi:[1,0]
	v_pk_mul_f32 v[62:63], v[6:7], 0.5 op_sel_hi:[1,0]
	v_pk_mul_f32 v[60:61], v[4:5], 0.5 op_sel_hi:[1,0]
	v_pk_mul_f32 v[58:59], v[2:3], 0.5 op_sel_hi:[1,0]
	s_and_b64 vcc, exec, s[38:39]
	s_cbranch_vccz .LBB0_802

.LBB0_892:
	ds_read_b128 v[130:133], v172
	ds_read_b128 v[134:137], v172 offset:1024
	ds_read_b128 v[148:151], v172 offset:2048
	ds_read_b128 v[152:155], v172 offset:3072
	ds_read_b128 v[156:159], v173
	ds_read_b128 v[160:163], v173 offset:1024
	ds_read_b128 v[164:167], v173 offset:2048
	ds_read_b128 v[180:183], v173 offset:3072
	s_add_i32 s18, s8, 0xffe80080
	s_cmp_eq_u32 s77, s52
	s_cselect_b32 s53, s6, s18
	s_cselect_b32 s58, s7, s9
	s_or_b32 s57, s53, 0x80
	s_add_i32 s18, s8, 0xfff80000
	s_mov_b32 m0, s78
	ds_read_b128 v[184:187], v174
	ds_read_b128 v[188:191], v174 offset:1024
	ds_read_b128 v[192:195], v174 offset:2048
	ds_read_b128 v[196:199], v174 offset:3072
	ds_read_b128 v[200:203], v174 offset:4096
	ds_read_b128 v[204:207], v174 offset:5120
	ds_read_b128 v[208:211], v174 offset:6144
	ds_read_b128 v[212:215], v174 offset:7168
	buffer_load_dwordx4 v170, s[12:15], s18 offen lds
	s_mov_b32 m0, s79
	s_nop 0
	buffer_load_dwordx4 v170, s[12:15], s8 offen lds
	s_waitcnt vmcnt(8)
	s_waitcnt lgkmcnt(0)
	s_setprio 1
	v_mfma_f32_16x16x32_bf16 v[126:129], v[130:133], v[184:187], v[126:129]
	s_barrier
	v_mfma_f32_16x16x32_bf16 v[126:129], v[134:137], v[188:191], v[126:129]
	v_mfma_f32_16x16x32_bf16 v[118:121], v[148:151], v[184:187], v[118:121]
	v_mfma_f32_16x16x32_bf16 v[118:121], v[152:155], v[188:191], v[118:121]
	v_mfma_f32_16x16x32_bf16 v[110:113], v[130:133], v[192:195], v[110:113]
	v_mfma_f32_16x16x32_bf16 v[110:113], v[134:137], v[196:199], v[110:113]
	v_mfma_f32_16x16x32_bf16 v[102:105], v[148:151], v[192:195], v[102:105]
	v_mfma_f32_16x16x32_bf16 v[102:105], v[152:155], v[196:199], v[102:105]
	v_mfma_f32_16x16x32_bf16 v[94:97], v[130:133], v[200:203], v[94:97]
	v_mfma_f32_16x16x32_bf16 v[94:97], v[134:137], v[204:207], v[94:97]
	v_mfma_f32_16x16x32_bf16 v[90:93], v[148:151], v[200:203], v[90:93]
	v_mfma_f32_16x16x32_bf16 v[90:93], v[152:155], v[204:207], v[90:93]
	v_mfma_f32_16x16x32_bf16 v[78:81], v[130:133], v[208:211], v[78:81]
	v_mfma_f32_16x16x32_bf16 v[78:81], v[134:137], v[212:215], v[78:81]
	v_mfma_f32_16x16x32_bf16 v[70:73], v[148:151], v[208:211], v[70:73]
	v_mfma_f32_16x16x32_bf16 v[70:73], v[152:155], v[212:215], v[70:73]
	v_mfma_f32_16x16x32_bf16 v[122:125], v[156:159], v[184:187], v[122:125]
	v_mfma_f32_16x16x32_bf16 v[122:125], v[160:163], v[188:191], v[122:125]
	v_mfma_f32_16x16x32_bf16 v[114:117], v[164:167], v[184:187], v[114:117]
	v_mfma_f32_16x16x32_bf16 v[114:117], v[180:183], v[188:191], v[114:117]
	v_mfma_f32_16x16x32_bf16 v[106:109], v[156:159], v[192:195], v[106:109]
	v_mfma_f32_16x16x32_bf16 v[106:109], v[160:163], v[196:199], v[106:109]
	v_mfma_f32_16x16x32_bf16 v[98:101], v[164:167], v[192:195], v[98:101]
	v_mfma_f32_16x16x32_bf16 v[98:101], v[180:183], v[196:199], v[98:101]
	v_mfma_f32_16x16x32_bf16 v[86:89], v[156:159], v[200:203], v[86:89]
	v_mfma_f32_16x16x32_bf16 v[86:89], v[160:163], v[204:207], v[86:89]
	v_mfma_f32_16x16x32_bf16 v[82:85], v[164:167], v[200:203], v[82:85]
	v_mfma_f32_16x16x32_bf16 v[82:85], v[180:183], v[204:207], v[82:85]
	v_mfma_f32_16x16x32_bf16 v[74:77], v[156:159], v[208:211], v[74:77]
	v_mfma_f32_16x16x32_bf16 v[74:77], v[160:163], v[212:215], v[74:77]
	v_mfma_f32_16x16x32_bf16 v[66:69], v[164:167], v[208:211], v[66:69]
	v_mfma_f32_16x16x32_bf16 v[66:69], v[180:183], v[212:215], v[66:69]
	s_setprio 0
	s_barrier
	s_mov_b32 m0, s27
	s_mov_b32 s18, s14
	s_mov_b32 s19, s15
	ds_read_b128 v[184:187], v174 offset:16384
	ds_read_b128 v[188:191], v174 offset:17408
	ds_read_b128 v[192:195], v174 offset:18432
	ds_read_b128 v[196:199], v174 offset:19456
	ds_read_b128 v[200:203], v174 offset:20480
	ds_read_b128 v[204:207], v174 offset:21504
	ds_read_b128 v[208:211], v174 offset:22528
	ds_read_b128 v[212:215], v174 offset:23552
	buffer_load_dwordx4 v171, s[16:19], s58 offen lds
	s_add_i32 s59, s58, 0x80000
	s_mov_b32 m0, s60
	s_nop 0
	buffer_load_dwordx4 v171, s[16:19], s59 offen lds
	s_add_i32 s59, s58, 0x100000
	s_mov_b32 m0, s61
	s_nop 0
	buffer_load_dwordx4 v171, s[16:19], s59 offen lds
	s_add_i32 s59, s58, 0x180000
	s_mov_b32 m0, s62
	s_nop 0
	buffer_load_dwordx4 v171, s[16:19], s59 offen lds
	s_mov_b32 m0, s25
	s_add_i32 s59, s53, 0x80000
	buffer_load_dwordx4 v170, s[12:15], s53 offen lds
	s_mov_b32 m0, s63
	s_nop 0
	buffer_load_dwordx4 v170, s[12:15], s59 offen lds
	s_waitcnt vmcnt(8)
	s_waitcnt lgkmcnt(0)
	s_setprio 1
	v_mfma_f32_16x16x32_bf16 v[62:65], v[130:133], v[184:187], v[62:65]
	s_barrier
	v_mfma_f32_16x16x32_bf16 v[62:65], v[134:137], v[188:191], v[62:65]
	v_mfma_f32_16x16x32_bf16 v[54:57], v[148:151], v[184:187], v[54:57]
	v_mfma_f32_16x16x32_bf16 v[54:57], v[152:155], v[188:191], v[54:57]
	v_mfma_f32_16x16x32_bf16 v[46:49], v[130:133], v[192:195], v[46:49]
	v_mfma_f32_16x16x32_bf16 v[46:49], v[134:137], v[196:199], v[46:49]
	v_mfma_f32_16x16x32_bf16 v[38:41], v[148:151], v[192:195], v[38:41]
	v_mfma_f32_16x16x32_bf16 v[38:41], v[152:155], v[196:199], v[38:41]
	v_mfma_f32_16x16x32_bf16 v[30:33], v[130:133], v[200:203], v[30:33]
	v_mfma_f32_16x16x32_bf16 v[30:33], v[134:137], v[204:207], v[30:33]
	v_mfma_f32_16x16x32_bf16 v[22:25], v[148:151], v[200:203], v[22:25]
	v_mfma_f32_16x16x32_bf16 v[22:25], v[152:155], v[204:207], v[22:25]
	v_mfma_f32_16x16x32_bf16 v[14:17], v[130:133], v[208:211], v[14:17]
	v_mfma_f32_16x16x32_bf16 v[14:17], v[134:137], v[212:215], v[14:17]
	v_mfma_f32_16x16x32_bf16 v[6:9], v[148:151], v[208:211], v[6:9]
	v_mfma_f32_16x16x32_bf16 v[6:9], v[152:155], v[212:215], v[6:9]
	v_mfma_f32_16x16x32_bf16 v[58:61], v[156:159], v[184:187], v[58:61]
	v_mfma_f32_16x16x32_bf16 v[58:61], v[160:163], v[188:191], v[58:61]
	v_mfma_f32_16x16x32_bf16 v[50:53], v[164:167], v[184:187], v[50:53]
	v_mfma_f32_16x16x32_bf16 v[50:53], v[180:183], v[188:191], v[50:53]
	v_mfma_f32_16x16x32_bf16 v[42:45], v[156:159], v[192:195], v[42:45]
	v_mfma_f32_16x16x32_bf16 v[42:45], v[160:163], v[196:199], v[42:45]
	v_mfma_f32_16x16x32_bf16 v[34:37], v[164:167], v[192:195], v[34:37]
	v_mfma_f32_16x16x32_bf16 v[34:37], v[180:183], v[196:199], v[34:37]
	v_mfma_f32_16x16x32_bf16 v[26:29], v[156:159], v[200:203], v[26:29]
	v_mfma_f32_16x16x32_bf16 v[26:29], v[160:163], v[204:207], v[26:29]
	v_mfma_f32_16x16x32_bf16 v[18:21], v[164:167], v[200:203], v[18:21]
	v_mfma_f32_16x16x32_bf16 v[18:21], v[180:183], v[204:207], v[18:21]
	v_mfma_f32_16x16x32_bf16 v[10:13], v[156:159], v[208:211], v[10:13]
	v_mfma_f32_16x16x32_bf16 v[10:13], v[160:163], v[212:215], v[10:13]
	v_mfma_f32_16x16x32_bf16 v[2:5], v[164:167], v[208:211], v[2:5]
	v_mfma_f32_16x16x32_bf16 v[2:5], v[180:183], v[212:215], v[2:5]
	s_setprio 0
	s_barrier
	ds_read_b128 v[130:133], v175
	ds_read_b128 v[134:137], v175 offset:1024
	ds_read_b128 v[148:151], v175 offset:2048
	ds_read_b128 v[152:155], v175 offset:3072
	ds_read_b128 v[156:159], v176
	ds_read_b128 v[160:163], v176 offset:1024
	ds_read_b128 v[164:167], v176 offset:2048
	ds_read_b128 v[180:183], v176 offset:3072
	s_mov_b32 m0, s64
	s_add_i32 s59, s53, 0x100000
	ds_read_b128 v[184:187], v174 offset:32768
	ds_read_b128 v[188:191], v174 offset:33792
	ds_read_b128 v[192:195], v174 offset:34816
	ds_read_b128 v[196:199], v174 offset:35840
	ds_read_b128 v[200:203], v174 offset:36864
	ds_read_b128 v[204:207], v174 offset:37888
	ds_read_b128 v[208:211], v174 offset:38912
	ds_read_b128 v[212:215], v174 offset:39936
	buffer_load_dwordx4 v170, s[12:15], s59 offen lds
	s_add_i32 s59, s53, 0x180000
	s_mov_b32 m0, s65
	s_nop 0
	buffer_load_dwordx4 v170, s[12:15], s59 offen lds
	s_waitcnt vmcnt(8)
	s_waitcnt lgkmcnt(0)
	s_setprio 1
	v_mfma_f32_16x16x32_bf16 v[126:129], v[130:133], v[184:187], v[126:129]
	s_barrier
	v_mfma_f32_16x16x32_bf16 v[126:129], v[134:137], v[188:191], v[126:129]
	v_mfma_f32_16x16x32_bf16 v[118:121], v[148:151], v[184:187], v[118:121]
	v_mfma_f32_16x16x32_bf16 v[118:121], v[152:155], v[188:191], v[118:121]
	v_mfma_f32_16x16x32_bf16 v[110:113], v[130:133], v[192:195], v[110:113]
	v_mfma_f32_16x16x32_bf16 v[110:113], v[134:137], v[196:199], v[110:113]
	v_mfma_f32_16x16x32_bf16 v[102:105], v[148:151], v[192:195], v[102:105]
	v_mfma_f32_16x16x32_bf16 v[102:105], v[152:155], v[196:199], v[102:105]
	v_mfma_f32_16x16x32_bf16 v[94:97], v[130:133], v[200:203], v[94:97]
	v_mfma_f32_16x16x32_bf16 v[94:97], v[134:137], v[204:207], v[94:97]
	v_mfma_f32_16x16x32_bf16 v[90:93], v[148:151], v[200:203], v[90:93]
	v_mfma_f32_16x16x32_bf16 v[90:93], v[152:155], v[204:207], v[90:93]
	v_mfma_f32_16x16x32_bf16 v[78:81], v[130:133], v[208:211], v[78:81]
	v_mfma_f32_16x16x32_bf16 v[78:81], v[134:137], v[212:215], v[78:81]
	v_mfma_f32_16x16x32_bf16 v[70:73], v[148:151], v[208:211], v[70:73]
	v_mfma_f32_16x16x32_bf16 v[70:73], v[152:155], v[212:215], v[70:73]
	v_mfma_f32_16x16x32_bf16 v[122:125], v[156:159], v[184:187], v[122:125]
	v_mfma_f32_16x16x32_bf16 v[122:125], v[160:163], v[188:191], v[122:125]
	v_mfma_f32_16x16x32_bf16 v[114:117], v[164:167], v[184:187], v[114:117]
	v_mfma_f32_16x16x32_bf16 v[114:117], v[180:183], v[188:191], v[114:117]
	v_mfma_f32_16x16x32_bf16 v[106:109], v[156:159], v[192:195], v[106:109]
	v_mfma_f32_16x16x32_bf16 v[106:109], v[160:163], v[196:199], v[106:109]
	v_mfma_f32_16x16x32_bf16 v[98:101], v[164:167], v[192:195], v[98:101]
	v_mfma_f32_16x16x32_bf16 v[98:101], v[180:183], v[196:199], v[98:101]
	v_mfma_f32_16x16x32_bf16 v[86:89], v[156:159], v[200:203], v[86:89]
	v_mfma_f32_16x16x32_bf16 v[86:89], v[160:163], v[204:207], v[86:89]
	v_mfma_f32_16x16x32_bf16 v[82:85], v[164:167], v[200:203], v[82:85]
	v_mfma_f32_16x16x32_bf16 v[82:85], v[180:183], v[204:207], v[82:85]
	v_mfma_f32_16x16x32_bf16 v[74:77], v[156:159], v[208:211], v[74:77]
	v_mfma_f32_16x16x32_bf16 v[74:77], v[160:163], v[212:215], v[74:77]
	v_mfma_f32_16x16x32_bf16 v[66:69], v[164:167], v[208:211], v[66:69]
	v_mfma_f32_16x16x32_bf16 v[66:69], v[180:183], v[212:215], v[66:69]
	s_setprio 0
	s_barrier
	s_mov_b32 m0, s70
	s_or_b32 s59, s58, 0x80
	ds_read_b128 v[184:187], v174 offset:49152
	ds_read_b128 v[188:191], v174 offset:50176
	ds_read_b128 v[192:195], v174 offset:51200
	ds_read_b128 v[196:199], v174 offset:52224
	ds_read_b128 v[200:203], v174 offset:53248
	ds_read_b128 v[204:207], v174 offset:54272
	ds_read_b128 v[208:211], v174 offset:55296
	ds_read_b128 v[212:215], v174 offset:56320
	buffer_load_dwordx4 v171, s[16:19], s59 offen lds
	s_add_i32 s59, s58, 0x80080
	s_mov_b32 m0, s71
	s_add_i32 s53, s53, 0x80080
	buffer_load_dwordx4 v171, s[16:19], s59 offen lds
	s_add_i32 s59, s58, 0x100080
	s_mov_b32 m0, s74
	s_add_i32 s58, s58, 0x180080
	buffer_load_dwordx4 v171, s[16:19], s59 offen lds
	s_mov_b32 m0, s75
	s_nop 0
	buffer_load_dwordx4 v171, s[16:19], s58 offen lds
	s_mov_b32 m0, s72
	s_nop 0
	buffer_load_dwordx4 v170, s[12:15], s57 offen lds
	s_mov_b32 m0, s73
	s_nop 0
	buffer_load_dwordx4 v170, s[12:15], s53 offen lds
	s_waitcnt vmcnt(8)
	s_waitcnt lgkmcnt(0)
	s_setprio 1
	v_mfma_f32_16x16x32_bf16 v[62:65], v[130:133], v[184:187], v[62:65]
	s_barrier
	v_mfma_f32_16x16x32_bf16 v[62:65], v[134:137], v[188:191], v[62:65]
	v_mfma_f32_16x16x32_bf16 v[54:57], v[148:151], v[184:187], v[54:57]
	v_mfma_f32_16x16x32_bf16 v[54:57], v[152:155], v[188:191], v[54:57]
	v_mfma_f32_16x16x32_bf16 v[46:49], v[130:133], v[192:195], v[46:49]
	v_mfma_f32_16x16x32_bf16 v[46:49], v[134:137], v[196:199], v[46:49]
	v_mfma_f32_16x16x32_bf16 v[38:41], v[148:151], v[192:195], v[38:41]
	v_mfma_f32_16x16x32_bf16 v[38:41], v[152:155], v[196:199], v[38:41]
	v_mfma_f32_16x16x32_bf16 v[30:33], v[130:133], v[200:203], v[30:33]
	v_mfma_f32_16x16x32_bf16 v[30:33], v[134:137], v[204:207], v[30:33]
	v_mfma_f32_16x16x32_bf16 v[22:25], v[148:151], v[200:203], v[22:25]
	v_mfma_f32_16x16x32_bf16 v[22:25], v[152:155], v[204:207], v[22:25]
	v_mfma_f32_16x16x32_bf16 v[14:17], v[130:133], v[208:211], v[14:17]
	v_mfma_f32_16x16x32_bf16 v[14:17], v[134:137], v[212:215], v[14:17]
	v_mfma_f32_16x16x32_bf16 v[6:9], v[148:151], v[208:211], v[6:9]
	v_mfma_f32_16x16x32_bf16 v[6:9], v[152:155], v[212:215], v[6:9]
	v_mfma_f32_16x16x32_bf16 v[58:61], v[156:159], v[184:187], v[58:61]
	v_mfma_f32_16x16x32_bf16 v[58:61], v[160:163], v[188:191], v[58:61]
	v_mfma_f32_16x16x32_bf16 v[50:53], v[164:167], v[184:187], v[50:53]
	v_mfma_f32_16x16x32_bf16 v[50:53], v[180:183], v[188:191], v[50:53]
	v_mfma_f32_16x16x32_bf16 v[42:45], v[156:159], v[192:195], v[42:45]
	v_mfma_f32_16x16x32_bf16 v[42:45], v[160:163], v[196:199], v[42:45]
	v_mfma_f32_16x16x32_bf16 v[34:37], v[164:167], v[192:195], v[34:37]
	v_mfma_f32_16x16x32_bf16 v[34:37], v[180:183], v[196:199], v[34:37]
	v_mfma_f32_16x16x32_bf16 v[26:29], v[156:159], v[200:203], v[26:29]
	v_mfma_f32_16x16x32_bf16 v[26:29], v[160:163], v[204:207], v[26:29]
	v_mfma_f32_16x16x32_bf16 v[18:21], v[164:167], v[200:203], v[18:21]
	v_mfma_f32_16x16x32_bf16 v[18:21], v[180:183], v[204:207], v[18:21]
	v_mfma_f32_16x16x32_bf16 v[10:13], v[156:159], v[208:211], v[10:13]
	v_mfma_f32_16x16x32_bf16 v[10:13], v[160:163], v[212:215], v[10:13]
	v_mfma_f32_16x16x32_bf16 v[2:5], v[164:167], v[208:211], v[2:5]
	v_mfma_f32_16x16x32_bf16 v[2:5], v[180:183], v[212:215], v[2:5]
	s_setprio 0
	s_barrier
	s_add_i32 s52, s52, 2
	s_addk_i32 s8, 0x100
	s_addk_i32 s9, 0x100
	s_cmp_ge_i32 s52, s21
	s_cbranch_scc0 .LBB0_892
	s_and_b64 vcc, exec, s[48:49]
	s_cbranch_vccz .LBB0_895

.LBB0_1020:
	v_add_u32_e32 v142, 0x10000, v162
	v_add_u32_e32 v150, 0x14000, v162
	ds_read_b128 v[130:133], v142
	ds_read_b128 v[134:137], v142 offset:1024
	ds_read_b128 v[138:141], v142 offset:2048
	ds_read_b128 v[142:145], v142 offset:3072
	ds_read_b128 v[154:157], v150
	ds_read_b128 v[164:167], v150 offset:1024
	ds_read_b128 v[168:171], v150 offset:2048
	ds_read_b128 v[172:175], v150 offset:3072
	s_add_i32 s90, s6, 0x100
	s_add_i32 s7, s88, s6
	s_cmp_eq_u32 s81, s89
	s_cselect_b32 s91, 0, s90
	s_cselect_b32 s93, s87, s7
	s_add_i32 s91, s91, s70
	s_or_b32 s92, s91, 0x80
	s_add_i32 s6, s3, s6
	s_mov_b32 m0, s82
	s_add_i32 s7, s6, 0x20080
	ds_read_b128 v[176:179], v163
	ds_read_b128 v[180:183], v163 offset:1024
	ds_read_b128 v[184:187], v163 offset:2048
	ds_read_b128 v[188:191], v163 offset:3072
	ds_read_b128 v[192:195], v163 offset:4096
	ds_read_b128 v[196:199], v163 offset:5120
	ds_read_b128 v[200:203], v163 offset:6144
	ds_read_b128 v[204:207], v163 offset:7168
	buffer_load_dwordx4 v161, s[12:15], s7 offen lds
	s_add_i32 s6, s6, 0x30080
	s_mov_b32 m0, s83
	s_nop 0
	buffer_load_dwordx4 v161, s[12:15], s6 offen lds
	s_waitcnt vmcnt(8)
	s_waitcnt lgkmcnt(0)
	s_setprio 1
	v_mfma_f32_16x16x32_bf16 v[126:129], v[130:133], v[176:179], v[126:129]
	s_barrier
	v_mfma_f32_16x16x32_bf16 v[126:129], v[134:137], v[180:183], v[126:129]
	v_mfma_f32_16x16x32_bf16 v[122:125], v[138:141], v[176:179], v[122:125]
	v_mfma_f32_16x16x32_bf16 v[122:125], v[142:145], v[180:183], v[122:125]
	v_mfma_f32_16x16x32_bf16 v[110:113], v[130:133], v[184:187], v[110:113]
	v_mfma_f32_16x16x32_bf16 v[110:113], v[134:137], v[188:191], v[110:113]
	v_mfma_f32_16x16x32_bf16 v[106:109], v[138:141], v[184:187], v[106:109]
	v_mfma_f32_16x16x32_bf16 v[106:109], v[142:145], v[188:191], v[106:109]
	v_mfma_f32_16x16x32_bf16 v[94:97], v[130:133], v[192:195], v[94:97]
	v_mfma_f32_16x16x32_bf16 v[94:97], v[134:137], v[196:199], v[94:97]
	v_mfma_f32_16x16x32_bf16 v[90:93], v[138:141], v[192:195], v[90:93]
	v_mfma_f32_16x16x32_bf16 v[90:93], v[142:145], v[196:199], v[90:93]
	v_mfma_f32_16x16x32_bf16 v[78:81], v[130:133], v[200:203], v[78:81]
	v_mfma_f32_16x16x32_bf16 v[78:81], v[134:137], v[204:207], v[78:81]
	v_mfma_f32_16x16x32_bf16 v[74:77], v[138:141], v[200:203], v[74:77]
	v_mfma_f32_16x16x32_bf16 v[74:77], v[142:145], v[204:207], v[74:77]
	v_mfma_f32_16x16x32_bf16 v[118:121], v[154:157], v[176:179], v[118:121]
	v_mfma_f32_16x16x32_bf16 v[118:121], v[164:167], v[180:183], v[118:121]
	v_mfma_f32_16x16x32_bf16 v[114:117], v[168:171], v[176:179], v[114:117]
	v_mfma_f32_16x16x32_bf16 v[114:117], v[172:175], v[180:183], v[114:117]
	v_mfma_f32_16x16x32_bf16 v[102:105], v[154:157], v[184:187], v[102:105]
	v_mfma_f32_16x16x32_bf16 v[102:105], v[164:167], v[188:191], v[102:105]
	v_mfma_f32_16x16x32_bf16 v[98:101], v[168:171], v[184:187], v[98:101]
	v_mfma_f32_16x16x32_bf16 v[98:101], v[172:175], v[188:191], v[98:101]
	v_mfma_f32_16x16x32_bf16 v[86:89], v[154:157], v[192:195], v[86:89]
	v_mfma_f32_16x16x32_bf16 v[86:89], v[164:167], v[196:199], v[86:89]
	v_mfma_f32_16x16x32_bf16 v[82:85], v[168:171], v[192:195], v[82:85]
	v_mfma_f32_16x16x32_bf16 v[82:85], v[172:175], v[196:199], v[82:85]
	v_mfma_f32_16x16x32_bf16 v[70:73], v[154:157], v[200:203], v[70:73]
	v_mfma_f32_16x16x32_bf16 v[70:73], v[164:167], v[204:207], v[70:73]
	v_mfma_f32_16x16x32_bf16 v[66:69], v[168:171], v[200:203], v[66:69]
	v_mfma_f32_16x16x32_bf16 v[66:69], v[172:175], v[204:207], v[66:69]
	s_setprio 0
	s_barrier
	s_mov_b32 m0, s66
	s_mov_b32 s6, s14
	s_mov_b32 s7, s15
	ds_read_b128 v[176:179], v163 offset:16384
	ds_read_b128 v[180:183], v163 offset:17408
	ds_read_b128 v[184:187], v163 offset:18432
	ds_read_b128 v[188:191], v163 offset:19456
	ds_read_b128 v[192:195], v163 offset:20480
	ds_read_b128 v[196:199], v163 offset:21504
	ds_read_b128 v[200:203], v163 offset:22528
	ds_read_b128 v[204:207], v163 offset:23552
	buffer_load_dwordx4 v160, s[4:7], s93 offen lds
	s_add_i32 s94, s93, 0x10000
	s_mov_b32 m0, s67
	s_nop 0
	buffer_load_dwordx4 v160, s[4:7], s94 offen lds
	s_add_i32 s94, s93, 0x20000
	s_mov_b32 m0, s68
	s_nop 0
	buffer_load_dwordx4 v160, s[4:7], s94 offen lds
	s_add_i32 s94, s93, 0x30000
	s_mov_b32 m0, s69
	s_nop 0
	buffer_load_dwordx4 v160, s[4:7], s94 offen lds
	s_mov_b32 m0, s65
	s_add_i32 s94, s91, 0x10000
	buffer_load_dwordx4 v161, s[12:15], s91 offen lds
	s_mov_b32 m0, s71
	s_nop 0
	buffer_load_dwordx4 v161, s[12:15], s94 offen lds
	s_waitcnt vmcnt(8)
	s_waitcnt lgkmcnt(0)
	s_setprio 1
	v_mfma_f32_16x16x32_bf16 v[62:65], v[130:133], v[176:179], v[62:65]
	s_barrier
	v_mfma_f32_16x16x32_bf16 v[62:65], v[134:137], v[180:183], v[62:65]
	v_mfma_f32_16x16x32_bf16 v[58:61], v[138:141], v[176:179], v[58:61]
	v_mfma_f32_16x16x32_bf16 v[58:61], v[142:145], v[180:183], v[58:61]
	v_mfma_f32_16x16x32_bf16 v[46:49], v[130:133], v[184:187], v[46:49]
	v_mfma_f32_16x16x32_bf16 v[46:49], v[134:137], v[188:191], v[46:49]
	v_mfma_f32_16x16x32_bf16 v[42:45], v[138:141], v[184:187], v[42:45]
	v_mfma_f32_16x16x32_bf16 v[42:45], v[142:145], v[188:191], v[42:45]
	v_mfma_f32_16x16x32_bf16 v[30:33], v[130:133], v[192:195], v[30:33]
	v_mfma_f32_16x16x32_bf16 v[30:33], v[134:137], v[196:199], v[30:33]
	v_mfma_f32_16x16x32_bf16 v[26:29], v[138:141], v[192:195], v[26:29]
	v_mfma_f32_16x16x32_bf16 v[26:29], v[142:145], v[196:199], v[26:29]
	v_mfma_f32_16x16x32_bf16 v[14:17], v[130:133], v[200:203], v[14:17]
	v_mfma_f32_16x16x32_bf16 v[14:17], v[134:137], v[204:207], v[14:17]
	v_mfma_f32_16x16x32_bf16 v[10:13], v[138:141], v[200:203], v[10:13]
	v_mfma_f32_16x16x32_bf16 v[10:13], v[142:145], v[204:207], v[10:13]
	v_mfma_f32_16x16x32_bf16 v[54:57], v[154:157], v[176:179], v[54:57]
	v_mfma_f32_16x16x32_bf16 v[54:57], v[164:167], v[180:183], v[54:57]
	v_mfma_f32_16x16x32_bf16 v[50:53], v[168:171], v[176:179], v[50:53]
	v_mfma_f32_16x16x32_bf16 v[50:53], v[172:175], v[180:183], v[50:53]
	v_mfma_f32_16x16x32_bf16 v[38:41], v[154:157], v[184:187], v[38:41]
	v_mfma_f32_16x16x32_bf16 v[38:41], v[164:167], v[188:191], v[38:41]
	v_mfma_f32_16x16x32_bf16 v[34:37], v[168:171], v[184:187], v[34:37]
	v_mfma_f32_16x16x32_bf16 v[34:37], v[172:175], v[188:191], v[34:37]
	v_mfma_f32_16x16x32_bf16 v[22:25], v[154:157], v[192:195], v[22:25]
	v_mfma_f32_16x16x32_bf16 v[22:25], v[164:167], v[196:199], v[22:25]
	v_mfma_f32_16x16x32_bf16 v[18:21], v[168:171], v[192:195], v[18:21]
	v_mfma_f32_16x16x32_bf16 v[18:21], v[172:175], v[196:199], v[18:21]
	v_mfma_f32_16x16x32_bf16 v[6:9], v[154:157], v[200:203], v[6:9]
	v_mfma_f32_16x16x32_bf16 v[6:9], v[164:167], v[204:207], v[6:9]
	v_mfma_f32_16x16x32_bf16 v[2:5], v[168:171], v[200:203], v[2:5]
	v_mfma_f32_16x16x32_bf16 v[2:5], v[172:175], v[204:207], v[2:5]
	s_setprio 0
	s_barrier
	v_add_u32_e32 v142, 0x18000, v162
	v_add_u32_e32 v150, 0x1c000, v162
	ds_read_b128 v[130:133], v142
	ds_read_b128 v[134:137], v142 offset:1024
	ds_read_b128 v[138:141], v142 offset:2048
	ds_read_b128 v[142:145], v142 offset:3072
	ds_read_b128 v[154:157], v150
	ds_read_b128 v[164:167], v150 offset:1024
	ds_read_b128 v[168:171], v150 offset:2048
	ds_read_b128 v[172:175], v150 offset:3072
	s_mov_b32 m0, s72
	s_add_i32 s94, s91, 0x20000
	ds_read_b128 v[176:179], v163 offset:32768
	ds_read_b128 v[180:183], v163 offset:33792
	ds_read_b128 v[184:187], v163 offset:34816
	ds_read_b128 v[188:191], v163 offset:35840
	ds_read_b128 v[192:195], v163 offset:36864
	ds_read_b128 v[196:199], v163 offset:37888
	ds_read_b128 v[200:203], v163 offset:38912
	ds_read_b128 v[204:207], v163 offset:39936
	buffer_load_dwordx4 v161, s[12:15], s94 offen lds
	s_add_i32 s94, s91, 0x30000
	s_mov_b32 m0, s73
	s_nop 0
	buffer_load_dwordx4 v161, s[12:15], s94 offen lds
	s_waitcnt vmcnt(8)
	s_waitcnt lgkmcnt(0)
	s_setprio 1
	v_mfma_f32_16x16x32_bf16 v[126:129], v[130:133], v[176:179], v[126:129]
	s_barrier
	v_mfma_f32_16x16x32_bf16 v[126:129], v[134:137], v[180:183], v[126:129]
	v_mfma_f32_16x16x32_bf16 v[122:125], v[138:141], v[176:179], v[122:125]
	v_mfma_f32_16x16x32_bf16 v[122:125], v[142:145], v[180:183], v[122:125]
	v_mfma_f32_16x16x32_bf16 v[110:113], v[130:133], v[184:187], v[110:113]
	v_mfma_f32_16x16x32_bf16 v[110:113], v[134:137], v[188:191], v[110:113]
	v_mfma_f32_16x16x32_bf16 v[106:109], v[138:141], v[184:187], v[106:109]
	v_mfma_f32_16x16x32_bf16 v[106:109], v[142:145], v[188:191], v[106:109]
	v_mfma_f32_16x16x32_bf16 v[94:97], v[130:133], v[192:195], v[94:97]
	v_mfma_f32_16x16x32_bf16 v[94:97], v[134:137], v[196:199], v[94:97]
	v_mfma_f32_16x16x32_bf16 v[90:93], v[138:141], v[192:195], v[90:93]
	v_mfma_f32_16x16x32_bf16 v[90:93], v[142:145], v[196:199], v[90:93]
	v_mfma_f32_16x16x32_bf16 v[78:81], v[130:133], v[200:203], v[78:81]
	v_mfma_f32_16x16x32_bf16 v[78:81], v[134:137], v[204:207], v[78:81]
	v_mfma_f32_16x16x32_bf16 v[74:77], v[138:141], v[200:203], v[74:77]
	v_mfma_f32_16x16x32_bf16 v[74:77], v[142:145], v[204:207], v[74:77]
	v_mfma_f32_16x16x32_bf16 v[118:121], v[154:157], v[176:179], v[118:121]
	v_mfma_f32_16x16x32_bf16 v[118:121], v[164:167], v[180:183], v[118:121]
	v_mfma_f32_16x16x32_bf16 v[114:117], v[168:171], v[176:179], v[114:117]
	v_mfma_f32_16x16x32_bf16 v[114:117], v[172:175], v[180:183], v[114:117]
	v_mfma_f32_16x16x32_bf16 v[102:105], v[154:157], v[184:187], v[102:105]
	v_mfma_f32_16x16x32_bf16 v[102:105], v[164:167], v[188:191], v[102:105]
	v_mfma_f32_16x16x32_bf16 v[98:101], v[168:171], v[184:187], v[98:101]
	v_mfma_f32_16x16x32_bf16 v[98:101], v[172:175], v[188:191], v[98:101]
	v_mfma_f32_16x16x32_bf16 v[86:89], v[154:157], v[192:195], v[86:89]
	v_mfma_f32_16x16x32_bf16 v[86:89], v[164:167], v[196:199], v[86:89]
	v_mfma_f32_16x16x32_bf16 v[82:85], v[168:171], v[192:195], v[82:85]
	v_mfma_f32_16x16x32_bf16 v[82:85], v[172:175], v[196:199], v[82:85]
	v_mfma_f32_16x16x32_bf16 v[70:73], v[154:157], v[200:203], v[70:73]
	v_mfma_f32_16x16x32_bf16 v[70:73], v[164:167], v[204:207], v[70:73]
	v_mfma_f32_16x16x32_bf16 v[66:69], v[168:171], v[200:203], v[66:69]
	v_mfma_f32_16x16x32_bf16 v[66:69], v[172:175], v[204:207], v[66:69]
	s_setprio 0
	s_barrier
	s_mov_b32 m0, s74
	s_or_b32 s94, s93, 0x80
	ds_read_b128 v[176:179], v163 offset:49152
	ds_read_b128 v[180:183], v163 offset:50176
	ds_read_b128 v[184:187], v163 offset:51200
	ds_read_b128 v[188:191], v163 offset:52224
	ds_read_b128 v[192:195], v163 offset:53248
	ds_read_b128 v[196:199], v163 offset:54272
	ds_read_b128 v[200:203], v163 offset:55296
	ds_read_b128 v[204:207], v163 offset:56320
	buffer_load_dwordx4 v160, s[4:7], s94 offen lds
	s_add_i32 s94, s93, 0x10080
	s_mov_b32 m0, s75
	s_add_i32 s91, s91, 0x10080
	buffer_load_dwordx4 v160, s[4:7], s94 offen lds
	s_add_i32 s94, s93, 0x20080
	s_mov_b32 m0, s78
	s_add_i32 s93, s93, 0x30080
	buffer_load_dwordx4 v160, s[4:7], s94 offen lds
	s_mov_b32 m0, s79
	s_nop 0
	buffer_load_dwordx4 v160, s[4:7], s93 offen lds
	s_mov_b32 m0, s76
	s_nop 0
	buffer_load_dwordx4 v161, s[12:15], s92 offen lds
	s_mov_b32 m0, s77
	s_nop 0
	buffer_load_dwordx4 v161, s[12:15], s91 offen lds
	s_waitcnt vmcnt(8)
	s_waitcnt lgkmcnt(0)
	s_setprio 1
	v_mfma_f32_16x16x32_bf16 v[62:65], v[130:133], v[176:179], v[62:65]
	s_barrier
	v_mfma_f32_16x16x32_bf16 v[62:65], v[134:137], v[180:183], v[62:65]
	v_mfma_f32_16x16x32_bf16 v[58:61], v[138:141], v[176:179], v[58:61]
	v_mfma_f32_16x16x32_bf16 v[58:61], v[142:145], v[180:183], v[58:61]
	v_mfma_f32_16x16x32_bf16 v[46:49], v[130:133], v[184:187], v[46:49]
	v_mfma_f32_16x16x32_bf16 v[46:49], v[134:137], v[188:191], v[46:49]
	v_mfma_f32_16x16x32_bf16 v[42:45], v[138:141], v[184:187], v[42:45]
	v_mfma_f32_16x16x32_bf16 v[42:45], v[142:145], v[188:191], v[42:45]
	v_mfma_f32_16x16x32_bf16 v[30:33], v[130:133], v[192:195], v[30:33]
	v_mfma_f32_16x16x32_bf16 v[30:33], v[134:137], v[196:199], v[30:33]
	v_mfma_f32_16x16x32_bf16 v[26:29], v[138:141], v[192:195], v[26:29]
	v_mfma_f32_16x16x32_bf16 v[26:29], v[142:145], v[196:199], v[26:29]
	v_mfma_f32_16x16x32_bf16 v[14:17], v[130:133], v[200:203], v[14:17]
	v_mfma_f32_16x16x32_bf16 v[14:17], v[134:137], v[204:207], v[14:17]
	v_mfma_f32_16x16x32_bf16 v[10:13], v[138:141], v[200:203], v[10:13]
	v_mfma_f32_16x16x32_bf16 v[10:13], v[142:145], v[204:207], v[10:13]
	v_mfma_f32_16x16x32_bf16 v[54:57], v[154:157], v[176:179], v[54:57]
	v_mfma_f32_16x16x32_bf16 v[54:57], v[164:167], v[180:183], v[54:57]
	v_mfma_f32_16x16x32_bf16 v[50:53], v[168:171], v[176:179], v[50:53]
	v_mfma_f32_16x16x32_bf16 v[50:53], v[172:175], v[180:183], v[50:53]
	v_mfma_f32_16x16x32_bf16 v[38:41], v[154:157], v[184:187], v[38:41]
	v_mfma_f32_16x16x32_bf16 v[38:41], v[164:167], v[188:191], v[38:41]
	v_mfma_f32_16x16x32_bf16 v[34:37], v[168:171], v[184:187], v[34:37]
	v_mfma_f32_16x16x32_bf16 v[34:37], v[172:175], v[188:191], v[34:37]
	v_mfma_f32_16x16x32_bf16 v[22:25], v[154:157], v[192:195], v[22:25]
	v_mfma_f32_16x16x32_bf16 v[22:25], v[164:167], v[196:199], v[22:25]
	v_mfma_f32_16x16x32_bf16 v[18:21], v[168:171], v[192:195], v[18:21]
	v_mfma_f32_16x16x32_bf16 v[18:21], v[172:175], v[196:199], v[18:21]
	v_mfma_f32_16x16x32_bf16 v[6:9], v[154:157], v[200:203], v[6:9]
	v_mfma_f32_16x16x32_bf16 v[6:9], v[164:167], v[204:207], v[6:9]
	v_mfma_f32_16x16x32_bf16 v[2:5], v[168:171], v[200:203], v[2:5]
	v_mfma_f32_16x16x32_bf16 v[2:5], v[172:175], v[204:207], v[2:5]
	s_setprio 0
	s_barrier
	s_add_i32 s89, s89, 2
	s_cmp_ge_i32 s89, s63
	s_mov_b32 s6, s90
	s_cbranch_scc0 .LBB0_1020
	s_and_b64 vcc, exec, s[54:55]
	s_cbranch_vccz .LBB0_1023

.LBB0_1035:
	ds_read_b128 v[140:143], v134
	ds_read_b128 v[148:151], v134 offset:1024
	ds_read_b128 v[152:155], v134 offset:2048
	ds_read_b128 v[156:159], v134 offset:3072
	ds_read_b128 v[160:163], v135
	ds_read_b128 v[164:167], v135 offset:1024
	ds_read_b128 v[168:171], v135 offset:2048
	ds_read_b128 v[172:175], v135 offset:3072
	s_add_i32 s73, s70, 0xfffb8080
	s_cmp_eq_u32 s53, s72
	s_cselect_b32 s73, s68, s73
	s_cselect_b32 s75, s69, s71
	s_add_i32 s74, s73, 0x80
	s_add_i32 s76, s70, 0xfffe8000
	s_mov_b32 m0, s54
	ds_read_b128 v[176:179], v136
	ds_read_b128 v[180:183], v136 offset:1024
	ds_read_b128 v[184:187], v136 offset:2048
	ds_read_b128 v[188:191], v136 offset:3072
	ds_read_b128 v[192:195], v136 offset:4096
	ds_read_b128 v[196:199], v136 offset:5120
	ds_read_b128 v[200:203], v136 offset:6144
	ds_read_b128 v[204:207], v136 offset:7168
	buffer_load_dwordx4 v132, s[12:15], s76 offen lds
	s_mov_b32 m0, s55
	s_nop 0
	buffer_load_dwordx4 v132, s[12:15], s70 offen lds
	s_waitcnt vmcnt(8)
	s_waitcnt lgkmcnt(0)
	s_setprio 1
	v_mfma_f32_16x16x32_bf16 v[126:129], v[140:143], v[176:179], v[126:129]
	s_barrier
	v_mfma_f32_16x16x32_bf16 v[126:129], v[148:151], v[180:183], v[126:129]
	v_mfma_f32_16x16x32_bf16 v[122:125], v[152:155], v[176:179], v[122:125]
	v_mfma_f32_16x16x32_bf16 v[122:125], v[156:159], v[180:183], v[122:125]
	v_mfma_f32_16x16x32_bf16 v[110:113], v[140:143], v[184:187], v[110:113]
	v_mfma_f32_16x16x32_bf16 v[110:113], v[148:151], v[188:191], v[110:113]
	v_mfma_f32_16x16x32_bf16 v[106:109], v[152:155], v[184:187], v[106:109]
	v_mfma_f32_16x16x32_bf16 v[106:109], v[156:159], v[188:191], v[106:109]
	v_mfma_f32_16x16x32_bf16 v[94:97], v[140:143], v[192:195], v[94:97]
	v_mfma_f32_16x16x32_bf16 v[94:97], v[148:151], v[196:199], v[94:97]
	v_mfma_f32_16x16x32_bf16 v[90:93], v[152:155], v[192:195], v[90:93]
	v_mfma_f32_16x16x32_bf16 v[90:93], v[156:159], v[196:199], v[90:93]
	v_mfma_f32_16x16x32_bf16 v[78:81], v[140:143], v[200:203], v[78:81]
	v_mfma_f32_16x16x32_bf16 v[78:81], v[148:151], v[204:207], v[78:81]
	v_mfma_f32_16x16x32_bf16 v[74:77], v[152:155], v[200:203], v[74:77]
	v_mfma_f32_16x16x32_bf16 v[74:77], v[156:159], v[204:207], v[74:77]
	v_mfma_f32_16x16x32_bf16 v[118:121], v[160:163], v[176:179], v[118:121]
	v_mfma_f32_16x16x32_bf16 v[118:121], v[164:167], v[180:183], v[118:121]
	v_mfma_f32_16x16x32_bf16 v[114:117], v[168:171], v[176:179], v[114:117]
	v_mfma_f32_16x16x32_bf16 v[114:117], v[172:175], v[180:183], v[114:117]
	v_mfma_f32_16x16x32_bf16 v[102:105], v[160:163], v[184:187], v[102:105]
	v_mfma_f32_16x16x32_bf16 v[102:105], v[164:167], v[188:191], v[102:105]
	v_mfma_f32_16x16x32_bf16 v[98:101], v[168:171], v[184:187], v[98:101]
	v_mfma_f32_16x16x32_bf16 v[98:101], v[172:175], v[188:191], v[98:101]
	v_mfma_f32_16x16x32_bf16 v[86:89], v[160:163], v[192:195], v[86:89]
	v_mfma_f32_16x16x32_bf16 v[86:89], v[164:167], v[196:199], v[86:89]
	v_mfma_f32_16x16x32_bf16 v[82:85], v[168:171], v[192:195], v[82:85]
	v_mfma_f32_16x16x32_bf16 v[82:85], v[172:175], v[196:199], v[82:85]
	v_mfma_f32_16x16x32_bf16 v[70:73], v[160:163], v[200:203], v[70:73]
	v_mfma_f32_16x16x32_bf16 v[70:73], v[164:167], v[204:207], v[70:73]
	v_mfma_f32_16x16x32_bf16 v[66:69], v[168:171], v[200:203], v[66:69]
	v_mfma_f32_16x16x32_bf16 v[66:69], v[172:175], v[204:207], v[66:69]
	s_setprio 0
	s_barrier
	s_mov_b32 m0, s30
	ds_read_b128 v[176:179], v136 offset:16384
	ds_read_b128 v[180:183], v136 offset:17408
	ds_read_b128 v[184:187], v136 offset:18432
	ds_read_b128 v[188:191], v136 offset:19456
	ds_read_b128 v[192:195], v136 offset:20480
	ds_read_b128 v[196:199], v136 offset:21504
	ds_read_b128 v[200:203], v136 offset:22528
	ds_read_b128 v[204:207], v136 offset:23552
	buffer_load_dwordx4 v133, s[16:19], s75 offen lds
	s_add_i32 s76, s75, 0x200000
	s_mov_b32 m0, s31
	s_nop 0
	buffer_load_dwordx4 v133, s[16:19], s76 offen lds
	s_add_i32 s76, s75, 0x400000
	s_mov_b32 m0, s35
	s_nop 0
	buffer_load_dwordx4 v133, s[16:19], s76 offen lds
	s_add_i32 s76, s75, 0x600000
	s_mov_b32 m0, s42
	s_nop 0
	buffer_load_dwordx4 v133, s[16:19], s76 offen lds
	s_mov_b32 m0, s27
	s_add_i32 s76, s73, 0x18000
	buffer_load_dwordx4 v132, s[12:15], s73 offen lds
	s_mov_b32 m0, s43
	s_nop 0
	buffer_load_dwordx4 v132, s[12:15], s76 offen lds
	s_waitcnt vmcnt(8)
	s_waitcnt lgkmcnt(0)
	s_setprio 1
	v_mfma_f32_16x16x32_bf16 v[62:65], v[140:143], v[176:179], v[62:65]
	s_barrier
	v_mfma_f32_16x16x32_bf16 v[62:65], v[148:151], v[180:183], v[62:65]
	v_mfma_f32_16x16x32_bf16 v[58:61], v[152:155], v[176:179], v[58:61]
	v_mfma_f32_16x16x32_bf16 v[58:61], v[156:159], v[180:183], v[58:61]
	v_mfma_f32_16x16x32_bf16 v[46:49], v[140:143], v[184:187], v[46:49]
	v_mfma_f32_16x16x32_bf16 v[46:49], v[148:151], v[188:191], v[46:49]
	v_mfma_f32_16x16x32_bf16 v[42:45], v[152:155], v[184:187], v[42:45]
	v_mfma_f32_16x16x32_bf16 v[42:45], v[156:159], v[188:191], v[42:45]
	v_mfma_f32_16x16x32_bf16 v[30:33], v[140:143], v[192:195], v[30:33]
	v_mfma_f32_16x16x32_bf16 v[30:33], v[148:151], v[196:199], v[30:33]
	v_mfma_f32_16x16x32_bf16 v[26:29], v[152:155], v[192:195], v[26:29]
	v_mfma_f32_16x16x32_bf16 v[26:29], v[156:159], v[196:199], v[26:29]
	v_mfma_f32_16x16x32_bf16 v[14:17], v[140:143], v[200:203], v[14:17]
	v_mfma_f32_16x16x32_bf16 v[14:17], v[148:151], v[204:207], v[14:17]
	v_mfma_f32_16x16x32_bf16 v[10:13], v[152:155], v[200:203], v[10:13]
	v_mfma_f32_16x16x32_bf16 v[10:13], v[156:159], v[204:207], v[10:13]
	v_mfma_f32_16x16x32_bf16 v[54:57], v[160:163], v[176:179], v[54:57]
	v_mfma_f32_16x16x32_bf16 v[54:57], v[164:167], v[180:183], v[54:57]
	v_mfma_f32_16x16x32_bf16 v[50:53], v[168:171], v[176:179], v[50:53]
	v_mfma_f32_16x16x32_bf16 v[50:53], v[172:175], v[180:183], v[50:53]
	v_mfma_f32_16x16x32_bf16 v[38:41], v[160:163], v[184:187], v[38:41]
	v_mfma_f32_16x16x32_bf16 v[38:41], v[164:167], v[188:191], v[38:41]
	v_mfma_f32_16x16x32_bf16 v[34:37], v[168:171], v[184:187], v[34:37]
	v_mfma_f32_16x16x32_bf16 v[34:37], v[172:175], v[188:191], v[34:37]
	v_mfma_f32_16x16x32_bf16 v[22:25], v[160:163], v[192:195], v[22:25]
	v_mfma_f32_16x16x32_bf16 v[22:25], v[164:167], v[196:199], v[22:25]
	v_mfma_f32_16x16x32_bf16 v[18:21], v[168:171], v[192:195], v[18:21]
	v_mfma_f32_16x16x32_bf16 v[18:21], v[172:175], v[196:199], v[18:21]
	v_mfma_f32_16x16x32_bf16 v[6:9], v[160:163], v[200:203], v[6:9]
	v_mfma_f32_16x16x32_bf16 v[6:9], v[164:167], v[204:207], v[6:9]
	v_mfma_f32_16x16x32_bf16 v[2:5], v[168:171], v[200:203], v[2:5]
	v_mfma_f32_16x16x32_bf16 v[2:5], v[172:175], v[204:207], v[2:5]
	s_setprio 0
	s_barrier
	ds_read_b128 v[140:143], v137
	ds_read_b128 v[148:151], v137 offset:1024
	ds_read_b128 v[152:155], v137 offset:2048
	ds_read_b128 v[156:159], v137 offset:3072
	ds_read_b128 v[160:163], v138
	ds_read_b128 v[164:167], v138 offset:1024
	ds_read_b128 v[168:171], v138 offset:2048
	ds_read_b128 v[172:175], v138 offset:3072
	s_mov_b32 m0, s44
	s_add_i32 s76, s73, 0x30000
	ds_read_b128 v[176:179], v136 offset:32768
	ds_read_b128 v[180:183], v136 offset:33792
	ds_read_b128 v[184:187], v136 offset:34816
	ds_read_b128 v[188:191], v136 offset:35840
	ds_read_b128 v[192:195], v136 offset:36864
	ds_read_b128 v[196:199], v136 offset:37888
	ds_read_b128 v[200:203], v136 offset:38912
	ds_read_b128 v[204:207], v136 offset:39936
	buffer_load_dwordx4 v132, s[12:15], s76 offen lds
	s_add_i32 s76, s73, 0x48000
	s_mov_b32 m0, s45
	s_nop 0
	buffer_load_dwordx4 v132, s[12:15], s76 offen lds
	s_waitcnt vmcnt(8)
	s_waitcnt lgkmcnt(0)
	s_setprio 1
	v_mfma_f32_16x16x32_bf16 v[126:129], v[140:143], v[176:179], v[126:129]
	s_barrier
	v_mfma_f32_16x16x32_bf16 v[126:129], v[148:151], v[180:183], v[126:129]
	v_mfma_f32_16x16x32_bf16 v[122:125], v[152:155], v[176:179], v[122:125]
	v_mfma_f32_16x16x32_bf16 v[122:125], v[156:159], v[180:183], v[122:125]
	v_mfma_f32_16x16x32_bf16 v[110:113], v[140:143], v[184:187], v[110:113]
	v_mfma_f32_16x16x32_bf16 v[110:113], v[148:151], v[188:191], v[110:113]
	v_mfma_f32_16x16x32_bf16 v[106:109], v[152:155], v[184:187], v[106:109]
	v_mfma_f32_16x16x32_bf16 v[106:109], v[156:159], v[188:191], v[106:109]
	v_mfma_f32_16x16x32_bf16 v[94:97], v[140:143], v[192:195], v[94:97]
	v_mfma_f32_16x16x32_bf16 v[94:97], v[148:151], v[196:199], v[94:97]
	v_mfma_f32_16x16x32_bf16 v[90:93], v[152:155], v[192:195], v[90:93]
	v_mfma_f32_16x16x32_bf16 v[90:93], v[156:159], v[196:199], v[90:93]
	v_mfma_f32_16x16x32_bf16 v[78:81], v[140:143], v[200:203], v[78:81]
	v_mfma_f32_16x16x32_bf16 v[78:81], v[148:151], v[204:207], v[78:81]
	v_mfma_f32_16x16x32_bf16 v[74:77], v[152:155], v[200:203], v[74:77]
	v_mfma_f32_16x16x32_bf16 v[74:77], v[156:159], v[204:207], v[74:77]
	v_mfma_f32_16x16x32_bf16 v[118:121], v[160:163], v[176:179], v[118:121]
	v_mfma_f32_16x16x32_bf16 v[118:121], v[164:167], v[180:183], v[118:121]
	v_mfma_f32_16x16x32_bf16 v[114:117], v[168:171], v[176:179], v[114:117]
	v_mfma_f32_16x16x32_bf16 v[114:117], v[172:175], v[180:183], v[114:117]
	v_mfma_f32_16x16x32_bf16 v[102:105], v[160:163], v[184:187], v[102:105]
	v_mfma_f32_16x16x32_bf16 v[102:105], v[164:167], v[188:191], v[102:105]
	v_mfma_f32_16x16x32_bf16 v[98:101], v[168:171], v[184:187], v[98:101]
	v_mfma_f32_16x16x32_bf16 v[98:101], v[172:175], v[188:191], v[98:101]
	v_mfma_f32_16x16x32_bf16 v[86:89], v[160:163], v[192:195], v[86:89]
	v_mfma_f32_16x16x32_bf16 v[86:89], v[164:167], v[196:199], v[86:89]
	v_mfma_f32_16x16x32_bf16 v[82:85], v[168:171], v[192:195], v[82:85]
	v_mfma_f32_16x16x32_bf16 v[82:85], v[172:175], v[196:199], v[82:85]
	v_mfma_f32_16x16x32_bf16 v[70:73], v[160:163], v[200:203], v[70:73]
	v_mfma_f32_16x16x32_bf16 v[70:73], v[164:167], v[204:207], v[70:73]
	v_mfma_f32_16x16x32_bf16 v[66:69], v[168:171], v[200:203], v[66:69]
	v_mfma_f32_16x16x32_bf16 v[66:69], v[172:175], v[204:207], v[66:69]
	s_setprio 0
	s_barrier
	s_mov_b32 m0, s46
	s_add_i32 s76, s75, 0x80
	ds_read_b128 v[176:179], v136 offset:49152
	ds_read_b128 v[180:183], v136 offset:50176
	ds_read_b128 v[184:187], v136 offset:51200
	ds_read_b128 v[188:191], v136 offset:52224
	ds_read_b128 v[192:195], v136 offset:53248
	ds_read_b128 v[196:199], v136 offset:54272
	ds_read_b128 v[200:203], v136 offset:55296
	ds_read_b128 v[204:207], v136 offset:56320
	buffer_load_dwordx4 v133, s[16:19], s76 offen lds
	s_add_i32 s76, s75, 0x200080
	s_mov_b32 m0, s47
	s_add_i32 s73, s73, 0x18080
	buffer_load_dwordx4 v133, s[16:19], s76 offen lds
	s_add_i32 s76, s75, 0x400080
	s_mov_b32 m0, s50
	s_add_i32 s75, s75, 0x600080
	buffer_load_dwordx4 v133, s[16:19], s76 offen lds
	s_mov_b32 m0, s51
	s_nop 0
	buffer_load_dwordx4 v133, s[16:19], s75 offen lds
	s_mov_b32 m0, s48
	s_nop 0
	buffer_load_dwordx4 v132, s[12:15], s74 offen lds
	s_mov_b32 m0, s49
	s_nop 0
	buffer_load_dwordx4 v132, s[12:15], s73 offen lds
	s_waitcnt vmcnt(8)
	s_waitcnt lgkmcnt(0)
	s_setprio 1
	v_mfma_f32_16x16x32_bf16 v[62:65], v[140:143], v[176:179], v[62:65]
	s_barrier
	v_mfma_f32_16x16x32_bf16 v[62:65], v[148:151], v[180:183], v[62:65]
	v_mfma_f32_16x16x32_bf16 v[58:61], v[152:155], v[176:179], v[58:61]
	v_mfma_f32_16x16x32_bf16 v[58:61], v[156:159], v[180:183], v[58:61]
	v_mfma_f32_16x16x32_bf16 v[46:49], v[140:143], v[184:187], v[46:49]
	v_mfma_f32_16x16x32_bf16 v[46:49], v[148:151], v[188:191], v[46:49]
	v_mfma_f32_16x16x32_bf16 v[42:45], v[152:155], v[184:187], v[42:45]
	v_mfma_f32_16x16x32_bf16 v[42:45], v[156:159], v[188:191], v[42:45]
	v_mfma_f32_16x16x32_bf16 v[30:33], v[140:143], v[192:195], v[30:33]
	v_mfma_f32_16x16x32_bf16 v[30:33], v[148:151], v[196:199], v[30:33]
	v_mfma_f32_16x16x32_bf16 v[26:29], v[152:155], v[192:195], v[26:29]
	v_mfma_f32_16x16x32_bf16 v[26:29], v[156:159], v[196:199], v[26:29]
	v_mfma_f32_16x16x32_bf16 v[14:17], v[140:143], v[200:203], v[14:17]
	v_mfma_f32_16x16x32_bf16 v[14:17], v[148:151], v[204:207], v[14:17]
	v_mfma_f32_16x16x32_bf16 v[10:13], v[152:155], v[200:203], v[10:13]
	v_mfma_f32_16x16x32_bf16 v[10:13], v[156:159], v[204:207], v[10:13]
	v_mfma_f32_16x16x32_bf16 v[54:57], v[160:163], v[176:179], v[54:57]
	v_mfma_f32_16x16x32_bf16 v[54:57], v[164:167], v[180:183], v[54:57]
	v_mfma_f32_16x16x32_bf16 v[50:53], v[168:171], v[176:179], v[50:53]
	v_mfma_f32_16x16x32_bf16 v[50:53], v[172:175], v[180:183], v[50:53]
	v_mfma_f32_16x16x32_bf16 v[38:41], v[160:163], v[184:187], v[38:41]
	v_mfma_f32_16x16x32_bf16 v[38:41], v[164:167], v[188:191], v[38:41]
	v_mfma_f32_16x16x32_bf16 v[34:37], v[168:171], v[184:187], v[34:37]
	v_mfma_f32_16x16x32_bf16 v[34:37], v[172:175], v[188:191], v[34:37]
	v_mfma_f32_16x16x32_bf16 v[22:25], v[160:163], v[192:195], v[22:25]
	v_mfma_f32_16x16x32_bf16 v[22:25], v[164:167], v[196:199], v[22:25]
	v_mfma_f32_16x16x32_bf16 v[18:21], v[168:171], v[192:195], v[18:21]
	v_mfma_f32_16x16x32_bf16 v[18:21], v[172:175], v[196:199], v[18:21]
	v_mfma_f32_16x16x32_bf16 v[6:9], v[160:163], v[200:203], v[6:9]
	v_mfma_f32_16x16x32_bf16 v[6:9], v[164:167], v[204:207], v[6:9]
	v_mfma_f32_16x16x32_bf16 v[2:5], v[168:171], v[200:203], v[2:5]
	v_mfma_f32_16x16x32_bf16 v[2:5], v[172:175], v[204:207], v[2:5]
	s_setprio 0
	s_barrier
	s_add_i32 s72, s72, 2
	s_addk_i32 s70, 0x100
	s_addk_i32 s71, 0x100
	s_cmp_ge_i32 s72, s21
	s_cbranch_scc0 .LBB0_1035

.LBB0_1050:
	ds_read_b128 v[132:135], v142
	ds_read_b128 v[136:139], v142 offset:1024
	ds_read_b128 v[148:151], v142 offset:2048
	ds_read_b128 v[152:155], v142 offset:3072
	ds_read_b128 v[156:159], v143
	ds_read_b128 v[160:163], v143 offset:1024
	ds_read_b128 v[164:167], v143 offset:2048
	ds_read_b128 v[168:171], v143 offset:3072
	s_add_i32 s18, s61, 0xfff40080
	s_cmp_eq_u32 s54, s62
	s_cselect_b32 s64, s35, s18
	s_add_i32 s63, s64, 0x80
	s_add_i32 s18, s61, 0xfffc0000
	s_mov_b32 m0, s55
	ds_read_b128 v[172:175], v144
	ds_read_b128 v[176:179], v144 offset:1024
	ds_read_b128 v[180:183], v144 offset:2048
	ds_read_b128 v[184:187], v144 offset:3072
	ds_read_b128 v[188:191], v144 offset:4096
	ds_read_b128 v[192:195], v144 offset:5120
	ds_read_b128 v[196:199], v144 offset:6144
	ds_read_b128 v[200:203], v144 offset:7168
	buffer_load_dwordx4 v140, s[12:15], s18 offen lds
	s_mov_b32 m0, s56
	s_nop 0
	buffer_load_dwordx4 v140, s[12:15], s61 offen lds
	s_waitcnt vmcnt(8)
	s_waitcnt lgkmcnt(0)
	s_setprio 1
	v_mfma_f32_16x16x32_bf16 v[126:129], v[132:135], v[172:175], v[126:129]
	s_barrier
	v_mfma_f32_16x16x32_bf16 v[126:129], v[136:139], v[176:179], v[126:129]
	v_mfma_f32_16x16x32_bf16 v[122:125], v[148:151], v[172:175], v[122:125]
	v_mfma_f32_16x16x32_bf16 v[122:125], v[152:155], v[176:179], v[122:125]
	v_mfma_f32_16x16x32_bf16 v[110:113], v[132:135], v[180:183], v[110:113]
	v_mfma_f32_16x16x32_bf16 v[110:113], v[136:139], v[184:187], v[110:113]
	v_mfma_f32_16x16x32_bf16 v[106:109], v[148:151], v[180:183], v[106:109]
	v_mfma_f32_16x16x32_bf16 v[106:109], v[152:155], v[184:187], v[106:109]
	v_mfma_f32_16x16x32_bf16 v[94:97], v[132:135], v[188:191], v[94:97]
	v_mfma_f32_16x16x32_bf16 v[94:97], v[136:139], v[192:195], v[94:97]
	v_mfma_f32_16x16x32_bf16 v[90:93], v[148:151], v[188:191], v[90:93]
	v_mfma_f32_16x16x32_bf16 v[90:93], v[152:155], v[192:195], v[90:93]
	v_mfma_f32_16x16x32_bf16 v[78:81], v[132:135], v[196:199], v[78:81]
	v_mfma_f32_16x16x32_bf16 v[78:81], v[136:139], v[200:203], v[78:81]
	v_mfma_f32_16x16x32_bf16 v[74:77], v[148:151], v[196:199], v[74:77]
	v_mfma_f32_16x16x32_bf16 v[74:77], v[152:155], v[200:203], v[74:77]
	v_mfma_f32_16x16x32_bf16 v[118:121], v[156:159], v[172:175], v[118:121]
	v_mfma_f32_16x16x32_bf16 v[118:121], v[160:163], v[176:179], v[118:121]
	v_mfma_f32_16x16x32_bf16 v[114:117], v[164:167], v[172:175], v[114:117]
	v_mfma_f32_16x16x32_bf16 v[114:117], v[168:171], v[176:179], v[114:117]
	v_mfma_f32_16x16x32_bf16 v[102:105], v[156:159], v[180:183], v[102:105]
	v_mfma_f32_16x16x32_bf16 v[102:105], v[160:163], v[184:187], v[102:105]
	v_mfma_f32_16x16x32_bf16 v[98:101], v[164:167], v[180:183], v[98:101]
	v_mfma_f32_16x16x32_bf16 v[98:101], v[168:171], v[184:187], v[98:101]
	v_mfma_f32_16x16x32_bf16 v[86:89], v[156:159], v[188:191], v[86:89]
	v_mfma_f32_16x16x32_bf16 v[86:89], v[160:163], v[192:195], v[86:89]
	v_mfma_f32_16x16x32_bf16 v[82:85], v[164:167], v[188:191], v[82:85]
	v_mfma_f32_16x16x32_bf16 v[82:85], v[168:171], v[192:195], v[82:85]
	v_mfma_f32_16x16x32_bf16 v[70:73], v[156:159], v[196:199], v[70:73]
	v_mfma_f32_16x16x32_bf16 v[70:73], v[160:163], v[200:203], v[70:73]
	v_mfma_f32_16x16x32_bf16 v[66:69], v[164:167], v[196:199], v[66:69]
	v_mfma_f32_16x16x32_bf16 v[66:69], v[168:171], v[200:203], v[66:69]
	s_setprio 0
	s_barrier
	s_mov_b32 m0, s25
	s_mov_b32 s18, s14
	s_mov_b32 s19, s15
	ds_read_b128 v[172:175], v144 offset:16384
	ds_read_b128 v[176:179], v144 offset:17408
	ds_read_b128 v[180:183], v144 offset:18432
	ds_read_b128 v[184:187], v144 offset:19456
	ds_read_b128 v[188:191], v144 offset:20480
	ds_read_b128 v[192:195], v144 offset:21504
	ds_read_b128 v[196:199], v144 offset:22528
	ds_read_b128 v[200:203], v144 offset:23552
	buffer_load_dwordx4 v141, s[16:19], s64 offen lds
	s_add_i32 s65, s64, 0x40000
	s_mov_b32 m0, s27
	s_add_i32 s66, s64, 0x80000
	buffer_load_dwordx4 v141, s[16:19], s65 offen lds
	s_mov_b32 m0, s30
	s_add_i32 s67, s64, 0xc0000
	buffer_load_dwordx4 v141, s[16:19], s66 offen lds
	s_mov_b32 m0, s31
	s_nop 0
	buffer_load_dwordx4 v141, s[16:19], s67 offen lds
	s_mov_b32 m0, s21
	s_nop 0
	buffer_load_dwordx4 v140, s[12:15], s64 offen lds
	s_mov_b32 m0, s38
	s_nop 0
	buffer_load_dwordx4 v140, s[12:15], s65 offen lds
	s_waitcnt vmcnt(8)
	s_waitcnt lgkmcnt(0)
	s_setprio 1
	v_mfma_f32_16x16x32_bf16 v[62:65], v[132:135], v[172:175], v[62:65]
	s_barrier
	v_mfma_f32_16x16x32_bf16 v[62:65], v[136:139], v[176:179], v[62:65]
	v_mfma_f32_16x16x32_bf16 v[58:61], v[148:151], v[172:175], v[58:61]
	v_mfma_f32_16x16x32_bf16 v[58:61], v[152:155], v[176:179], v[58:61]
	v_mfma_f32_16x16x32_bf16 v[46:49], v[132:135], v[180:183], v[46:49]
	v_mfma_f32_16x16x32_bf16 v[46:49], v[136:139], v[184:187], v[46:49]
	v_mfma_f32_16x16x32_bf16 v[42:45], v[148:151], v[180:183], v[42:45]
	v_mfma_f32_16x16x32_bf16 v[42:45], v[152:155], v[184:187], v[42:45]
	v_mfma_f32_16x16x32_bf16 v[30:33], v[132:135], v[188:191], v[30:33]
	v_mfma_f32_16x16x32_bf16 v[30:33], v[136:139], v[192:195], v[30:33]
	v_mfma_f32_16x16x32_bf16 v[26:29], v[148:151], v[188:191], v[26:29]
	v_mfma_f32_16x16x32_bf16 v[26:29], v[152:155], v[192:195], v[26:29]
	v_mfma_f32_16x16x32_bf16 v[14:17], v[132:135], v[196:199], v[14:17]
	v_mfma_f32_16x16x32_bf16 v[14:17], v[136:139], v[200:203], v[14:17]
	v_mfma_f32_16x16x32_bf16 v[10:13], v[148:151], v[196:199], v[10:13]
	v_mfma_f32_16x16x32_bf16 v[10:13], v[152:155], v[200:203], v[10:13]
	v_mfma_f32_16x16x32_bf16 v[54:57], v[156:159], v[172:175], v[54:57]
	v_mfma_f32_16x16x32_bf16 v[54:57], v[160:163], v[176:179], v[54:57]
	v_mfma_f32_16x16x32_bf16 v[50:53], v[164:167], v[172:175], v[50:53]
	v_mfma_f32_16x16x32_bf16 v[50:53], v[168:171], v[176:179], v[50:53]
	v_mfma_f32_16x16x32_bf16 v[38:41], v[156:159], v[180:183], v[38:41]
	v_mfma_f32_16x16x32_bf16 v[38:41], v[160:163], v[184:187], v[38:41]
	v_mfma_f32_16x16x32_bf16 v[34:37], v[164:167], v[180:183], v[34:37]
	v_mfma_f32_16x16x32_bf16 v[34:37], v[168:171], v[184:187], v[34:37]
	v_mfma_f32_16x16x32_bf16 v[22:25], v[156:159], v[188:191], v[22:25]
	v_mfma_f32_16x16x32_bf16 v[22:25], v[160:163], v[192:195], v[22:25]
	v_mfma_f32_16x16x32_bf16 v[18:21], v[164:167], v[188:191], v[18:21]
	v_mfma_f32_16x16x32_bf16 v[18:21], v[168:171], v[192:195], v[18:21]
	v_mfma_f32_16x16x32_bf16 v[6:9], v[156:159], v[196:199], v[6:9]
	v_mfma_f32_16x16x32_bf16 v[6:9], v[160:163], v[200:203], v[6:9]
	v_mfma_f32_16x16x32_bf16 v[2:5], v[164:167], v[196:199], v[2:5]
	v_mfma_f32_16x16x32_bf16 v[2:5], v[168:171], v[200:203], v[2:5]
	s_setprio 0
	s_barrier
	ds_read_b128 v[132:135], v145
	ds_read_b128 v[136:139], v145 offset:1024
	ds_read_b128 v[148:151], v145 offset:2048
	ds_read_b128 v[152:155], v145 offset:3072
	ds_read_b128 v[156:159], v147
	ds_read_b128 v[160:163], v147 offset:1024
	ds_read_b128 v[164:167], v147 offset:2048
	ds_read_b128 v[168:171], v147 offset:3072
	s_mov_b32 m0, s39
	ds_read_b128 v[172:175], v144 offset:32768
	ds_read_b128 v[176:179], v144 offset:33792
	ds_read_b128 v[180:183], v144 offset:34816
	ds_read_b128 v[184:187], v144 offset:35840
	ds_read_b128 v[188:191], v144 offset:36864
	ds_read_b128 v[192:195], v144 offset:37888
	ds_read_b128 v[196:199], v144 offset:38912
	ds_read_b128 v[200:203], v144 offset:39936
	buffer_load_dwordx4 v140, s[12:15], s66 offen lds
	s_mov_b32 m0, s40
	s_nop 0
	buffer_load_dwordx4 v140, s[12:15], s67 offen lds
	s_waitcnt vmcnt(8)
	s_waitcnt lgkmcnt(0)
	s_setprio 1
	v_mfma_f32_16x16x32_bf16 v[126:129], v[132:135], v[172:175], v[126:129]
	s_barrier
	v_mfma_f32_16x16x32_bf16 v[126:129], v[136:139], v[176:179], v[126:129]
	v_mfma_f32_16x16x32_bf16 v[122:125], v[148:151], v[172:175], v[122:125]
	v_mfma_f32_16x16x32_bf16 v[122:125], v[152:155], v[176:179], v[122:125]
	v_mfma_f32_16x16x32_bf16 v[110:113], v[132:135], v[180:183], v[110:113]
	v_mfma_f32_16x16x32_bf16 v[110:113], v[136:139], v[184:187], v[110:113]
	v_mfma_f32_16x16x32_bf16 v[106:109], v[148:151], v[180:183], v[106:109]
	v_mfma_f32_16x16x32_bf16 v[106:109], v[152:155], v[184:187], v[106:109]
	v_mfma_f32_16x16x32_bf16 v[94:97], v[132:135], v[188:191], v[94:97]
	v_mfma_f32_16x16x32_bf16 v[94:97], v[136:139], v[192:195], v[94:97]
	v_mfma_f32_16x16x32_bf16 v[90:93], v[148:151], v[188:191], v[90:93]
	v_mfma_f32_16x16x32_bf16 v[90:93], v[152:155], v[192:195], v[90:93]
	v_mfma_f32_16x16x32_bf16 v[78:81], v[132:135], v[196:199], v[78:81]
	v_mfma_f32_16x16x32_bf16 v[78:81], v[136:139], v[200:203], v[78:81]
	v_mfma_f32_16x16x32_bf16 v[74:77], v[148:151], v[196:199], v[74:77]
	v_mfma_f32_16x16x32_bf16 v[74:77], v[152:155], v[200:203], v[74:77]
	v_mfma_f32_16x16x32_bf16 v[118:121], v[156:159], v[172:175], v[118:121]
	v_mfma_f32_16x16x32_bf16 v[118:121], v[160:163], v[176:179], v[118:121]
	v_mfma_f32_16x16x32_bf16 v[114:117], v[164:167], v[172:175], v[114:117]
	v_mfma_f32_16x16x32_bf16 v[114:117], v[168:171], v[176:179], v[114:117]
	v_mfma_f32_16x16x32_bf16 v[102:105], v[156:159], v[180:183], v[102:105]
	v_mfma_f32_16x16x32_bf16 v[102:105], v[160:163], v[184:187], v[102:105]
	v_mfma_f32_16x16x32_bf16 v[98:101], v[164:167], v[180:183], v[98:101]
	v_mfma_f32_16x16x32_bf16 v[98:101], v[168:171], v[184:187], v[98:101]
	v_mfma_f32_16x16x32_bf16 v[86:89], v[156:159], v[188:191], v[86:89]
	v_mfma_f32_16x16x32_bf16 v[86:89], v[160:163], v[192:195], v[86:89]
	v_mfma_f32_16x16x32_bf16 v[82:85], v[164:167], v[188:191], v[82:85]
	v_mfma_f32_16x16x32_bf16 v[82:85], v[168:171], v[192:195], v[82:85]
	v_mfma_f32_16x16x32_bf16 v[70:73], v[156:159], v[196:199], v[70:73]
	v_mfma_f32_16x16x32_bf16 v[70:73], v[160:163], v[200:203], v[70:73]
	v_mfma_f32_16x16x32_bf16 v[66:69], v[164:167], v[196:199], v[66:69]
	v_mfma_f32_16x16x32_bf16 v[66:69], v[168:171], v[200:203], v[66:69]
	s_setprio 0
	s_barrier
	s_mov_b32 m0, s48
	ds_read_b128 v[172:175], v144 offset:49152
	ds_read_b128 v[176:179], v144 offset:50176
	ds_read_b128 v[180:183], v144 offset:51200
	ds_read_b128 v[184:187], v144 offset:52224
	ds_read_b128 v[188:191], v144 offset:53248
	ds_read_b128 v[192:195], v144 offset:54272
	ds_read_b128 v[196:199], v144 offset:55296
	ds_read_b128 v[200:203], v144 offset:56320
	buffer_load_dwordx4 v141, s[16:19], s63 offen lds
	s_add_i32 s65, s64, 0x40080
	s_mov_b32 m0, s49
	s_add_i32 s66, s64, 0x80080
	buffer_load_dwordx4 v141, s[16:19], s65 offen lds
	s_mov_b32 m0, s52
	s_add_i32 s64, s64, 0xc0080
	buffer_load_dwordx4 v141, s[16:19], s66 offen lds
	s_mov_b32 m0, s53
	s_nop 0
	buffer_load_dwordx4 v141, s[16:19], s64 offen lds
	s_mov_b32 m0, s50
	s_nop 0
	buffer_load_dwordx4 v140, s[12:15], s63 offen lds
	s_mov_b32 m0, s51
	s_nop 0
	buffer_load_dwordx4 v140, s[12:15], s65 offen lds
	s_waitcnt vmcnt(8)
	s_waitcnt lgkmcnt(0)
	s_setprio 1
	v_mfma_f32_16x16x32_bf16 v[62:65], v[132:135], v[172:175], v[62:65]
	s_barrier
	v_mfma_f32_16x16x32_bf16 v[62:65], v[136:139], v[176:179], v[62:65]
	v_mfma_f32_16x16x32_bf16 v[58:61], v[148:151], v[172:175], v[58:61]
	v_mfma_f32_16x16x32_bf16 v[58:61], v[152:155], v[176:179], v[58:61]
	v_mfma_f32_16x16x32_bf16 v[46:49], v[132:135], v[180:183], v[46:49]
	v_mfma_f32_16x16x32_bf16 v[46:49], v[136:139], v[184:187], v[46:49]
	v_mfma_f32_16x16x32_bf16 v[42:45], v[148:151], v[180:183], v[42:45]
	v_mfma_f32_16x16x32_bf16 v[42:45], v[152:155], v[184:187], v[42:45]
	v_mfma_f32_16x16x32_bf16 v[30:33], v[132:135], v[188:191], v[30:33]
	v_mfma_f32_16x16x32_bf16 v[30:33], v[136:139], v[192:195], v[30:33]
	v_mfma_f32_16x16x32_bf16 v[26:29], v[148:151], v[188:191], v[26:29]
	v_mfma_f32_16x16x32_bf16 v[26:29], v[152:155], v[192:195], v[26:29]
	v_mfma_f32_16x16x32_bf16 v[14:17], v[132:135], v[196:199], v[14:17]
	v_mfma_f32_16x16x32_bf16 v[14:17], v[136:139], v[200:203], v[14:17]
	v_mfma_f32_16x16x32_bf16 v[10:13], v[148:151], v[196:199], v[10:13]
	v_mfma_f32_16x16x32_bf16 v[10:13], v[152:155], v[200:203], v[10:13]
	v_mfma_f32_16x16x32_bf16 v[54:57], v[156:159], v[172:175], v[54:57]
	v_mfma_f32_16x16x32_bf16 v[54:57], v[160:163], v[176:179], v[54:57]
	v_mfma_f32_16x16x32_bf16 v[50:53], v[164:167], v[172:175], v[50:53]
	v_mfma_f32_16x16x32_bf16 v[50:53], v[168:171], v[176:179], v[50:53]
	v_mfma_f32_16x16x32_bf16 v[38:41], v[156:159], v[180:183], v[38:41]
	v_mfma_f32_16x16x32_bf16 v[38:41], v[160:163], v[184:187], v[38:41]
	v_mfma_f32_16x16x32_bf16 v[34:37], v[164:167], v[180:183], v[34:37]
	v_mfma_f32_16x16x32_bf16 v[34:37], v[168:171], v[184:187], v[34:37]
	v_mfma_f32_16x16x32_bf16 v[22:25], v[156:159], v[188:191], v[22:25]
	v_mfma_f32_16x16x32_bf16 v[22:25], v[160:163], v[192:195], v[22:25]
	v_mfma_f32_16x16x32_bf16 v[18:21], v[164:167], v[188:191], v[18:21]
	v_mfma_f32_16x16x32_bf16 v[18:21], v[168:171], v[192:195], v[18:21]
	v_mfma_f32_16x16x32_bf16 v[6:9], v[156:159], v[196:199], v[6:9]
	v_mfma_f32_16x16x32_bf16 v[6:9], v[160:163], v[200:203], v[6:9]
	v_mfma_f32_16x16x32_bf16 v[2:5], v[164:167], v[196:199], v[2:5]
	v_mfma_f32_16x16x32_bf16 v[2:5], v[168:171], v[200:203], v[2:5]
	s_setprio 0
	s_barrier
	s_add_i32 s62, s62, 2
	s_addk_i32 s61, 0x100
	s_cmp_ge_i32 s62, s3
	s_cbranch_scc0 .LBB0_1050

.LBB0_1181:
	v_add_u32_e32 v2, 0x10000, v232
	ds_read_b128 v[134:137], v2
	ds_read_b128 v[138:141], v2 offset:1024
	ds_read_b128 v[142:145], v2 offset:2048
	ds_read_b128 v[146:149], v2 offset:3072
	v_add_u32_e32 v2, 0x14000, v232
	ds_read_b128 v[150:153], v2
	ds_read_b128 v[154:157], v2 offset:1024
	ds_read_b128 v[158:161], v2 offset:2048
	ds_read_b128 v[162:165], v2 offset:3072
	s_add_i32 s50, s47, s90
	s_and_b64 s[18:19], exec, s[18:19]
	s_cselect_b32 s51, s88, s50
	s_add_i32 s50, s92, 0x80
	s_or_b32 s52, s51, 0x80
	s_add_i32 s18, s89, s93
	s_add_i32 s94, s94, 0x1bfffc80
	s_cmp_lt_u32 s91, 8
	s_cselect_b32 s18, s18, s94
	s_mov_b32 m0, s74
	s_add_i32 s19, s18, 0x80000
	ds_read_b128 v[166:169], v233
	ds_read_b128 v[170:173], v233 offset:1024
	ds_read_b128 v[174:177], v233 offset:2048
	ds_read_b128 v[178:181], v233 offset:3072
	ds_read_b128 v[182:185], v233 offset:4096
	ds_read_b128 v[186:189], v233 offset:5120
	ds_read_b128 v[190:193], v233 offset:6144
	ds_read_b128 v[194:197], v233 offset:7168
	buffer_load_dwordx4 v230, s[12:15], s19 offen lds
	s_add_i32 s18, s18, 0xc0000
	s_mov_b32 m0, s75
	s_nop 0
	buffer_load_dwordx4 v230, s[12:15], s18 offen lds
	s_waitcnt vmcnt(8)
	s_waitcnt lgkmcnt(0)
	s_setprio 1
	v_mfma_f32_16x16x32_bf16 v[130:133], v[134:137], v[166:169], v[130:133]
	s_barrier
	v_mfma_f32_16x16x32_bf16 v[130:133], v[138:141], v[170:173], v[130:133]
	v_mfma_f32_16x16x32_bf16 v[126:129], v[142:145], v[166:169], v[126:129]
	v_mfma_f32_16x16x32_bf16 v[126:129], v[146:149], v[170:173], v[126:129]
	v_mfma_f32_16x16x32_bf16 v[114:117], v[134:137], v[174:177], v[114:117]
	v_mfma_f32_16x16x32_bf16 v[114:117], v[138:141], v[178:181], v[114:117]
	v_mfma_f32_16x16x32_bf16 v[110:113], v[142:145], v[174:177], v[110:113]
	v_mfma_f32_16x16x32_bf16 v[110:113], v[146:149], v[178:181], v[110:113]
	v_mfma_f32_16x16x32_bf16 v[98:101], v[134:137], v[182:185], v[98:101]
	v_mfma_f32_16x16x32_bf16 v[98:101], v[138:141], v[186:189], v[98:101]
	v_mfma_f32_16x16x32_bf16 v[94:97], v[142:145], v[182:185], v[94:97]
	v_mfma_f32_16x16x32_bf16 v[94:97], v[146:149], v[186:189], v[94:97]
	v_mfma_f32_16x16x32_bf16 v[82:85], v[134:137], v[190:193], v[82:85]
	v_mfma_f32_16x16x32_bf16 v[82:85], v[138:141], v[194:197], v[82:85]
	v_mfma_f32_16x16x32_bf16 v[78:81], v[142:145], v[190:193], v[78:81]
	v_mfma_f32_16x16x32_bf16 v[78:81], v[146:149], v[194:197], v[78:81]
	v_mfma_f32_16x16x32_bf16 v[122:125], v[150:153], v[166:169], v[122:125]
	v_mfma_f32_16x16x32_bf16 v[122:125], v[154:157], v[170:173], v[122:125]
	v_mfma_f32_16x16x32_bf16 v[118:121], v[158:161], v[166:169], v[118:121]
	v_mfma_f32_16x16x32_bf16 v[118:121], v[162:165], v[170:173], v[118:121]
	v_mfma_f32_16x16x32_bf16 v[106:109], v[150:153], v[174:177], v[106:109]
	v_mfma_f32_16x16x32_bf16 v[106:109], v[154:157], v[178:181], v[106:109]
	v_mfma_f32_16x16x32_bf16 v[102:105], v[158:161], v[174:177], v[102:105]
	v_mfma_f32_16x16x32_bf16 v[102:105], v[162:165], v[178:181], v[102:105]
	v_mfma_f32_16x16x32_bf16 v[90:93], v[150:153], v[182:185], v[90:93]
	v_mfma_f32_16x16x32_bf16 v[90:93], v[154:157], v[186:189], v[90:93]
	v_mfma_f32_16x16x32_bf16 v[86:89], v[158:161], v[182:185], v[86:89]
	v_mfma_f32_16x16x32_bf16 v[86:89], v[162:165], v[186:189], v[86:89]
	v_mfma_f32_16x16x32_bf16 v[74:77], v[150:153], v[190:193], v[74:77]
	v_mfma_f32_16x16x32_bf16 v[74:77], v[154:157], v[194:197], v[74:77]
	v_mfma_f32_16x16x32_bf16 v[70:73], v[158:161], v[190:193], v[70:73]
	v_mfma_f32_16x16x32_bf16 v[70:73], v[162:165], v[194:197], v[70:73]
	s_setprio 0
	s_barrier
	s_mov_b32 m0, s27
	s_mov_b32 s18, s14
	s_mov_b32 s19, s15
	ds_read_b128 v[166:169], v233 offset:16384
	ds_read_b128 v[170:173], v233 offset:17408
	ds_read_b128 v[174:177], v233 offset:18432
	ds_read_b128 v[178:181], v233 offset:19456
	ds_read_b128 v[182:185], v233 offset:20480
	ds_read_b128 v[186:189], v233 offset:21504
	ds_read_b128 v[190:193], v233 offset:22528
	ds_read_b128 v[194:197], v233 offset:23552
	buffer_load_dwordx4 v231, s[16:19], s51 offen lds
	s_add_i32 s53, s51, 0x18000
	s_mov_b32 m0, s30
	s_nop 0
	buffer_load_dwordx4 v231, s[16:19], s53 offen lds
	s_add_i32 s53, s51, 0x30000
	s_mov_b32 m0, s31
	s_nop 0
	buffer_load_dwordx4 v231, s[16:19], s53 offen lds
	s_add_i32 s53, s51, 0x48000
	s_mov_b32 m0, s54
	s_nop 0
	buffer_load_dwordx4 v231, s[16:19], s53 offen lds
	s_mov_b32 m0, s25
	s_add_i32 s53, s92, 0x40000
	buffer_load_dwordx4 v230, s[12:15], s92 offen lds
	s_mov_b32 m0, s55
	s_nop 0
	buffer_load_dwordx4 v230, s[12:15], s53 offen lds
	s_waitcnt vmcnt(8)
	s_waitcnt lgkmcnt(0)
	s_setprio 1
	v_mfma_f32_16x16x32_bf16 v[66:69], v[134:137], v[166:169], v[66:69]
	s_barrier
	v_mfma_f32_16x16x32_bf16 v[62:65], v[142:145], v[166:169], v[62:65]
	v_mfma_f32_16x16x32_bf16 v[50:53], v[134:137], v[174:177], v[50:53]
	v_mfma_f32_16x16x32_bf16 v[46:49], v[142:145], v[174:177], v[46:49]
	v_mfma_f32_16x16x32_bf16 v[34:37], v[134:137], v[182:185], v[34:37]
	v_mfma_f32_16x16x32_bf16 v[30:33], v[142:145], v[182:185], v[30:33]
	v_mfma_f32_16x16x32_bf16 v[18:21], v[134:137], v[190:193], v[18:21]
	v_mfma_f32_16x16x32_bf16 v[14:17], v[142:145], v[190:193], v[14:17]
	v_mfma_f32_16x16x32_bf16 v[58:61], v[150:153], v[166:169], v[58:61]
	v_mfma_f32_16x16x32_bf16 v[54:57], v[158:161], v[166:169], v[54:57]
	v_mfma_f32_16x16x32_bf16 v[42:45], v[150:153], v[174:177], v[42:45]
	v_mfma_f32_16x16x32_bf16 v[38:41], v[158:161], v[174:177], v[38:41]
	v_mfma_f32_16x16x32_bf16 v[26:29], v[150:153], v[182:185], v[26:29]
	v_mfma_f32_16x16x32_bf16 v[22:25], v[158:161], v[182:185], v[22:25]
	v_mfma_f32_16x16x32_bf16 v[10:13], v[150:153], v[190:193], v[10:13]
	v_mfma_f32_16x16x32_bf16 v[4:7], v[158:161], v[190:193], v[6:9]
	v_mfma_f32_16x16x32_bf16 v[66:69], v[138:141], v[170:173], v[66:69]
	v_mfma_f32_16x16x32_bf16 v[62:65], v[146:149], v[170:173], v[62:65]
	v_mfma_f32_16x16x32_bf16 v[50:53], v[138:141], v[178:181], v[50:53]
	v_mfma_f32_16x16x32_bf16 v[46:49], v[146:149], v[178:181], v[46:49]
	v_mfma_f32_16x16x32_bf16 v[34:37], v[138:141], v[186:189], v[34:37]
	v_mfma_f32_16x16x32_bf16 v[30:33], v[146:149], v[186:189], v[30:33]
	v_mfma_f32_16x16x32_bf16 v[18:21], v[138:141], v[194:197], v[18:21]
	v_mfma_f32_16x16x32_bf16 v[14:17], v[146:149], v[194:197], v[14:17]
	v_mfma_f32_16x16x32_bf16 v[58:61], v[154:157], v[170:173], v[58:61]
	v_mfma_f32_16x16x32_bf16 v[54:57], v[162:165], v[170:173], v[54:57]
	v_mfma_f32_16x16x32_bf16 v[42:45], v[154:157], v[178:181], v[42:45]
	v_mfma_f32_16x16x32_bf16 v[38:41], v[162:165], v[178:181], v[38:41]
	v_mfma_f32_16x16x32_bf16 v[26:29], v[154:157], v[186:189], v[26:29]
	v_mfma_f32_16x16x32_bf16 v[22:25], v[162:165], v[186:189], v[22:25]
	v_mfma_f32_16x16x32_bf16 v[10:13], v[154:157], v[194:197], v[10:13]
	v_mfma_f32_16x16x32_bf16 v[4:7], v[162:165], v[194:197], v[4:7]
	s_setprio 0
	s_barrier
	v_add_u32_e32 v2, 0x18000, v232
	ds_read_b128 v[134:137], v2
	ds_read_b128 v[138:141], v2 offset:1024
	ds_read_b128 v[142:145], v2 offset:2048
	ds_read_b128 v[146:149], v2 offset:3072
	v_add_u32_e32 v2, 0x1c000, v232
	ds_read_b128 v[150:153], v2
	ds_read_b128 v[154:157], v2 offset:1024
	ds_read_b128 v[158:161], v2 offset:2048
	ds_read_b128 v[162:165], v2 offset:3072
	s_mov_b32 m0, s56
	s_add_i32 s53, s92, 0x80000
	ds_read_b128 v[166:169], v233 offset:32768
	ds_read_b128 v[170:173], v233 offset:33792
	ds_read_b128 v[174:177], v233 offset:34816
	ds_read_b128 v[178:181], v233 offset:35840
	ds_read_b128 v[182:185], v233 offset:36864
	ds_read_b128 v[186:189], v233 offset:37888
	ds_read_b128 v[190:193], v233 offset:38912
	ds_read_b128 v[194:197], v233 offset:39936
	buffer_load_dwordx4 v230, s[12:15], s53 offen lds
	s_add_i32 s53, s92, 0xc0000
	s_mov_b32 m0, s57
	s_nop 0
	buffer_load_dwordx4 v230, s[12:15], s53 offen lds
	s_waitcnt vmcnt(8)
	s_waitcnt lgkmcnt(0)
	s_setprio 1
	v_mfma_f32_16x16x32_bf16 v[130:133], v[134:137], v[166:169], v[130:133]
	s_barrier
	v_mfma_f32_16x16x32_bf16 v[130:133], v[138:141], v[170:173], v[130:133]
	v_mfma_f32_16x16x32_bf16 v[126:129], v[142:145], v[166:169], v[126:129]
	v_mfma_f32_16x16x32_bf16 v[126:129], v[146:149], v[170:173], v[126:129]
	v_mfma_f32_16x16x32_bf16 v[114:117], v[134:137], v[174:177], v[114:117]
	v_mfma_f32_16x16x32_bf16 v[114:117], v[138:141], v[178:181], v[114:117]
	v_mfma_f32_16x16x32_bf16 v[110:113], v[142:145], v[174:177], v[110:113]
	v_mfma_f32_16x16x32_bf16 v[110:113], v[146:149], v[178:181], v[110:113]
	v_mfma_f32_16x16x32_bf16 v[98:101], v[134:137], v[182:185], v[98:101]
	v_mfma_f32_16x16x32_bf16 v[98:101], v[138:141], v[186:189], v[98:101]
	v_mfma_f32_16x16x32_bf16 v[94:97], v[142:145], v[182:185], v[94:97]
	v_mfma_f32_16x16x32_bf16 v[94:97], v[146:149], v[186:189], v[94:97]
	v_mfma_f32_16x16x32_bf16 v[82:85], v[134:137], v[190:193], v[82:85]
	v_mfma_f32_16x16x32_bf16 v[82:85], v[138:141], v[194:197], v[82:85]
	v_mfma_f32_16x16x32_bf16 v[78:81], v[142:145], v[190:193], v[78:81]
	v_mfma_f32_16x16x32_bf16 v[78:81], v[146:149], v[194:197], v[78:81]
	v_mfma_f32_16x16x32_bf16 v[122:125], v[150:153], v[166:169], v[122:125]
	v_mfma_f32_16x16x32_bf16 v[122:125], v[154:157], v[170:173], v[122:125]
	v_mfma_f32_16x16x32_bf16 v[118:121], v[158:161], v[166:169], v[118:121]
	v_mfma_f32_16x16x32_bf16 v[118:121], v[162:165], v[170:173], v[118:121]
	v_mfma_f32_16x16x32_bf16 v[106:109], v[150:153], v[174:177], v[106:109]
	v_mfma_f32_16x16x32_bf16 v[106:109], v[154:157], v[178:181], v[106:109]
	v_mfma_f32_16x16x32_bf16 v[102:105], v[158:161], v[174:177], v[102:105]
	v_mfma_f32_16x16x32_bf16 v[102:105], v[162:165], v[178:181], v[102:105]
	v_mfma_f32_16x16x32_bf16 v[90:93], v[150:153], v[182:185], v[90:93]
	v_mfma_f32_16x16x32_bf16 v[90:93], v[154:157], v[186:189], v[90:93]
	v_mfma_f32_16x16x32_bf16 v[86:89], v[158:161], v[182:185], v[86:89]
	v_mfma_f32_16x16x32_bf16 v[86:89], v[162:165], v[186:189], v[86:89]
	v_mfma_f32_16x16x32_bf16 v[74:77], v[150:153], v[190:193], v[74:77]
	v_mfma_f32_16x16x32_bf16 v[74:77], v[154:157], v[194:197], v[74:77]
	v_mfma_f32_16x16x32_bf16 v[70:73], v[158:161], v[190:193], v[70:73]
	v_mfma_f32_16x16x32_bf16 v[70:73], v[162:165], v[194:197], v[70:73]
	s_setprio 0
	s_barrier
	s_mov_b32 m0, s64
	ds_read_b128 v[166:169], v233 offset:49152
	ds_read_b128 v[170:173], v233 offset:50176
	ds_read_b128 v[174:177], v233 offset:51200
	ds_read_b128 v[178:181], v233 offset:52224
	ds_read_b128 v[182:185], v233 offset:53248
	ds_read_b128 v[186:189], v233 offset:54272
	ds_read_b128 v[190:193], v233 offset:55296
	ds_read_b128 v[194:197], v233 offset:56320
	buffer_load_dwordx4 v231, s[16:19], s52 offen lds
	s_add_i32 s52, s51, 0x18080
	s_mov_b32 m0, s65
	s_nop 0
	buffer_load_dwordx4 v231, s[16:19], s52 offen lds
	s_add_i32 s52, s51, 0x30080
	s_mov_b32 m0, s68
	s_add_i32 s51, s51, 0x48080
	buffer_load_dwordx4 v231, s[16:19], s52 offen lds
	s_mov_b32 m0, s69
	s_nop 0
	buffer_load_dwordx4 v231, s[16:19], s51 offen lds
	s_mov_b32 m0, s66
	s_add_i32 s18, s92, 0x40080
	buffer_load_dwordx4 v230, s[12:15], s50 offen lds
	s_mov_b32 m0, s67
	s_nop 0
	buffer_load_dwordx4 v230, s[12:15], s18 offen lds
	s_waitcnt vmcnt(8)
	s_waitcnt lgkmcnt(0)
	s_setprio 1
	v_mfma_f32_16x16x32_bf16 v[66:69], v[134:137], v[166:169], v[66:69]
	s_barrier
	v_mfma_f32_16x16x32_bf16 v[62:65], v[142:145], v[166:169], v[62:65]
	v_mfma_f32_16x16x32_bf16 v[50:53], v[134:137], v[174:177], v[50:53]
	v_mfma_f32_16x16x32_bf16 v[46:49], v[142:145], v[174:177], v[46:49]
	v_mfma_f32_16x16x32_bf16 v[34:37], v[134:137], v[182:185], v[34:37]
	v_mfma_f32_16x16x32_bf16 v[30:33], v[142:145], v[182:185], v[30:33]
	v_mfma_f32_16x16x32_bf16 v[18:21], v[134:137], v[190:193], v[18:21]
	v_mfma_f32_16x16x32_bf16 v[14:17], v[142:145], v[190:193], v[14:17]
	v_mfma_f32_16x16x32_bf16 v[58:61], v[150:153], v[166:169], v[58:61]
	v_mfma_f32_16x16x32_bf16 v[54:57], v[158:161], v[166:169], v[54:57]
	v_mfma_f32_16x16x32_bf16 v[42:45], v[150:153], v[174:177], v[42:45]
	v_mfma_f32_16x16x32_bf16 v[38:41], v[158:161], v[174:177], v[38:41]
	v_mfma_f32_16x16x32_bf16 v[26:29], v[150:153], v[182:185], v[26:29]
	v_mfma_f32_16x16x32_bf16 v[22:25], v[158:161], v[182:185], v[22:25]
	v_mfma_f32_16x16x32_bf16 v[8:11], v[150:153], v[190:193], v[10:13]
	v_mfma_f32_16x16x32_bf16 v[4:7], v[158:161], v[190:193], v[4:7]
	v_mfma_f32_16x16x32_bf16 v[66:69], v[138:141], v[170:173], v[66:69]
	v_mfma_f32_16x16x32_bf16 v[62:65], v[146:149], v[170:173], v[62:65]
	v_mfma_f32_16x16x32_bf16 v[50:53], v[138:141], v[178:181], v[50:53]
	v_mfma_f32_16x16x32_bf16 v[46:49], v[146:149], v[178:181], v[46:49]
	v_mfma_f32_16x16x32_bf16 v[34:37], v[138:141], v[186:189], v[34:37]
	v_mfma_f32_16x16x32_bf16 v[30:33], v[146:149], v[186:189], v[30:33]
	v_mfma_f32_16x16x32_bf16 v[18:21], v[138:141], v[194:197], v[18:21]
	v_mfma_f32_16x16x32_bf16 v[14:17], v[146:149], v[194:197], v[14:17]
	v_mfma_f32_16x16x32_bf16 v[58:61], v[154:157], v[170:173], v[58:61]
	v_mfma_f32_16x16x32_bf16 v[54:57], v[162:165], v[170:173], v[54:57]
	v_mfma_f32_16x16x32_bf16 v[42:45], v[154:157], v[178:181], v[42:45]
	v_mfma_f32_16x16x32_bf16 v[38:41], v[162:165], v[178:181], v[38:41]
	v_mfma_f32_16x16x32_bf16 v[26:29], v[154:157], v[186:189], v[26:29]
	v_mfma_f32_16x16x32_bf16 v[22:25], v[162:165], v[186:189], v[22:25]
	v_mfma_f32_16x16x32_bf16 v[10:13], v[154:157], v[194:197], v[8:11]
	v_mfma_f32_16x16x32_bf16 v[6:9], v[162:165], v[194:197], v[4:7]
	s_setprio 0
	s_barrier
	s_add_i32 s91, s91, 2
	s_addk_i32 s90, 0x100
	s_cmp_ge_i32 s91, s3
	s_cbranch_scc1 .LBB0_1193

.LBB0_1290:
	ds_read_b128 v[106:109], v224
	ds_read_b128 v[118:121], v224 offset:1024
	ds_read_b128 v[130:133], v224 offset:2048
	ds_read_b128 v[138:141], v224 offset:3072
	ds_read_b128 v[146:149], v225
	ds_read_b128 v[150:153], v225 offset:1024
	ds_read_b128 v[154:157], v225 offset:2048
	ds_read_b128 v[158:161], v225 offset:3072
	s_add_i32 s18, s72, 0xffe80080
	s_cmp_eq_u32 s56, s74
	s_cselect_b32 s75, s6, s18
	s_cselect_b32 s77, s7, s73
	s_or_b32 s76, s75, 0x80
	s_add_i32 s18, s72, 0xfff80000
	s_mov_b32 m0, s57
	ds_read_b128 v[162:165], v226
	ds_read_b128 v[166:169], v226 offset:1024
	ds_read_b128 v[170:173], v226 offset:2048
	ds_read_b128 v[174:177], v226 offset:3072
	ds_read_b128 v[178:181], v226 offset:4096
	ds_read_b128 v[182:185], v226 offset:5120
	ds_read_b128 v[190:193], v226 offset:6144
	ds_read_b128 v[194:197], v226 offset:7168
	buffer_load_dwordx4 v222, s[12:15], s18 offen lds
	s_mov_b32 m0, s60
	s_nop 0
	buffer_load_dwordx4 v222, s[12:15], s72 offen lds
	s_waitcnt vmcnt(8)
	s_waitcnt lgkmcnt(0)
	s_setprio 1
	v_mfma_f32_16x16x32_bf16 v[142:145], v[106:109], v[162:165], v[142:145]
	s_barrier
	v_mfma_f32_16x16x32_bf16 v[142:145], v[118:121], v[166:169], v[142:145]
	v_mfma_f32_16x16x32_bf16 v[134:137], v[130:133], v[162:165], v[134:137]
	v_mfma_f32_16x16x32_bf16 v[134:137], v[138:141], v[166:169], v[134:137]
	v_mfma_f32_16x16x32_bf16 v[114:117], v[106:109], v[170:173], v[114:117]
	v_mfma_f32_16x16x32_bf16 v[114:117], v[118:121], v[174:177], v[114:117]
	v_mfma_f32_16x16x32_bf16 v[110:113], v[130:133], v[170:173], v[110:113]
	v_mfma_f32_16x16x32_bf16 v[110:113], v[138:141], v[174:177], v[110:113]
	v_mfma_f32_16x16x32_bf16 v[94:97], v[106:109], v[178:181], v[94:97]
	v_mfma_f32_16x16x32_bf16 v[94:97], v[118:121], v[182:185], v[94:97]
	v_mfma_f32_16x16x32_bf16 v[90:93], v[130:133], v[178:181], v[90:93]
	v_mfma_f32_16x16x32_bf16 v[90:93], v[138:141], v[182:185], v[90:93]
	v_mfma_f32_16x16x32_bf16 v[78:81], v[106:109], v[190:193], v[78:81]
	v_mfma_f32_16x16x32_bf16 v[78:81], v[118:121], v[194:197], v[78:81]
	v_mfma_f32_16x16x32_bf16 v[74:77], v[130:133], v[190:193], v[74:77]
	v_mfma_f32_16x16x32_bf16 v[74:77], v[138:141], v[194:197], v[74:77]
	v_mfma_f32_16x16x32_bf16 v[126:129], v[146:149], v[162:165], v[126:129]
	v_mfma_f32_16x16x32_bf16 v[126:129], v[150:153], v[166:169], v[126:129]
	v_mfma_f32_16x16x32_bf16 v[122:125], v[154:157], v[162:165], v[122:125]
	v_mfma_f32_16x16x32_bf16 v[122:125], v[158:161], v[166:169], v[122:125]
	v_mfma_f32_16x16x32_bf16 v[102:105], v[146:149], v[170:173], v[102:105]
	v_mfma_f32_16x16x32_bf16 v[102:105], v[150:153], v[174:177], v[102:105]
	v_mfma_f32_16x16x32_bf16 v[98:101], v[154:157], v[170:173], v[98:101]
	v_mfma_f32_16x16x32_bf16 v[98:101], v[158:161], v[174:177], v[98:101]
	v_mfma_f32_16x16x32_bf16 v[86:89], v[146:149], v[178:181], v[86:89]
	v_mfma_f32_16x16x32_bf16 v[86:89], v[150:153], v[182:185], v[86:89]
	v_mfma_f32_16x16x32_bf16 v[82:85], v[154:157], v[178:181], v[82:85]
	v_mfma_f32_16x16x32_bf16 v[82:85], v[158:161], v[182:185], v[82:85]
	v_mfma_f32_16x16x32_bf16 v[70:73], v[146:149], v[190:193], v[70:73]
	v_mfma_f32_16x16x32_bf16 v[70:73], v[150:153], v[194:197], v[70:73]
	v_mfma_f32_16x16x32_bf16 v[66:69], v[154:157], v[190:193], v[66:69]
	v_mfma_f32_16x16x32_bf16 v[66:69], v[158:161], v[194:197], v[66:69]
	s_setprio 0
	s_barrier
	s_mov_b32 m0, s27
	s_mov_b32 s18, s14
	s_mov_b32 s19, s15
	ds_read_b128 v[162:165], v226 offset:16384
	ds_read_b128 v[166:169], v226 offset:17408
	ds_read_b128 v[170:173], v226 offset:18432
	ds_read_b128 v[174:177], v226 offset:19456
	ds_read_b128 v[178:181], v226 offset:20480
	ds_read_b128 v[182:185], v226 offset:21504
	ds_read_b128 v[190:193], v226 offset:22528
	ds_read_b128 v[194:197], v226 offset:23552
	buffer_load_dwordx4 v223, s[16:19], s77 offen lds
	s_add_i32 s78, s77, 0x80000
	s_mov_b32 m0, s30
	s_nop 0
	buffer_load_dwordx4 v223, s[16:19], s78 offen lds
	s_add_i32 s78, s77, 0x100000
	s_mov_b32 m0, s31
	s_nop 0
	buffer_load_dwordx4 v223, s[16:19], s78 offen lds
	s_add_i32 s78, s77, 0x180000
	s_mov_b32 m0, s41
	s_nop 0
	buffer_load_dwordx4 v223, s[16:19], s78 offen lds
	s_mov_b32 m0, s25
	s_add_i32 s78, s75, 0x80000
	buffer_load_dwordx4 v222, s[12:15], s75 offen lds
	s_mov_b32 m0, s42
	s_nop 0
	buffer_load_dwordx4 v222, s[12:15], s78 offen lds
	s_waitcnt vmcnt(8)
	s_waitcnt lgkmcnt(0)
	s_setprio 1
	v_mfma_f32_16x16x32_bf16 v[62:65], v[106:109], v[162:165], v[62:65]
	s_barrier
	v_mfma_f32_16x16x32_bf16 v[62:65], v[118:121], v[166:169], v[62:65]
	v_mfma_f32_16x16x32_bf16 v[58:61], v[130:133], v[162:165], v[58:61]
	v_mfma_f32_16x16x32_bf16 v[58:61], v[138:141], v[166:169], v[58:61]
	v_mfma_f32_16x16x32_bf16 v[46:49], v[106:109], v[170:173], v[46:49]
	v_mfma_f32_16x16x32_bf16 v[46:49], v[118:121], v[174:177], v[46:49]
	v_mfma_f32_16x16x32_bf16 v[42:45], v[130:133], v[170:173], v[42:45]
	v_mfma_f32_16x16x32_bf16 v[42:45], v[138:141], v[174:177], v[42:45]
	v_mfma_f32_16x16x32_bf16 v[30:33], v[106:109], v[178:181], v[30:33]
	v_mfma_f32_16x16x32_bf16 v[30:33], v[118:121], v[182:185], v[30:33]
	v_mfma_f32_16x16x32_bf16 v[26:29], v[130:133], v[178:181], v[26:29]
	v_mfma_f32_16x16x32_bf16 v[26:29], v[138:141], v[182:185], v[26:29]
	v_mfma_f32_16x16x32_bf16 v[14:17], v[106:109], v[190:193], v[14:17]
	v_mfma_f32_16x16x32_bf16 v[14:17], v[118:121], v[194:197], v[14:17]
	v_mfma_f32_16x16x32_bf16 v[10:13], v[130:133], v[190:193], v[10:13]
	v_mfma_f32_16x16x32_bf16 v[10:13], v[138:141], v[194:197], v[10:13]
	v_mfma_f32_16x16x32_bf16 v[54:57], v[146:149], v[162:165], v[54:57]
	v_mfma_f32_16x16x32_bf16 v[54:57], v[150:153], v[166:169], v[54:57]
	v_mfma_f32_16x16x32_bf16 v[50:53], v[154:157], v[162:165], v[50:53]
	v_mfma_f32_16x16x32_bf16 v[50:53], v[158:161], v[166:169], v[50:53]
	v_mfma_f32_16x16x32_bf16 v[38:41], v[146:149], v[170:173], v[38:41]
	v_mfma_f32_16x16x32_bf16 v[38:41], v[150:153], v[174:177], v[38:41]
	v_mfma_f32_16x16x32_bf16 v[34:37], v[154:157], v[170:173], v[34:37]
	v_mfma_f32_16x16x32_bf16 v[34:37], v[158:161], v[174:177], v[34:37]
	v_mfma_f32_16x16x32_bf16 v[22:25], v[146:149], v[178:181], v[22:25]
	v_mfma_f32_16x16x32_bf16 v[22:25], v[150:153], v[182:185], v[22:25]
	v_mfma_f32_16x16x32_bf16 v[18:21], v[154:157], v[178:181], v[18:21]
	v_mfma_f32_16x16x32_bf16 v[18:21], v[158:161], v[182:185], v[18:21]
	v_mfma_f32_16x16x32_bf16 v[6:9], v[146:149], v[190:193], v[6:9]
	v_mfma_f32_16x16x32_bf16 v[6:9], v[150:153], v[194:197], v[6:9]
	v_mfma_f32_16x16x32_bf16 v[2:5], v[154:157], v[190:193], v[2:5]
	v_mfma_f32_16x16x32_bf16 v[2:5], v[158:161], v[194:197], v[2:5]
	s_setprio 0
	s_barrier
	ds_read_b128 v[106:109], v227
	ds_read_b128 v[118:121], v227 offset:1024
	ds_read_b128 v[130:133], v227 offset:2048
	ds_read_b128 v[138:141], v227 offset:3072
	ds_read_b128 v[146:149], v228
	ds_read_b128 v[150:153], v228 offset:1024
	ds_read_b128 v[154:157], v228 offset:2048
	ds_read_b128 v[158:161], v228 offset:3072
	s_mov_b32 m0, s43
	s_add_i32 s78, s75, 0x100000
	ds_read_b128 v[162:165], v226 offset:32768
	ds_read_b128 v[166:169], v226 offset:33792
	ds_read_b128 v[170:173], v226 offset:34816
	ds_read_b128 v[174:177], v226 offset:35840
	ds_read_b128 v[178:181], v226 offset:36864
	ds_read_b128 v[182:185], v226 offset:37888
	ds_read_b128 v[190:193], v226 offset:38912
	ds_read_b128 v[194:197], v226 offset:39936
	buffer_load_dwordx4 v222, s[12:15], s78 offen lds
	s_add_i32 s78, s75, 0x180000
	s_mov_b32 m0, s44
	s_nop 0
	buffer_load_dwordx4 v222, s[12:15], s78 offen lds
	s_waitcnt vmcnt(8)
	s_waitcnt lgkmcnt(0)
	s_setprio 1
	v_mfma_f32_16x16x32_bf16 v[142:145], v[106:109], v[162:165], v[142:145]
	s_barrier
	v_mfma_f32_16x16x32_bf16 v[142:145], v[118:121], v[166:169], v[142:145]
	v_mfma_f32_16x16x32_bf16 v[134:137], v[130:133], v[162:165], v[134:137]
	v_mfma_f32_16x16x32_bf16 v[134:137], v[138:141], v[166:169], v[134:137]
	v_mfma_f32_16x16x32_bf16 v[114:117], v[106:109], v[170:173], v[114:117]
	v_mfma_f32_16x16x32_bf16 v[114:117], v[118:121], v[174:177], v[114:117]
	v_mfma_f32_16x16x32_bf16 v[110:113], v[130:133], v[170:173], v[110:113]
	v_mfma_f32_16x16x32_bf16 v[110:113], v[138:141], v[174:177], v[110:113]
	v_mfma_f32_16x16x32_bf16 v[94:97], v[106:109], v[178:181], v[94:97]
	v_mfma_f32_16x16x32_bf16 v[94:97], v[118:121], v[182:185], v[94:97]
	v_mfma_f32_16x16x32_bf16 v[90:93], v[130:133], v[178:181], v[90:93]
	v_mfma_f32_16x16x32_bf16 v[90:93], v[138:141], v[182:185], v[90:93]
	v_mfma_f32_16x16x32_bf16 v[78:81], v[106:109], v[190:193], v[78:81]
	v_mfma_f32_16x16x32_bf16 v[78:81], v[118:121], v[194:197], v[78:81]
	v_mfma_f32_16x16x32_bf16 v[74:77], v[130:133], v[190:193], v[74:77]
	v_mfma_f32_16x16x32_bf16 v[74:77], v[138:141], v[194:197], v[74:77]
	v_mfma_f32_16x16x32_bf16 v[126:129], v[146:149], v[162:165], v[126:129]
	v_mfma_f32_16x16x32_bf16 v[126:129], v[150:153], v[166:169], v[126:129]
	v_mfma_f32_16x16x32_bf16 v[122:125], v[154:157], v[162:165], v[122:125]
	v_mfma_f32_16x16x32_bf16 v[122:125], v[158:161], v[166:169], v[122:125]
	v_mfma_f32_16x16x32_bf16 v[102:105], v[146:149], v[170:173], v[102:105]
	v_mfma_f32_16x16x32_bf16 v[102:105], v[150:153], v[174:177], v[102:105]
	v_mfma_f32_16x16x32_bf16 v[98:101], v[154:157], v[170:173], v[98:101]
	v_mfma_f32_16x16x32_bf16 v[98:101], v[158:161], v[174:177], v[98:101]
	v_mfma_f32_16x16x32_bf16 v[86:89], v[146:149], v[178:181], v[86:89]
	v_mfma_f32_16x16x32_bf16 v[86:89], v[150:153], v[182:185], v[86:89]
	v_mfma_f32_16x16x32_bf16 v[82:85], v[154:157], v[178:181], v[82:85]
	v_mfma_f32_16x16x32_bf16 v[82:85], v[158:161], v[182:185], v[82:85]
	v_mfma_f32_16x16x32_bf16 v[70:73], v[146:149], v[190:193], v[70:73]
	v_mfma_f32_16x16x32_bf16 v[70:73], v[150:153], v[194:197], v[70:73]
	v_mfma_f32_16x16x32_bf16 v[66:69], v[154:157], v[190:193], v[66:69]
	v_mfma_f32_16x16x32_bf16 v[66:69], v[158:161], v[194:197], v[66:69]
	s_setprio 0
	s_barrier
	s_mov_b32 m0, s48
	s_or_b32 s78, s77, 0x80
	ds_read_b128 v[162:165], v226 offset:49152
	ds_read_b128 v[166:169], v226 offset:50176
	ds_read_b128 v[170:173], v226 offset:51200
	ds_read_b128 v[174:177], v226 offset:52224
	ds_read_b128 v[178:181], v226 offset:53248
	ds_read_b128 v[182:185], v226 offset:54272
	ds_read_b128 v[190:193], v226 offset:55296
	ds_read_b128 v[194:197], v226 offset:56320
	buffer_load_dwordx4 v223, s[16:19], s78 offen lds
	s_add_i32 s78, s77, 0x80080
	s_mov_b32 m0, s49
	s_add_i32 s75, s75, 0x80080
	buffer_load_dwordx4 v223, s[16:19], s78 offen lds
	s_add_i32 s78, s77, 0x100080
	s_mov_b32 m0, s52
	s_add_i32 s77, s77, 0x180080
	buffer_load_dwordx4 v223, s[16:19], s78 offen lds
	s_mov_b32 m0, s53
	s_nop 0
	buffer_load_dwordx4 v223, s[16:19], s77 offen lds
	s_mov_b32 m0, s50
	s_nop 0
	buffer_load_dwordx4 v222, s[12:15], s76 offen lds
	s_mov_b32 m0, s51
	s_nop 0
	buffer_load_dwordx4 v222, s[12:15], s75 offen lds
	s_waitcnt vmcnt(8)
	s_waitcnt lgkmcnt(0)
	s_setprio 1
	v_mfma_f32_16x16x32_bf16 v[62:65], v[106:109], v[162:165], v[62:65]
	s_barrier
	v_mfma_f32_16x16x32_bf16 v[62:65], v[118:121], v[166:169], v[62:65]
	v_mfma_f32_16x16x32_bf16 v[58:61], v[130:133], v[162:165], v[58:61]
	v_mfma_f32_16x16x32_bf16 v[58:61], v[138:141], v[166:169], v[58:61]
	v_mfma_f32_16x16x32_bf16 v[46:49], v[106:109], v[170:173], v[46:49]
	v_mfma_f32_16x16x32_bf16 v[46:49], v[118:121], v[174:177], v[46:49]
	v_mfma_f32_16x16x32_bf16 v[42:45], v[130:133], v[170:173], v[42:45]
	v_mfma_f32_16x16x32_bf16 v[42:45], v[138:141], v[174:177], v[42:45]
	v_mfma_f32_16x16x32_bf16 v[30:33], v[106:109], v[178:181], v[30:33]
	v_mfma_f32_16x16x32_bf16 v[30:33], v[118:121], v[182:185], v[30:33]
	v_mfma_f32_16x16x32_bf16 v[26:29], v[130:133], v[178:181], v[26:29]
	v_mfma_f32_16x16x32_bf16 v[26:29], v[138:141], v[182:185], v[26:29]
	v_mfma_f32_16x16x32_bf16 v[14:17], v[106:109], v[190:193], v[14:17]
	v_mfma_f32_16x16x32_bf16 v[14:17], v[118:121], v[194:197], v[14:17]
	v_mfma_f32_16x16x32_bf16 v[10:13], v[130:133], v[190:193], v[10:13]
	v_mfma_f32_16x16x32_bf16 v[10:13], v[138:141], v[194:197], v[10:13]
	v_mfma_f32_16x16x32_bf16 v[54:57], v[146:149], v[162:165], v[54:57]
	v_mfma_f32_16x16x32_bf16 v[54:57], v[150:153], v[166:169], v[54:57]
	v_mfma_f32_16x16x32_bf16 v[50:53], v[154:157], v[162:165], v[50:53]
	v_mfma_f32_16x16x32_bf16 v[50:53], v[158:161], v[166:169], v[50:53]
	v_mfma_f32_16x16x32_bf16 v[38:41], v[146:149], v[170:173], v[38:41]
	v_mfma_f32_16x16x32_bf16 v[38:41], v[150:153], v[174:177], v[38:41]
	v_mfma_f32_16x16x32_bf16 v[34:37], v[154:157], v[170:173], v[34:37]
	v_mfma_f32_16x16x32_bf16 v[34:37], v[158:161], v[174:177], v[34:37]
	v_mfma_f32_16x16x32_bf16 v[22:25], v[146:149], v[178:181], v[22:25]
	v_mfma_f32_16x16x32_bf16 v[22:25], v[150:153], v[182:185], v[22:25]
	v_mfma_f32_16x16x32_bf16 v[18:21], v[154:157], v[178:181], v[18:21]
	v_mfma_f32_16x16x32_bf16 v[18:21], v[158:161], v[182:185], v[18:21]
	v_mfma_f32_16x16x32_bf16 v[6:9], v[146:149], v[190:193], v[6:9]
	v_mfma_f32_16x16x32_bf16 v[6:9], v[150:153], v[194:197], v[6:9]
	v_mfma_f32_16x16x32_bf16 v[2:5], v[154:157], v[190:193], v[2:5]
	v_mfma_f32_16x16x32_bf16 v[2:5], v[158:161], v[194:197], v[2:5]
	s_setprio 0
	s_barrier
	s_add_i32 s74, s74, 2
	s_addk_i32 s72, 0x100
	s_addk_i32 s73, 0x100
	s_cmp_ge_i32 s74, s3
	s_cbranch_scc0 .LBB0_1290
	s_and_b64 vcc, exec, s[38:39]
	s_cbranch_vccz .LBB0_1293

.LBB0_1382:
	ds_read_b128 v[144:147], v138
	ds_read_b128 v[148:151], v138 offset:1024
	ds_read_b128 v[152:155], v138 offset:2048
	ds_read_b128 v[156:159], v138 offset:3072
	ds_read_b128 v[160:163], v139
	ds_read_b128 v[164:167], v139 offset:1024
	ds_read_b128 v[168:171], v139 offset:2048
	ds_read_b128 v[172:175], v139 offset:3072
	s_add_i32 s14, s74, 0xffe80080
	s_cmp_eq_u32 s61, s76
	s_cselect_b32 s77, s72, s14
	s_cselect_b32 s79, s73, s75
	s_or_b32 s78, s77, 0x80
	s_add_i32 s14, s74, 0xfff80000
	s_mov_b32 m0, s62
	ds_read_b128 v[176:179], v140
	ds_read_b128 v[180:183], v140 offset:1024
	ds_read_b128 v[184:187], v140 offset:2048
	ds_read_b128 v[188:191], v140 offset:3072
	ds_read_b128 v[192:195], v140 offset:4096
	ds_read_b128 v[196:199], v140 offset:5120
	ds_read_b128 v[200:203], v140 offset:6144
	ds_read_b128 v[204:207], v140 offset:7168
	buffer_load_dwordx4 v136, s[16:19], s14 offen lds
	s_mov_b32 m0, s63
	s_nop 0
	buffer_load_dwordx4 v136, s[16:19], s74 offen lds
	s_waitcnt vmcnt(8)
	s_waitcnt lgkmcnt(0)
	s_setprio 1
	v_mfma_f32_16x16x32_bf16 v[118:121], v[144:147], v[176:179], v[118:121]
	s_barrier
	v_mfma_f32_16x16x32_bf16 v[118:121], v[148:151], v[180:183], v[118:121]
	v_mfma_f32_16x16x32_bf16 v[114:117], v[152:155], v[176:179], v[114:117]
	v_mfma_f32_16x16x32_bf16 v[114:117], v[156:159], v[180:183], v[114:117]
	v_mfma_f32_16x16x32_bf16 v[110:113], v[144:147], v[184:187], v[110:113]
	v_mfma_f32_16x16x32_bf16 v[110:113], v[148:151], v[188:191], v[110:113]
	v_mfma_f32_16x16x32_bf16 v[102:105], v[152:155], v[184:187], v[102:105]
	v_mfma_f32_16x16x32_bf16 v[102:105], v[156:159], v[188:191], v[102:105]
	v_mfma_f32_16x16x32_bf16 v[94:97], v[144:147], v[192:195], v[94:97]
	v_mfma_f32_16x16x32_bf16 v[94:97], v[148:151], v[196:199], v[94:97]
	v_mfma_f32_16x16x32_bf16 v[86:89], v[152:155], v[192:195], v[86:89]
	v_mfma_f32_16x16x32_bf16 v[86:89], v[156:159], v[196:199], v[86:89]
	v_mfma_f32_16x16x32_bf16 v[78:81], v[144:147], v[200:203], v[78:81]
	v_mfma_f32_16x16x32_bf16 v[78:81], v[148:151], v[204:207], v[78:81]
	v_mfma_f32_16x16x32_bf16 v[66:69], v[152:155], v[200:203], v[66:69]
	v_mfma_f32_16x16x32_bf16 v[66:69], v[156:159], v[204:207], v[66:69]
	v_mfma_f32_16x16x32_bf16 v[126:129], v[160:163], v[176:179], v[126:129]
	v_mfma_f32_16x16x32_bf16 v[126:129], v[164:167], v[180:183], v[126:129]
	v_mfma_f32_16x16x32_bf16 v[122:125], v[168:171], v[176:179], v[122:125]
	v_mfma_f32_16x16x32_bf16 v[122:125], v[172:175], v[180:183], v[122:125]
	v_mfma_f32_16x16x32_bf16 v[106:109], v[160:163], v[184:187], v[106:109]
	v_mfma_f32_16x16x32_bf16 v[106:109], v[164:167], v[188:191], v[106:109]
	v_mfma_f32_16x16x32_bf16 v[98:101], v[168:171], v[184:187], v[98:101]
	v_mfma_f32_16x16x32_bf16 v[98:101], v[172:175], v[188:191], v[98:101]
	v_mfma_f32_16x16x32_bf16 v[90:93], v[160:163], v[192:195], v[90:93]
	v_mfma_f32_16x16x32_bf16 v[90:93], v[164:167], v[196:199], v[90:93]
	v_mfma_f32_16x16x32_bf16 v[82:85], v[168:171], v[192:195], v[82:85]
	v_mfma_f32_16x16x32_bf16 v[82:85], v[172:175], v[196:199], v[82:85]
	v_mfma_f32_16x16x32_bf16 v[74:77], v[160:163], v[200:203], v[74:77]
	v_mfma_f32_16x16x32_bf16 v[74:77], v[164:167], v[204:207], v[74:77]
	v_mfma_f32_16x16x32_bf16 v[70:73], v[168:171], v[200:203], v[70:73]
	v_mfma_f32_16x16x32_bf16 v[70:73], v[172:175], v[204:207], v[70:73]
	s_setprio 0
	s_barrier
	s_mov_b32 m0, s45
	s_mov_b32 s14, s18
	s_mov_b32 s15, s19
	ds_read_b128 v[176:179], v140 offset:16384
	ds_read_b128 v[180:183], v140 offset:17408
	ds_read_b128 v[184:187], v140 offset:18432
	ds_read_b128 v[188:191], v140 offset:19456
	ds_read_b128 v[192:195], v140 offset:20480
	ds_read_b128 v[196:199], v140 offset:21504
	ds_read_b128 v[200:203], v140 offset:22528
	ds_read_b128 v[204:207], v140 offset:23552
	buffer_load_dwordx4 v137, s[12:15], s79 offen lds
	s_add_i32 s80, s79, 0x80000
	s_mov_b32 m0, s46
	s_nop 0
	buffer_load_dwordx4 v137, s[12:15], s80 offen lds
	s_add_i32 s80, s79, 0x100000
	s_mov_b32 m0, s47
	s_nop 0
	buffer_load_dwordx4 v137, s[12:15], s80 offen lds
	s_add_i32 s80, s79, 0x180000
	s_mov_b32 m0, s48
	s_nop 0
	buffer_load_dwordx4 v137, s[12:15], s80 offen lds
	s_mov_b32 m0, s44
	s_add_i32 s80, s77, 0x80000
	buffer_load_dwordx4 v136, s[16:19], s77 offen lds
	s_mov_b32 m0, s49
	s_nop 0
	buffer_load_dwordx4 v136, s[16:19], s80 offen lds
	s_waitcnt vmcnt(8)
	s_waitcnt lgkmcnt(0)
	s_setprio 1
	v_mfma_f32_16x16x32_bf16 v[62:65], v[144:147], v[176:179], v[62:65]
	s_barrier
	v_mfma_f32_16x16x32_bf16 v[62:65], v[148:151], v[180:183], v[62:65]
	v_mfma_f32_16x16x32_bf16 v[54:57], v[152:155], v[176:179], v[54:57]
	v_mfma_f32_16x16x32_bf16 v[54:57], v[156:159], v[180:183], v[54:57]
	v_mfma_f32_16x16x32_bf16 v[46:49], v[144:147], v[184:187], v[46:49]
	v_mfma_f32_16x16x32_bf16 v[46:49], v[148:151], v[188:191], v[46:49]
	v_mfma_f32_16x16x32_bf16 v[38:41], v[152:155], v[184:187], v[38:41]
	v_mfma_f32_16x16x32_bf16 v[38:41], v[156:159], v[188:191], v[38:41]
	v_mfma_f32_16x16x32_bf16 v[30:33], v[144:147], v[192:195], v[30:33]
	v_mfma_f32_16x16x32_bf16 v[30:33], v[148:151], v[196:199], v[30:33]
	v_mfma_f32_16x16x32_bf16 v[22:25], v[152:155], v[192:195], v[22:25]
	v_mfma_f32_16x16x32_bf16 v[22:25], v[156:159], v[196:199], v[22:25]
	v_mfma_f32_16x16x32_bf16 v[14:17], v[144:147], v[200:203], v[14:17]
	v_mfma_f32_16x16x32_bf16 v[14:17], v[148:151], v[204:207], v[14:17]
	v_mfma_f32_16x16x32_bf16 v[6:9], v[152:155], v[200:203], v[6:9]
	v_mfma_f32_16x16x32_bf16 v[6:9], v[156:159], v[204:207], v[6:9]
	v_mfma_f32_16x16x32_bf16 v[58:61], v[160:163], v[176:179], v[58:61]
	v_mfma_f32_16x16x32_bf16 v[58:61], v[164:167], v[180:183], v[58:61]
	v_mfma_f32_16x16x32_bf16 v[50:53], v[168:171], v[176:179], v[50:53]
	v_mfma_f32_16x16x32_bf16 v[50:53], v[172:175], v[180:183], v[50:53]
	v_mfma_f32_16x16x32_bf16 v[42:45], v[160:163], v[184:187], v[42:45]
	v_mfma_f32_16x16x32_bf16 v[42:45], v[164:167], v[188:191], v[42:45]
	v_mfma_f32_16x16x32_bf16 v[34:37], v[168:171], v[184:187], v[34:37]
	v_mfma_f32_16x16x32_bf16 v[34:37], v[172:175], v[188:191], v[34:37]
	v_mfma_f32_16x16x32_bf16 v[26:29], v[160:163], v[192:195], v[26:29]
	v_mfma_f32_16x16x32_bf16 v[26:29], v[164:167], v[196:199], v[26:29]
	v_mfma_f32_16x16x32_bf16 v[18:21], v[168:171], v[192:195], v[18:21]
	v_mfma_f32_16x16x32_bf16 v[18:21], v[172:175], v[196:199], v[18:21]
	v_mfma_f32_16x16x32_bf16 v[10:13], v[160:163], v[200:203], v[10:13]
	v_mfma_f32_16x16x32_bf16 v[10:13], v[164:167], v[204:207], v[10:13]
	v_mfma_f32_16x16x32_bf16 v[2:5], v[168:171], v[200:203], v[2:5]
	v_mfma_f32_16x16x32_bf16 v[2:5], v[172:175], v[204:207], v[2:5]
	s_setprio 0
	s_barrier
	ds_read_b128 v[144:147], v141
	ds_read_b128 v[148:151], v141 offset:1024
	ds_read_b128 v[152:155], v141 offset:2048
	ds_read_b128 v[156:159], v141 offset:3072
	ds_read_b128 v[160:163], v142
	ds_read_b128 v[164:167], v142 offset:1024
	ds_read_b128 v[168:171], v142 offset:2048
	ds_read_b128 v[172:175], v142 offset:3072
	s_mov_b32 m0, s50
	s_add_i32 s80, s77, 0x100000
	ds_read_b128 v[176:179], v140 offset:32768
	ds_read_b128 v[180:183], v140 offset:33792
	ds_read_b128 v[184:187], v140 offset:34816
	ds_read_b128 v[188:191], v140 offset:35840
	ds_read_b128 v[192:195], v140 offset:36864
	ds_read_b128 v[196:199], v140 offset:37888
	ds_read_b128 v[200:203], v140 offset:38912
	ds_read_b128 v[204:207], v140 offset:39936
	buffer_load_dwordx4 v136, s[16:19], s80 offen lds
	s_add_i32 s80, s77, 0x180000
	s_mov_b32 m0, s51
	s_nop 0
	buffer_load_dwordx4 v136, s[16:19], s80 offen lds
	s_waitcnt vmcnt(8)
	s_waitcnt lgkmcnt(0)
	s_setprio 1
	v_mfma_f32_16x16x32_bf16 v[118:121], v[144:147], v[176:179], v[118:121]
	s_barrier
	v_mfma_f32_16x16x32_bf16 v[118:121], v[148:151], v[180:183], v[118:121]
	v_mfma_f32_16x16x32_bf16 v[114:117], v[152:155], v[176:179], v[114:117]
	v_mfma_f32_16x16x32_bf16 v[114:117], v[156:159], v[180:183], v[114:117]
	v_mfma_f32_16x16x32_bf16 v[110:113], v[144:147], v[184:187], v[110:113]
	v_mfma_f32_16x16x32_bf16 v[110:113], v[148:151], v[188:191], v[110:113]
	v_mfma_f32_16x16x32_bf16 v[102:105], v[152:155], v[184:187], v[102:105]
	v_mfma_f32_16x16x32_bf16 v[102:105], v[156:159], v[188:191], v[102:105]
	v_mfma_f32_16x16x32_bf16 v[94:97], v[144:147], v[192:195], v[94:97]
	v_mfma_f32_16x16x32_bf16 v[94:97], v[148:151], v[196:199], v[94:97]
	v_mfma_f32_16x16x32_bf16 v[86:89], v[152:155], v[192:195], v[86:89]
	v_mfma_f32_16x16x32_bf16 v[86:89], v[156:159], v[196:199], v[86:89]
	v_mfma_f32_16x16x32_bf16 v[78:81], v[144:147], v[200:203], v[78:81]
	v_mfma_f32_16x16x32_bf16 v[78:81], v[148:151], v[204:207], v[78:81]
	v_mfma_f32_16x16x32_bf16 v[66:69], v[152:155], v[200:203], v[66:69]
	v_mfma_f32_16x16x32_bf16 v[66:69], v[156:159], v[204:207], v[66:69]
	v_mfma_f32_16x16x32_bf16 v[126:129], v[160:163], v[176:179], v[126:129]
	v_mfma_f32_16x16x32_bf16 v[126:129], v[164:167], v[180:183], v[126:129]
	v_mfma_f32_16x16x32_bf16 v[122:125], v[168:171], v[176:179], v[122:125]
	v_mfma_f32_16x16x32_bf16 v[122:125], v[172:175], v[180:183], v[122:125]
	v_mfma_f32_16x16x32_bf16 v[106:109], v[160:163], v[184:187], v[106:109]
	v_mfma_f32_16x16x32_bf16 v[106:109], v[164:167], v[188:191], v[106:109]
	v_mfma_f32_16x16x32_bf16 v[98:101], v[168:171], v[184:187], v[98:101]
	v_mfma_f32_16x16x32_bf16 v[98:101], v[172:175], v[188:191], v[98:101]
	v_mfma_f32_16x16x32_bf16 v[90:93], v[160:163], v[192:195], v[90:93]
	v_mfma_f32_16x16x32_bf16 v[90:93], v[164:167], v[196:199], v[90:93]
	v_mfma_f32_16x16x32_bf16 v[82:85], v[168:171], v[192:195], v[82:85]
	v_mfma_f32_16x16x32_bf16 v[82:85], v[172:175], v[196:199], v[82:85]
	v_mfma_f32_16x16x32_bf16 v[74:77], v[160:163], v[200:203], v[74:77]
	v_mfma_f32_16x16x32_bf16 v[74:77], v[164:167], v[204:207], v[74:77]
	v_mfma_f32_16x16x32_bf16 v[70:73], v[168:171], v[200:203], v[70:73]
	v_mfma_f32_16x16x32_bf16 v[70:73], v[172:175], v[204:207], v[70:73]
	s_setprio 0
	s_barrier
	s_mov_b32 m0, s53
	s_or_b32 s80, s79, 0x80
	ds_read_b128 v[176:179], v140 offset:49152
	ds_read_b128 v[180:183], v140 offset:50176
	ds_read_b128 v[184:187], v140 offset:51200
	ds_read_b128 v[188:191], v140 offset:52224
	ds_read_b128 v[192:195], v140 offset:53248
	ds_read_b128 v[196:199], v140 offset:54272
	ds_read_b128 v[200:203], v140 offset:55296
	ds_read_b128 v[204:207], v140 offset:56320
	buffer_load_dwordx4 v137, s[12:15], s80 offen lds
	s_add_i32 s80, s79, 0x80080
	s_mov_b32 m0, s54
	s_add_i32 s77, s77, 0x80080
	buffer_load_dwordx4 v137, s[12:15], s80 offen lds
	s_add_i32 s80, s79, 0x100080
	s_mov_b32 m0, s57
	s_add_i32 s79, s79, 0x180080
	buffer_load_dwordx4 v137, s[12:15], s80 offen lds
	s_mov_b32 m0, s58
	s_nop 0
	buffer_load_dwordx4 v137, s[12:15], s79 offen lds
	s_mov_b32 m0, s55
	s_nop 0
	buffer_load_dwordx4 v136, s[16:19], s78 offen lds
	s_mov_b32 m0, s56
	s_nop 0
	buffer_load_dwordx4 v136, s[16:19], s77 offen lds
	s_waitcnt vmcnt(8)
	s_waitcnt lgkmcnt(0)
	s_setprio 1
	v_mfma_f32_16x16x32_bf16 v[62:65], v[144:147], v[176:179], v[62:65]
	s_barrier
	v_mfma_f32_16x16x32_bf16 v[62:65], v[148:151], v[180:183], v[62:65]
	v_mfma_f32_16x16x32_bf16 v[54:57], v[152:155], v[176:179], v[54:57]
	v_mfma_f32_16x16x32_bf16 v[54:57], v[156:159], v[180:183], v[54:57]
	v_mfma_f32_16x16x32_bf16 v[46:49], v[144:147], v[184:187], v[46:49]
	v_mfma_f32_16x16x32_bf16 v[46:49], v[148:151], v[188:191], v[46:49]
	v_mfma_f32_16x16x32_bf16 v[38:41], v[152:155], v[184:187], v[38:41]
	v_mfma_f32_16x16x32_bf16 v[38:41], v[156:159], v[188:191], v[38:41]
	v_mfma_f32_16x16x32_bf16 v[30:33], v[144:147], v[192:195], v[30:33]
	v_mfma_f32_16x16x32_bf16 v[30:33], v[148:151], v[196:199], v[30:33]
	v_mfma_f32_16x16x32_bf16 v[22:25], v[152:155], v[192:195], v[22:25]
	v_mfma_f32_16x16x32_bf16 v[22:25], v[156:159], v[196:199], v[22:25]
	v_mfma_f32_16x16x32_bf16 v[14:17], v[144:147], v[200:203], v[14:17]
	v_mfma_f32_16x16x32_bf16 v[14:17], v[148:151], v[204:207], v[14:17]
	v_mfma_f32_16x16x32_bf16 v[6:9], v[152:155], v[200:203], v[6:9]
	v_mfma_f32_16x16x32_bf16 v[6:9], v[156:159], v[204:207], v[6:9]
	v_mfma_f32_16x16x32_bf16 v[58:61], v[160:163], v[176:179], v[58:61]
	v_mfma_f32_16x16x32_bf16 v[58:61], v[164:167], v[180:183], v[58:61]
	v_mfma_f32_16x16x32_bf16 v[50:53], v[168:171], v[176:179], v[50:53]
	v_mfma_f32_16x16x32_bf16 v[50:53], v[172:175], v[180:183], v[50:53]
	v_mfma_f32_16x16x32_bf16 v[42:45], v[160:163], v[184:187], v[42:45]
	v_mfma_f32_16x16x32_bf16 v[42:45], v[164:167], v[188:191], v[42:45]
	v_mfma_f32_16x16x32_bf16 v[34:37], v[168:171], v[184:187], v[34:37]
	v_mfma_f32_16x16x32_bf16 v[34:37], v[172:175], v[188:191], v[34:37]
	v_mfma_f32_16x16x32_bf16 v[26:29], v[160:163], v[192:195], v[26:29]
	v_mfma_f32_16x16x32_bf16 v[26:29], v[164:167], v[196:199], v[26:29]
	v_mfma_f32_16x16x32_bf16 v[18:21], v[168:171], v[192:195], v[18:21]
	v_mfma_f32_16x16x32_bf16 v[18:21], v[172:175], v[196:199], v[18:21]
	v_mfma_f32_16x16x32_bf16 v[10:13], v[160:163], v[200:203], v[10:13]
	v_mfma_f32_16x16x32_bf16 v[10:13], v[164:167], v[204:207], v[10:13]
	v_mfma_f32_16x16x32_bf16 v[2:5], v[168:171], v[200:203], v[2:5]
	v_mfma_f32_16x16x32_bf16 v[2:5], v[172:175], v[204:207], v[2:5]
	s_setprio 0
	s_barrier
	s_add_i32 s76, s76, 2
	s_addk_i32 s74, 0x100
	s_addk_i32 s75, 0x100
	s_cmp_ge_i32 s76, s27
	s_cbranch_scc0 .LBB0_1382
	s_and_b64 vcc, exec, s[42:43]
	s_cbranch_vccz .LBB0_1385

.LBB0_1402:
	ds_read_b128 v[146:149], v138
	ds_read_b128 v[150:153], v138 offset:1024
	ds_read_b128 v[154:157], v138 offset:2048
	ds_read_b128 v[158:161], v138 offset:3072
	ds_read_b128 v[162:165], v139
	ds_read_b128 v[166:169], v139 offset:1024
	ds_read_b128 v[170:173], v139 offset:2048
	ds_read_b128 v[174:177], v139 offset:3072
	s_add_i32 s22, s75, 0xffe80080
	s_cmp_eq_u32 s62, s77
	s_cselect_b32 s78, s73, s22
	s_cselect_b32 s80, s74, s76
	s_or_b32 s79, s78, 0x80
	s_add_i32 s22, s75, 0xfff80000
	s_mov_b32 m0, s63
	ds_read_b128 v[178:181], v140
	ds_read_b128 v[182:185], v140 offset:1024
	ds_read_b128 v[186:189], v140 offset:2048
	ds_read_b128 v[190:193], v140 offset:3072
	ds_read_b128 v[194:197], v140 offset:4096
	ds_read_b128 v[198:201], v140 offset:5120
	ds_read_b128 v[202:205], v140 offset:6144
	ds_read_b128 v[206:209], v140 offset:7168
	buffer_load_dwordx4 v136, s[16:19], s22 offen lds
	s_mov_b32 m0, s64
	s_nop 0
	buffer_load_dwordx4 v136, s[16:19], s75 offen lds
	s_waitcnt vmcnt(8)
	s_waitcnt lgkmcnt(0)
	s_setprio 1
	v_mfma_f32_16x16x32_bf16 v[118:121], v[146:149], v[178:181], v[118:121]
	s_barrier
	v_mfma_f32_16x16x32_bf16 v[118:121], v[150:153], v[182:185], v[118:121]
	v_mfma_f32_16x16x32_bf16 v[114:117], v[154:157], v[178:181], v[114:117]
	v_mfma_f32_16x16x32_bf16 v[114:117], v[158:161], v[182:185], v[114:117]
	v_mfma_f32_16x16x32_bf16 v[110:113], v[146:149], v[186:189], v[110:113]
	v_mfma_f32_16x16x32_bf16 v[110:113], v[150:153], v[190:193], v[110:113]
	v_mfma_f32_16x16x32_bf16 v[102:105], v[154:157], v[186:189], v[102:105]
	v_mfma_f32_16x16x32_bf16 v[102:105], v[158:161], v[190:193], v[102:105]
	v_mfma_f32_16x16x32_bf16 v[94:97], v[146:149], v[194:197], v[94:97]
	v_mfma_f32_16x16x32_bf16 v[94:97], v[150:153], v[198:201], v[94:97]
	v_mfma_f32_16x16x32_bf16 v[86:89], v[154:157], v[194:197], v[86:89]
	v_mfma_f32_16x16x32_bf16 v[86:89], v[158:161], v[198:201], v[86:89]
	v_mfma_f32_16x16x32_bf16 v[78:81], v[146:149], v[202:205], v[78:81]
	v_mfma_f32_16x16x32_bf16 v[78:81], v[150:153], v[206:209], v[78:81]
	v_mfma_f32_16x16x32_bf16 v[66:69], v[154:157], v[202:205], v[66:69]
	v_mfma_f32_16x16x32_bf16 v[66:69], v[158:161], v[206:209], v[66:69]
	v_mfma_f32_16x16x32_bf16 v[126:129], v[162:165], v[178:181], v[126:129]
	v_mfma_f32_16x16x32_bf16 v[126:129], v[166:169], v[182:185], v[126:129]
	v_mfma_f32_16x16x32_bf16 v[122:125], v[170:173], v[178:181], v[122:125]
	v_mfma_f32_16x16x32_bf16 v[122:125], v[174:177], v[182:185], v[122:125]
	v_mfma_f32_16x16x32_bf16 v[106:109], v[162:165], v[186:189], v[106:109]
	v_mfma_f32_16x16x32_bf16 v[106:109], v[166:169], v[190:193], v[106:109]
	v_mfma_f32_16x16x32_bf16 v[98:101], v[170:173], v[186:189], v[98:101]
	v_mfma_f32_16x16x32_bf16 v[98:101], v[174:177], v[190:193], v[98:101]
	v_mfma_f32_16x16x32_bf16 v[90:93], v[162:165], v[194:197], v[90:93]
	v_mfma_f32_16x16x32_bf16 v[90:93], v[166:169], v[198:201], v[90:93]
	v_mfma_f32_16x16x32_bf16 v[82:85], v[170:173], v[194:197], v[82:85]
	v_mfma_f32_16x16x32_bf16 v[82:85], v[174:177], v[198:201], v[82:85]
	v_mfma_f32_16x16x32_bf16 v[74:77], v[162:165], v[202:205], v[74:77]
	v_mfma_f32_16x16x32_bf16 v[74:77], v[166:169], v[206:209], v[74:77]
	v_mfma_f32_16x16x32_bf16 v[70:73], v[170:173], v[202:205], v[70:73]
	v_mfma_f32_16x16x32_bf16 v[70:73], v[174:177], v[206:209], v[70:73]
	s_setprio 0
	s_barrier
	s_mov_b32 m0, s31
	s_mov_b32 s22, s18
	s_mov_b32 s23, s19
	ds_read_b128 v[178:181], v140 offset:16384
	ds_read_b128 v[182:185], v140 offset:17408
	ds_read_b128 v[186:189], v140 offset:18432
	ds_read_b128 v[190:193], v140 offset:19456
	ds_read_b128 v[194:197], v140 offset:20480
	ds_read_b128 v[198:201], v140 offset:21504
	ds_read_b128 v[202:205], v140 offset:22528
	ds_read_b128 v[206:209], v140 offset:23552
	buffer_load_dwordx4 v137, s[20:23], s80 offen lds
	s_add_i32 s81, s80, 0x80000
	s_mov_b32 m0, s48
	s_nop 0
	buffer_load_dwordx4 v137, s[20:23], s81 offen lds
	s_add_i32 s81, s80, 0x100000
	s_mov_b32 m0, s49
	s_nop 0
	buffer_load_dwordx4 v137, s[20:23], s81 offen lds
	s_add_i32 s81, s80, 0x180000
	s_mov_b32 m0, s50
	s_nop 0
	buffer_load_dwordx4 v137, s[20:23], s81 offen lds
	s_mov_b32 m0, s30
	s_add_i32 s81, s78, 0x80000
	buffer_load_dwordx4 v136, s[16:19], s78 offen lds
	s_mov_b32 m0, s51
	s_nop 0
	buffer_load_dwordx4 v136, s[16:19], s81 offen lds
	s_waitcnt vmcnt(8)
	s_waitcnt lgkmcnt(0)
	s_setprio 1
	v_mfma_f32_16x16x32_bf16 v[62:65], v[146:149], v[178:181], v[62:65]
	s_barrier
	v_mfma_f32_16x16x32_bf16 v[62:65], v[150:153], v[182:185], v[62:65]
	v_mfma_f32_16x16x32_bf16 v[54:57], v[154:157], v[178:181], v[54:57]
	v_mfma_f32_16x16x32_bf16 v[54:57], v[158:161], v[182:185], v[54:57]
	v_mfma_f32_16x16x32_bf16 v[46:49], v[146:149], v[186:189], v[46:49]
	v_mfma_f32_16x16x32_bf16 v[46:49], v[150:153], v[190:193], v[46:49]
	v_mfma_f32_16x16x32_bf16 v[38:41], v[154:157], v[186:189], v[38:41]
	v_mfma_f32_16x16x32_bf16 v[38:41], v[158:161], v[190:193], v[38:41]
	v_mfma_f32_16x16x32_bf16 v[30:33], v[146:149], v[194:197], v[30:33]
	v_mfma_f32_16x16x32_bf16 v[30:33], v[150:153], v[198:201], v[30:33]
	v_mfma_f32_16x16x32_bf16 v[22:25], v[154:157], v[194:197], v[22:25]
	v_mfma_f32_16x16x32_bf16 v[22:25], v[158:161], v[198:201], v[22:25]
	v_mfma_f32_16x16x32_bf16 v[14:17], v[146:149], v[202:205], v[14:17]
	v_mfma_f32_16x16x32_bf16 v[14:17], v[150:153], v[206:209], v[14:17]
	v_mfma_f32_16x16x32_bf16 v[6:9], v[154:157], v[202:205], v[6:9]
	v_mfma_f32_16x16x32_bf16 v[6:9], v[158:161], v[206:209], v[6:9]
	v_mfma_f32_16x16x32_bf16 v[58:61], v[162:165], v[178:181], v[58:61]
	v_mfma_f32_16x16x32_bf16 v[58:61], v[166:169], v[182:185], v[58:61]
	v_mfma_f32_16x16x32_bf16 v[50:53], v[170:173], v[178:181], v[50:53]
	v_mfma_f32_16x16x32_bf16 v[50:53], v[174:177], v[182:185], v[50:53]
	v_mfma_f32_16x16x32_bf16 v[42:45], v[162:165], v[186:189], v[42:45]
	v_mfma_f32_16x16x32_bf16 v[42:45], v[166:169], v[190:193], v[42:45]
	v_mfma_f32_16x16x32_bf16 v[34:37], v[170:173], v[186:189], v[34:37]
	v_mfma_f32_16x16x32_bf16 v[34:37], v[174:177], v[190:193], v[34:37]
	v_mfma_f32_16x16x32_bf16 v[26:29], v[162:165], v[194:197], v[26:29]
	v_mfma_f32_16x16x32_bf16 v[26:29], v[166:169], v[198:201], v[26:29]
	v_mfma_f32_16x16x32_bf16 v[18:21], v[170:173], v[194:197], v[18:21]
	v_mfma_f32_16x16x32_bf16 v[18:21], v[174:177], v[198:201], v[18:21]
	v_mfma_f32_16x16x32_bf16 v[10:13], v[162:165], v[202:205], v[10:13]
	v_mfma_f32_16x16x32_bf16 v[10:13], v[166:169], v[206:209], v[10:13]
	v_mfma_f32_16x16x32_bf16 v[2:5], v[170:173], v[202:205], v[2:5]
	v_mfma_f32_16x16x32_bf16 v[2:5], v[174:177], v[206:209], v[2:5]
	s_setprio 0
	s_barrier
	ds_read_b128 v[146:149], v141
	ds_read_b128 v[150:153], v141 offset:1024
	ds_read_b128 v[154:157], v141 offset:2048
	ds_read_b128 v[158:161], v141 offset:3072
	ds_read_b128 v[162:165], v142
	ds_read_b128 v[166:169], v142 offset:1024
	ds_read_b128 v[170:173], v142 offset:2048
	ds_read_b128 v[174:177], v142 offset:3072
	s_mov_b32 m0, s52
	s_add_i32 s81, s78, 0x100000
	ds_read_b128 v[178:181], v140 offset:32768
	ds_read_b128 v[182:185], v140 offset:33792
	ds_read_b128 v[186:189], v140 offset:34816
	ds_read_b128 v[190:193], v140 offset:35840
	ds_read_b128 v[194:197], v140 offset:36864
	ds_read_b128 v[198:201], v140 offset:37888
	ds_read_b128 v[202:205], v140 offset:38912
	ds_read_b128 v[206:209], v140 offset:39936
	buffer_load_dwordx4 v136, s[16:19], s81 offen lds
	s_add_i32 s81, s78, 0x180000
	s_mov_b32 m0, s53
	s_nop 0
	buffer_load_dwordx4 v136, s[16:19], s81 offen lds
	s_waitcnt vmcnt(8)
	s_waitcnt lgkmcnt(0)
	s_setprio 1
	v_mfma_f32_16x16x32_bf16 v[118:121], v[146:149], v[178:181], v[118:121]
	s_barrier
	v_mfma_f32_16x16x32_bf16 v[118:121], v[150:153], v[182:185], v[118:121]
	v_mfma_f32_16x16x32_bf16 v[114:117], v[154:157], v[178:181], v[114:117]
	v_mfma_f32_16x16x32_bf16 v[114:117], v[158:161], v[182:185], v[114:117]
	v_mfma_f32_16x16x32_bf16 v[110:113], v[146:149], v[186:189], v[110:113]
	v_mfma_f32_16x16x32_bf16 v[110:113], v[150:153], v[190:193], v[110:113]
	v_mfma_f32_16x16x32_bf16 v[102:105], v[154:157], v[186:189], v[102:105]
	v_mfma_f32_16x16x32_bf16 v[102:105], v[158:161], v[190:193], v[102:105]
	v_mfma_f32_16x16x32_bf16 v[94:97], v[146:149], v[194:197], v[94:97]
	v_mfma_f32_16x16x32_bf16 v[94:97], v[150:153], v[198:201], v[94:97]
	v_mfma_f32_16x16x32_bf16 v[86:89], v[154:157], v[194:197], v[86:89]
	v_mfma_f32_16x16x32_bf16 v[86:89], v[158:161], v[198:201], v[86:89]
	v_mfma_f32_16x16x32_bf16 v[78:81], v[146:149], v[202:205], v[78:81]
	v_mfma_f32_16x16x32_bf16 v[78:81], v[150:153], v[206:209], v[78:81]
	v_mfma_f32_16x16x32_bf16 v[66:69], v[154:157], v[202:205], v[66:69]
	v_mfma_f32_16x16x32_bf16 v[66:69], v[158:161], v[206:209], v[66:69]
	v_mfma_f32_16x16x32_bf16 v[126:129], v[162:165], v[178:181], v[126:129]
	v_mfma_f32_16x16x32_bf16 v[126:129], v[166:169], v[182:185], v[126:129]
	v_mfma_f32_16x16x32_bf16 v[122:125], v[170:173], v[178:181], v[122:125]
	v_mfma_f32_16x16x32_bf16 v[122:125], v[174:177], v[182:185], v[122:125]
	v_mfma_f32_16x16x32_bf16 v[106:109], v[162:165], v[186:189], v[106:109]
	v_mfma_f32_16x16x32_bf16 v[106:109], v[166:169], v[190:193], v[106:109]
	v_mfma_f32_16x16x32_bf16 v[98:101], v[170:173], v[186:189], v[98:101]
	v_mfma_f32_16x16x32_bf16 v[98:101], v[174:177], v[190:193], v[98:101]
	v_mfma_f32_16x16x32_bf16 v[90:93], v[162:165], v[194:197], v[90:93]
	v_mfma_f32_16x16x32_bf16 v[90:93], v[166:169], v[198:201], v[90:93]
	v_mfma_f32_16x16x32_bf16 v[82:85], v[170:173], v[194:197], v[82:85]
	v_mfma_f32_16x16x32_bf16 v[82:85], v[174:177], v[198:201], v[82:85]
	v_mfma_f32_16x16x32_bf16 v[74:77], v[162:165], v[202:205], v[74:77]
	v_mfma_f32_16x16x32_bf16 v[74:77], v[166:169], v[206:209], v[74:77]
	v_mfma_f32_16x16x32_bf16 v[70:73], v[170:173], v[202:205], v[70:73]
	v_mfma_f32_16x16x32_bf16 v[70:73], v[174:177], v[206:209], v[70:73]
	s_setprio 0
	s_barrier
	s_mov_b32 m0, s54
	s_or_b32 s81, s80, 0x80
	ds_read_b128 v[178:181], v140 offset:49152
	ds_read_b128 v[182:185], v140 offset:50176
	ds_read_b128 v[186:189], v140 offset:51200
	ds_read_b128 v[190:193], v140 offset:52224
	ds_read_b128 v[194:197], v140 offset:53248
	ds_read_b128 v[198:201], v140 offset:54272
	ds_read_b128 v[202:205], v140 offset:55296
	ds_read_b128 v[206:209], v140 offset:56320
	buffer_load_dwordx4 v137, s[20:23], s81 offen lds
	s_add_i32 s81, s80, 0x80080
	s_mov_b32 m0, s55
	s_add_i32 s78, s78, 0x80080
	buffer_load_dwordx4 v137, s[20:23], s81 offen lds
	s_add_i32 s81, s80, 0x100080
	s_mov_b32 m0, s58
	s_add_i32 s80, s80, 0x180080
	buffer_load_dwordx4 v137, s[20:23], s81 offen lds
	s_mov_b32 m0, s59
	s_nop 0
	buffer_load_dwordx4 v137, s[20:23], s80 offen lds
	s_mov_b32 m0, s56
	s_nop 0
	buffer_load_dwordx4 v136, s[16:19], s79 offen lds
	s_mov_b32 m0, s57
	s_nop 0
	buffer_load_dwordx4 v136, s[16:19], s78 offen lds
	s_waitcnt vmcnt(8)
	s_waitcnt lgkmcnt(0)
	s_setprio 1
	v_mfma_f32_16x16x32_bf16 v[62:65], v[146:149], v[178:181], v[62:65]
	s_barrier
	v_mfma_f32_16x16x32_bf16 v[62:65], v[150:153], v[182:185], v[62:65]
	v_mfma_f32_16x16x32_bf16 v[54:57], v[154:157], v[178:181], v[54:57]
	v_mfma_f32_16x16x32_bf16 v[54:57], v[158:161], v[182:185], v[54:57]
	v_mfma_f32_16x16x32_bf16 v[46:49], v[146:149], v[186:189], v[46:49]
	v_mfma_f32_16x16x32_bf16 v[46:49], v[150:153], v[190:193], v[46:49]
	v_mfma_f32_16x16x32_bf16 v[38:41], v[154:157], v[186:189], v[38:41]
	v_mfma_f32_16x16x32_bf16 v[38:41], v[158:161], v[190:193], v[38:41]
	v_mfma_f32_16x16x32_bf16 v[30:33], v[146:149], v[194:197], v[30:33]
	v_mfma_f32_16x16x32_bf16 v[30:33], v[150:153], v[198:201], v[30:33]
	v_mfma_f32_16x16x32_bf16 v[22:25], v[154:157], v[194:197], v[22:25]
	v_mfma_f32_16x16x32_bf16 v[22:25], v[158:161], v[198:201], v[22:25]
	v_mfma_f32_16x16x32_bf16 v[14:17], v[146:149], v[202:205], v[14:17]
	v_mfma_f32_16x16x32_bf16 v[14:17], v[150:153], v[206:209], v[14:17]
	v_mfma_f32_16x16x32_bf16 v[6:9], v[154:157], v[202:205], v[6:9]
	v_mfma_f32_16x16x32_bf16 v[6:9], v[158:161], v[206:209], v[6:9]
	v_mfma_f32_16x16x32_bf16 v[58:61], v[162:165], v[178:181], v[58:61]
	v_mfma_f32_16x16x32_bf16 v[58:61], v[166:169], v[182:185], v[58:61]
	v_mfma_f32_16x16x32_bf16 v[50:53], v[170:173], v[178:181], v[50:53]
	v_mfma_f32_16x16x32_bf16 v[50:53], v[174:177], v[182:185], v[50:53]
	v_mfma_f32_16x16x32_bf16 v[42:45], v[162:165], v[186:189], v[42:45]
	v_mfma_f32_16x16x32_bf16 v[42:45], v[166:169], v[190:193], v[42:45]
	v_mfma_f32_16x16x32_bf16 v[34:37], v[170:173], v[186:189], v[34:37]
	v_mfma_f32_16x16x32_bf16 v[34:37], v[174:177], v[190:193], v[34:37]
	v_mfma_f32_16x16x32_bf16 v[26:29], v[162:165], v[194:197], v[26:29]
	v_mfma_f32_16x16x32_bf16 v[26:29], v[166:169], v[198:201], v[26:29]
	v_mfma_f32_16x16x32_bf16 v[18:21], v[170:173], v[194:197], v[18:21]
	v_mfma_f32_16x16x32_bf16 v[18:21], v[174:177], v[198:201], v[18:21]
	v_mfma_f32_16x16x32_bf16 v[10:13], v[162:165], v[202:205], v[10:13]
	v_mfma_f32_16x16x32_bf16 v[10:13], v[166:169], v[206:209], v[10:13]
	v_mfma_f32_16x16x32_bf16 v[2:5], v[170:173], v[202:205], v[2:5]
	v_mfma_f32_16x16x32_bf16 v[2:5], v[174:177], v[206:209], v[2:5]
	s_setprio 0
	s_barrier
	s_add_i32 s77, s77, 2
	s_addk_i32 s75, 0x100
	s_addk_i32 s76, 0x100
	s_cmp_ge_i32 s77, s13
	s_cbranch_scc0 .LBB0_1402
	s_and_b64 vcc, exec, s[46:47]
	s_cbranch_vccz .LBB0_1405

.LBB0_1519:
	ds_read_b128 v[134:137], v208
	ds_read_b128 v[138:141], v208 offset:1024
	ds_read_b128 v[142:145], v208 offset:2048
	ds_read_b128 v[146:149], v208 offset:3072
	ds_read_b128 v[150:153], v209
	ds_read_b128 v[154:157], v209 offset:1024
	ds_read_b128 v[158:161], v209 offset:2048
	ds_read_b128 v[162:165], v209 offset:3072
	s_add_i32 s18, s80, 0xffbf8080
	s_cmp_eq_u32 s65, s82
	s_cselect_b32 s83, s6, s18
	s_cselect_b32 s85, s7, s81
	s_or_b32 s84, s83, 0x80
	s_add_i32 s18, s80, 0xffea8000
	s_mov_b32 m0, s66
	ds_read_b128 v[166:169], v210
	ds_read_b128 v[170:173], v210 offset:1024
	ds_read_b128 v[174:177], v210 offset:2048
	ds_read_b128 v[178:181], v210 offset:3072
	ds_read_b128 v[182:185], v210 offset:4096
	ds_read_b128 v[186:189], v210 offset:5120
	ds_read_b128 v[190:193], v210 offset:6144
	ds_read_b128 v[194:197], v210 offset:7168
	buffer_load_dwordx4 v206, s[12:15], s18 offen lds
	s_mov_b32 m0, s69
	s_nop 0
	buffer_load_dwordx4 v206, s[12:15], s80 offen lds
	s_waitcnt vmcnt(8)
	s_waitcnt lgkmcnt(0)
	s_setprio 1
	v_mfma_f32_16x16x32_bf16 v[126:129], v[134:137], v[166:169], v[126:129]
	s_barrier
	v_mfma_f32_16x16x32_bf16 v[126:129], v[138:141], v[170:173], v[126:129]
	v_mfma_f32_16x16x32_bf16 v[122:125], v[142:145], v[166:169], v[122:125]
	v_mfma_f32_16x16x32_bf16 v[122:125], v[146:149], v[170:173], v[122:125]
	v_mfma_f32_16x16x32_bf16 v[118:121], v[134:137], v[174:177], v[118:121]
	v_mfma_f32_16x16x32_bf16 v[118:121], v[138:141], v[178:181], v[118:121]
	v_mfma_f32_16x16x32_bf16 v[114:117], v[142:145], v[174:177], v[114:117]
	v_mfma_f32_16x16x32_bf16 v[114:117], v[146:149], v[178:181], v[114:117]
	v_mfma_f32_16x16x32_bf16 v[106:109], v[134:137], v[182:185], v[106:109]
	v_mfma_f32_16x16x32_bf16 v[106:109], v[138:141], v[186:189], v[106:109]
	v_mfma_f32_16x16x32_bf16 v[98:101], v[142:145], v[182:185], v[98:101]
	v_mfma_f32_16x16x32_bf16 v[98:101], v[146:149], v[186:189], v[98:101]
	v_mfma_f32_16x16x32_bf16 v[90:93], v[134:137], v[190:193], v[90:93]
	v_mfma_f32_16x16x32_bf16 v[90:93], v[138:141], v[194:197], v[90:93]
	v_mfma_f32_16x16x32_bf16 v[82:85], v[142:145], v[190:193], v[82:85]
	v_mfma_f32_16x16x32_bf16 v[82:85], v[146:149], v[194:197], v[82:85]
	v_mfma_f32_16x16x32_bf16 v[110:113], v[150:153], v[166:169], v[110:113]
	v_mfma_f32_16x16x32_bf16 v[110:113], v[154:157], v[170:173], v[110:113]
	v_mfma_f32_16x16x32_bf16 v[102:105], v[158:161], v[166:169], v[102:105]
	v_mfma_f32_16x16x32_bf16 v[102:105], v[162:165], v[170:173], v[102:105]
	v_mfma_f32_16x16x32_bf16 v[94:97], v[150:153], v[174:177], v[94:97]
	v_mfma_f32_16x16x32_bf16 v[94:97], v[154:157], v[178:181], v[94:97]
	v_mfma_f32_16x16x32_bf16 v[86:89], v[158:161], v[174:177], v[86:89]
	v_mfma_f32_16x16x32_bf16 v[86:89], v[162:165], v[178:181], v[86:89]
	v_mfma_f32_16x16x32_bf16 v[78:81], v[150:153], v[182:185], v[78:81]
	v_mfma_f32_16x16x32_bf16 v[78:81], v[154:157], v[186:189], v[78:81]
	v_mfma_f32_16x16x32_bf16 v[74:77], v[158:161], v[182:185], v[74:77]
	v_mfma_f32_16x16x32_bf16 v[74:77], v[162:165], v[186:189], v[74:77]
	v_mfma_f32_16x16x32_bf16 v[70:73], v[150:153], v[190:193], v[70:73]
	v_mfma_f32_16x16x32_bf16 v[70:73], v[154:157], v[194:197], v[70:73]
	v_mfma_f32_16x16x32_bf16 v[66:69], v[158:161], v[190:193], v[66:69]
	v_mfma_f32_16x16x32_bf16 v[66:69], v[162:165], v[194:197], v[66:69]
	s_setprio 0
	s_barrier
	s_mov_b32 m0, s27
	s_mov_b32 s18, s14
	s_mov_b32 s19, s15
	ds_read_b128 v[166:169], v210 offset:16384
	ds_read_b128 v[170:173], v210 offset:17408
	ds_read_b128 v[174:177], v210 offset:18432
	ds_read_b128 v[178:181], v210 offset:19456
	ds_read_b128 v[182:185], v210 offset:20480
	ds_read_b128 v[186:189], v210 offset:21504
	ds_read_b128 v[190:193], v210 offset:22528
	ds_read_b128 v[194:197], v210 offset:23552
	buffer_load_dwordx4 v207, s[16:19], s85 offen lds
	s_add_i32 s86, s85, 0x158000
	s_mov_b32 m0, s30
	s_nop 0
	buffer_load_dwordx4 v207, s[16:19], s86 offen lds
	s_add_i32 s86, s85, 0x2b0000
	s_mov_b32 m0, s31
	s_nop 0
	buffer_load_dwordx4 v207, s[16:19], s86 offen lds
	s_add_i32 s86, s85, 0x408000
	s_mov_b32 m0, s50
	s_nop 0
	buffer_load_dwordx4 v207, s[16:19], s86 offen lds
	s_mov_b32 m0, s25
	s_add_i32 s86, s83, 0x158000
	buffer_load_dwordx4 v206, s[12:15], s83 offen lds
	s_mov_b32 m0, s51
	s_nop 0
	buffer_load_dwordx4 v206, s[12:15], s86 offen lds
	s_waitcnt vmcnt(8)
	s_waitcnt lgkmcnt(0)
	s_setprio 1
	v_mfma_f32_16x16x32_bf16 v[62:65], v[134:137], v[166:169], v[62:65]
	s_barrier
	v_mfma_f32_16x16x32_bf16 v[62:65], v[138:141], v[170:173], v[62:65]
	v_mfma_f32_16x16x32_bf16 v[58:61], v[142:145], v[166:169], v[58:61]
	v_mfma_f32_16x16x32_bf16 v[58:61], v[146:149], v[170:173], v[58:61]
	v_mfma_f32_16x16x32_bf16 v[54:57], v[134:137], v[174:177], v[54:57]
	v_mfma_f32_16x16x32_bf16 v[54:57], v[138:141], v[178:181], v[54:57]
	v_mfma_f32_16x16x32_bf16 v[50:53], v[142:145], v[174:177], v[50:53]
	v_mfma_f32_16x16x32_bf16 v[50:53], v[146:149], v[178:181], v[50:53]
	v_mfma_f32_16x16x32_bf16 v[42:45], v[134:137], v[182:185], v[42:45]
	v_mfma_f32_16x16x32_bf16 v[42:45], v[138:141], v[186:189], v[42:45]
	v_mfma_f32_16x16x32_bf16 v[34:37], v[142:145], v[182:185], v[34:37]
	v_mfma_f32_16x16x32_bf16 v[34:37], v[146:149], v[186:189], v[34:37]
	v_mfma_f32_16x16x32_bf16 v[26:29], v[134:137], v[190:193], v[26:29]
	v_mfma_f32_16x16x32_bf16 v[26:29], v[138:141], v[194:197], v[26:29]
	v_mfma_f32_16x16x32_bf16 v[18:21], v[142:145], v[190:193], v[18:21]
	v_mfma_f32_16x16x32_bf16 v[18:21], v[146:149], v[194:197], v[18:21]
	v_mfma_f32_16x16x32_bf16 v[46:49], v[150:153], v[166:169], v[46:49]
	v_mfma_f32_16x16x32_bf16 v[46:49], v[154:157], v[170:173], v[46:49]
	v_mfma_f32_16x16x32_bf16 v[38:41], v[158:161], v[166:169], v[38:41]
	v_mfma_f32_16x16x32_bf16 v[38:41], v[162:165], v[170:173], v[38:41]
	v_mfma_f32_16x16x32_bf16 v[30:33], v[150:153], v[174:177], v[30:33]
	v_mfma_f32_16x16x32_bf16 v[30:33], v[154:157], v[178:181], v[30:33]
	v_mfma_f32_16x16x32_bf16 v[22:25], v[158:161], v[174:177], v[22:25]
	v_mfma_f32_16x16x32_bf16 v[22:25], v[162:165], v[178:181], v[22:25]
	v_mfma_f32_16x16x32_bf16 v[14:17], v[150:153], v[182:185], v[14:17]
	v_mfma_f32_16x16x32_bf16 v[14:17], v[154:157], v[186:189], v[14:17]
	v_mfma_f32_16x16x32_bf16 v[10:13], v[158:161], v[182:185], v[10:13]
	v_mfma_f32_16x16x32_bf16 v[10:13], v[162:165], v[186:189], v[10:13]
	v_mfma_f32_16x16x32_bf16 v[6:9], v[150:153], v[190:193], v[6:9]
	v_mfma_f32_16x16x32_bf16 v[6:9], v[154:157], v[194:197], v[6:9]
	v_mfma_f32_16x16x32_bf16 v[2:5], v[158:161], v[190:193], v[2:5]
	v_mfma_f32_16x16x32_bf16 v[2:5], v[162:165], v[194:197], v[2:5]
	s_setprio 0
	s_barrier
	ds_read_b128 v[134:137], v211
	ds_read_b128 v[138:141], v211 offset:1024
	ds_read_b128 v[142:145], v211 offset:2048
	ds_read_b128 v[146:149], v211 offset:3072
	ds_read_b128 v[150:153], v212
	ds_read_b128 v[154:157], v212 offset:1024
	ds_read_b128 v[158:161], v212 offset:2048
	ds_read_b128 v[162:165], v212 offset:3072
	s_mov_b32 m0, s52
	s_add_i32 s86, s83, 0x2b0000
	ds_read_b128 v[166:169], v210 offset:32768
	ds_read_b128 v[170:173], v210 offset:33792
	ds_read_b128 v[174:177], v210 offset:34816
	ds_read_b128 v[178:181], v210 offset:35840
	ds_read_b128 v[182:185], v210 offset:36864
	ds_read_b128 v[186:189], v210 offset:37888
	ds_read_b128 v[190:193], v210 offset:38912
	ds_read_b128 v[194:197], v210 offset:39936
	buffer_load_dwordx4 v206, s[12:15], s86 offen lds
	s_add_i32 s86, s83, 0x408000
	s_mov_b32 m0, s53
	s_nop 0
	buffer_load_dwordx4 v206, s[12:15], s86 offen lds
	s_waitcnt vmcnt(8)
	s_waitcnt lgkmcnt(0)
	s_setprio 1
	v_mfma_f32_16x16x32_bf16 v[126:129], v[134:137], v[166:169], v[126:129]
	s_barrier
	v_mfma_f32_16x16x32_bf16 v[126:129], v[138:141], v[170:173], v[126:129]
	v_mfma_f32_16x16x32_bf16 v[122:125], v[142:145], v[166:169], v[122:125]
	v_mfma_f32_16x16x32_bf16 v[122:125], v[146:149], v[170:173], v[122:125]
	v_mfma_f32_16x16x32_bf16 v[118:121], v[134:137], v[174:177], v[118:121]
	v_mfma_f32_16x16x32_bf16 v[118:121], v[138:141], v[178:181], v[118:121]
	v_mfma_f32_16x16x32_bf16 v[114:117], v[142:145], v[174:177], v[114:117]
	v_mfma_f32_16x16x32_bf16 v[114:117], v[146:149], v[178:181], v[114:117]
	v_mfma_f32_16x16x32_bf16 v[106:109], v[134:137], v[182:185], v[106:109]
	v_mfma_f32_16x16x32_bf16 v[106:109], v[138:141], v[186:189], v[106:109]
	v_mfma_f32_16x16x32_bf16 v[98:101], v[142:145], v[182:185], v[98:101]
	v_mfma_f32_16x16x32_bf16 v[98:101], v[146:149], v[186:189], v[98:101]
	v_mfma_f32_16x16x32_bf16 v[90:93], v[134:137], v[190:193], v[90:93]
	v_mfma_f32_16x16x32_bf16 v[90:93], v[138:141], v[194:197], v[90:93]
	v_mfma_f32_16x16x32_bf16 v[82:85], v[142:145], v[190:193], v[82:85]
	v_mfma_f32_16x16x32_bf16 v[82:85], v[146:149], v[194:197], v[82:85]
	v_mfma_f32_16x16x32_bf16 v[110:113], v[150:153], v[166:169], v[110:113]
	v_mfma_f32_16x16x32_bf16 v[110:113], v[154:157], v[170:173], v[110:113]
	v_mfma_f32_16x16x32_bf16 v[102:105], v[158:161], v[166:169], v[102:105]
	v_mfma_f32_16x16x32_bf16 v[102:105], v[162:165], v[170:173], v[102:105]
	v_mfma_f32_16x16x32_bf16 v[94:97], v[150:153], v[174:177], v[94:97]
	v_mfma_f32_16x16x32_bf16 v[94:97], v[154:157], v[178:181], v[94:97]
	v_mfma_f32_16x16x32_bf16 v[86:89], v[158:161], v[174:177], v[86:89]
	v_mfma_f32_16x16x32_bf16 v[86:89], v[162:165], v[178:181], v[86:89]
	v_mfma_f32_16x16x32_bf16 v[78:81], v[150:153], v[182:185], v[78:81]
	v_mfma_f32_16x16x32_bf16 v[78:81], v[154:157], v[186:189], v[78:81]
	v_mfma_f32_16x16x32_bf16 v[74:77], v[158:161], v[182:185], v[74:77]
	v_mfma_f32_16x16x32_bf16 v[74:77], v[162:165], v[186:189], v[74:77]
	v_mfma_f32_16x16x32_bf16 v[70:73], v[150:153], v[190:193], v[70:73]
	v_mfma_f32_16x16x32_bf16 v[70:73], v[154:157], v[194:197], v[70:73]
	v_mfma_f32_16x16x32_bf16 v[66:69], v[158:161], v[190:193], v[66:69]
	v_mfma_f32_16x16x32_bf16 v[66:69], v[162:165], v[194:197], v[66:69]
	s_setprio 0
	s_barrier
	s_mov_b32 m0, s57
	s_or_b32 s86, s85, 0x80
	ds_read_b128 v[166:169], v210 offset:49152
	ds_read_b128 v[170:173], v210 offset:50176
	ds_read_b128 v[174:177], v210 offset:51200
	ds_read_b128 v[178:181], v210 offset:52224
	ds_read_b128 v[182:185], v210 offset:53248
	ds_read_b128 v[186:189], v210 offset:54272
	ds_read_b128 v[190:193], v210 offset:55296
	ds_read_b128 v[194:197], v210 offset:56320
	buffer_load_dwordx4 v207, s[16:19], s86 offen lds
	s_add_i32 s86, s85, 0x158080
	s_mov_b32 m0, s58
	s_add_i32 s83, s83, 0x158080
	buffer_load_dwordx4 v207, s[16:19], s86 offen lds
	s_add_i32 s86, s85, 0x2b0080
	s_mov_b32 m0, s61
	s_add_i32 s85, s85, 0x408080
	buffer_load_dwordx4 v207, s[16:19], s86 offen lds
	s_mov_b32 m0, s62
	s_nop 0
	buffer_load_dwordx4 v207, s[16:19], s85 offen lds
	s_mov_b32 m0, s59
	s_nop 0
	buffer_load_dwordx4 v206, s[12:15], s84 offen lds
	s_mov_b32 m0, s60
	s_nop 0
	buffer_load_dwordx4 v206, s[12:15], s83 offen lds
	s_waitcnt vmcnt(8)
	s_waitcnt lgkmcnt(0)
	s_setprio 1
	v_mfma_f32_16x16x32_bf16 v[62:65], v[134:137], v[166:169], v[62:65]
	s_barrier
	v_mfma_f32_16x16x32_bf16 v[62:65], v[138:141], v[170:173], v[62:65]
	v_mfma_f32_16x16x32_bf16 v[58:61], v[142:145], v[166:169], v[58:61]
	v_mfma_f32_16x16x32_bf16 v[58:61], v[146:149], v[170:173], v[58:61]
	v_mfma_f32_16x16x32_bf16 v[54:57], v[134:137], v[174:177], v[54:57]
	v_mfma_f32_16x16x32_bf16 v[54:57], v[138:141], v[178:181], v[54:57]
	v_mfma_f32_16x16x32_bf16 v[50:53], v[142:145], v[174:177], v[50:53]
	v_mfma_f32_16x16x32_bf16 v[50:53], v[146:149], v[178:181], v[50:53]
	v_mfma_f32_16x16x32_bf16 v[42:45], v[134:137], v[182:185], v[42:45]
	v_mfma_f32_16x16x32_bf16 v[42:45], v[138:141], v[186:189], v[42:45]
	v_mfma_f32_16x16x32_bf16 v[34:37], v[142:145], v[182:185], v[34:37]
	v_mfma_f32_16x16x32_bf16 v[34:37], v[146:149], v[186:189], v[34:37]
	v_mfma_f32_16x16x32_bf16 v[26:29], v[134:137], v[190:193], v[26:29]
	v_mfma_f32_16x16x32_bf16 v[26:29], v[138:141], v[194:197], v[26:29]
	v_mfma_f32_16x16x32_bf16 v[18:21], v[142:145], v[190:193], v[18:21]
	v_mfma_f32_16x16x32_bf16 v[18:21], v[146:149], v[194:197], v[18:21]
	v_mfma_f32_16x16x32_bf16 v[46:49], v[150:153], v[166:169], v[46:49]
	v_mfma_f32_16x16x32_bf16 v[46:49], v[154:157], v[170:173], v[46:49]
	v_mfma_f32_16x16x32_bf16 v[38:41], v[158:161], v[166:169], v[38:41]
	v_mfma_f32_16x16x32_bf16 v[38:41], v[162:165], v[170:173], v[38:41]
	v_mfma_f32_16x16x32_bf16 v[30:33], v[150:153], v[174:177], v[30:33]
	v_mfma_f32_16x16x32_bf16 v[30:33], v[154:157], v[178:181], v[30:33]
	v_mfma_f32_16x16x32_bf16 v[22:25], v[158:161], v[174:177], v[22:25]
	v_mfma_f32_16x16x32_bf16 v[22:25], v[162:165], v[178:181], v[22:25]
	v_mfma_f32_16x16x32_bf16 v[14:17], v[150:153], v[182:185], v[14:17]
	v_mfma_f32_16x16x32_bf16 v[14:17], v[154:157], v[186:189], v[14:17]
	v_mfma_f32_16x16x32_bf16 v[10:13], v[158:161], v[182:185], v[10:13]
	v_mfma_f32_16x16x32_bf16 v[10:13], v[162:165], v[186:189], v[10:13]
	v_mfma_f32_16x16x32_bf16 v[6:9], v[150:153], v[190:193], v[6:9]
	v_mfma_f32_16x16x32_bf16 v[6:9], v[154:157], v[194:197], v[6:9]
	v_mfma_f32_16x16x32_bf16 v[2:5], v[158:161], v[190:193], v[2:5]
	v_mfma_f32_16x16x32_bf16 v[2:5], v[162:165], v[194:197], v[2:5]
	s_setprio 0
	s_barrier
	s_add_i32 s82, s82, 2
	s_addk_i32 s80, 0x100
	s_addk_i32 s81, 0x100
	s_cmp_ge_i32 s82, s3
	s_cbranch_scc0 .LBB0_1519
	v_pk_mul_f32 v[182:183], v[128:129], 0.5 op_sel_hi:[1,0]
	v_pk_mul_f32 v[184:185], v[126:127], 0.5 op_sel_hi:[1,0]
	v_pk_mul_f32 v[186:187], v[124:125], 0.5 op_sel_hi:[1,0]
	v_pk_mul_f32 v[188:189], v[122:123], 0.5 op_sel_hi:[1,0]
	v_pk_mul_f32 v[196:197], v[112:113], 0.5 op_sel_hi:[1,0]
	v_pk_mul_f32 v[194:195], v[110:111], 0.5 op_sel_hi:[1,0]
	v_pk_mul_f32 v[192:193], v[104:105], 0.5 op_sel_hi:[1,0]
	v_pk_mul_f32 v[190:191], v[102:103], 0.5 op_sel_hi:[1,0]
	v_pk_mul_f32 v[180:181], v[120:121], 0.5 op_sel_hi:[1,0]
	v_pk_mul_f32 v[178:179], v[118:119], 0.5 op_sel_hi:[1,0]
	v_pk_mul_f32 v[176:177], v[116:117], 0.5 op_sel_hi:[1,0]
	v_pk_mul_f32 v[174:175], v[114:115], 0.5 op_sel_hi:[1,0]
	v_pk_mul_f32 v[170:171], v[96:97], 0.5 op_sel_hi:[1,0]
	v_pk_mul_f32 v[168:169], v[94:95], 0.5 op_sel_hi:[1,0]
	v_pk_mul_f32 v[166:167], v[88:89], 0.5 op_sel_hi:[1,0]
	v_pk_mul_f32 v[164:165], v[86:87], 0.5 op_sel_hi:[1,0]
	v_pk_mul_f32 v[162:163], v[108:109], 0.5 op_sel_hi:[1,0]
	v_pk_mul_f32 v[160:161], v[106:107], 0.5 op_sel_hi:[1,0]
	v_pk_mul_f32 v[158:159], v[100:101], 0.5 op_sel_hi:[1,0]
	v_pk_mul_f32 v[156:157], v[98:99], 0.5 op_sel_hi:[1,0]
	v_pk_mul_f32 v[154:155], v[80:81], 0.5 op_sel_hi:[1,0]
	v_pk_mul_f32 v[152:153], v[78:79], 0.5 op_sel_hi:[1,0]
	v_pk_mul_f32 v[150:151], v[76:77], 0.5 op_sel_hi:[1,0]
	v_pk_mul_f32 v[148:149], v[74:75], 0.5 op_sel_hi:[1,0]
	v_pk_mul_f32 v[144:145], v[92:93], 0.5 op_sel_hi:[1,0]
	v_pk_mul_f32 v[142:143], v[90:91], 0.5 op_sel_hi:[1,0]
	v_pk_mul_f32 v[140:141], v[84:85], 0.5 op_sel_hi:[1,0]
	v_pk_mul_f32 v[138:139], v[82:83], 0.5 op_sel_hi:[1,0]
	v_pk_mul_f32 v[136:137], v[72:73], 0.5 op_sel_hi:[1,0]
	v_pk_mul_f32 v[134:135], v[70:71], 0.5 op_sel_hi:[1,0]
	v_pk_mul_f32 v[128:129], v[68:69], 0.5 op_sel_hi:[1,0]
	v_pk_mul_f32 v[126:127], v[66:67], 0.5 op_sel_hi:[1,0]
	v_pk_mul_f32 v[122:123], v[64:65], 0.5 op_sel_hi:[1,0]
	v_pk_mul_f32 v[120:121], v[62:63], 0.5 op_sel_hi:[1,0]
	v_pk_mul_f32 v[118:119], v[60:61], 0.5 op_sel_hi:[1,0]
	v_pk_mul_f32 v[116:117], v[58:59], 0.5 op_sel_hi:[1,0]
	v_pk_mul_f32 v[112:113], v[48:49], 0.5 op_sel_hi:[1,0]
	v_pk_mul_f32 v[110:111], v[46:47], 0.5 op_sel_hi:[1,0]
	v_pk_mul_f32 v[108:109], v[40:41], 0.5 op_sel_hi:[1,0]
	v_pk_mul_f32 v[106:107], v[38:39], 0.5 op_sel_hi:[1,0]
	v_pk_mul_f32 v[104:105], v[56:57], 0.5 op_sel_hi:[1,0]
	v_pk_mul_f32 v[102:103], v[54:55], 0.5 op_sel_hi:[1,0]
	v_pk_mul_f32 v[100:101], v[52:53], 0.5 op_sel_hi:[1,0]
	v_pk_mul_f32 v[98:99], v[50:51], 0.5 op_sel_hi:[1,0]
	v_pk_mul_f32 v[96:97], v[32:33], 0.5 op_sel_hi:[1,0]
	v_pk_mul_f32 v[94:95], v[30:31], 0.5 op_sel_hi:[1,0]
	v_pk_mul_f32 v[92:93], v[24:25], 0.5 op_sel_hi:[1,0]
	v_pk_mul_f32 v[90:91], v[22:23], 0.5 op_sel_hi:[1,0]
	v_pk_mul_f32 v[88:89], v[44:45], 0.5 op_sel_hi:[1,0]
	v_pk_mul_f32 v[86:87], v[42:43], 0.5 op_sel_hi:[1,0]
	v_pk_mul_f32 v[84:85], v[36:37], 0.5 op_sel_hi:[1,0]
	v_pk_mul_f32 v[82:83], v[34:35], 0.5 op_sel_hi:[1,0]
	v_pk_mul_f32 v[80:81], v[16:17], 0.5 op_sel_hi:[1,0]
	v_pk_mul_f32 v[78:79], v[14:15], 0.5 op_sel_hi:[1,0]
	v_pk_mul_f32 v[76:77], v[12:13], 0.5 op_sel_hi:[1,0]
	v_pk_mul_f32 v[74:75], v[10:11], 0.5 op_sel_hi:[1,0]
	v_pk_mul_f32 v[72:73], v[28:29], 0.5 op_sel_hi:[1,0]
	v_pk_mul_f32 v[70:71], v[26:27], 0.5 op_sel_hi:[1,0]
	v_pk_mul_f32 v[68:69], v[20:21], 0.5 op_sel_hi:[1,0]
	v_pk_mul_f32 v[66:67], v[18:19], 0.5 op_sel_hi:[1,0]
	v_pk_mul_f32 v[64:65], v[8:9], 0.5 op_sel_hi:[1,0]
	v_pk_mul_f32 v[62:63], v[6:7], 0.5 op_sel_hi:[1,0]
	v_pk_mul_f32 v[60:61], v[4:5], 0.5 op_sel_hi:[1,0]
	v_pk_mul_f32 v[58:59], v[2:3], 0.5 op_sel_hi:[1,0]
	s_and_b64 vcc, exec, s[40:41]
	s_cbranch_vccz .LBB0_1522
